# int8 W_up/W_in row copies: all 16 row loads of an iteration requested before the first use
# baseline (speedup 1.0000x reference)
; __device__ __forceinline__ float bflo(unsigned w) { return __uint_as_float(w << 16); }
; __device__ __forceinline__ float bfhi(unsigned w) { return __uint_as_float(w & 0xffff0000u); }
; #pragma unroll
;     for (int j = 0; j < 8; ++j) mx = fmaxf(mx, fmaxf(fmaxf(fmaxf(fabsf(bflo(w[j].x)), fabsf(bfhi(w[j].x))), fmaxf(fabsf(bflo(w[j].y)), fabsf(bfhi(w[j].y)))), fmaxf(fmaxf(fabsf(bflo(w[j].z)), fabsf(bfhi(w[j].z))), fmaxf(fabsf(bflo(w[j].w)), fabsf(bfhi(w[j].w))))));
; #pragma unroll
;     for (int o = 1; o < 64; o <<= 1) mx = fmaxf(mx, __shfl_xor(mx, o));
;     return mx; }
; __device__ __forceinline__ void quant_rows2(const bf16_t* s0, const bf16_t* s1, signed char* d0, signed char* d1, int lane, float& step0, float& step1) {
;     const u32x4* p0 = (const u32x4*)s0 + lane; const u32x4* p1 = (const u32x4*)s1 + lane; u32x4 w0[8], w1[8];
; #pragma unroll
;     for (int j = 0; j < 8; ++j) { w0[j] = p0[64 * j]; w1[j] = p1[64 * j]; }
;     step0 = fmaxf(absmax8(w0), 1e-30f) * (1.0f / 127.0f); step1 = fmaxf(absmax8(w1), 1e-30f) * (1.0f / 127.0f);
.LBB0_64:
	v_lshl_add_u64 v[2:3], s[78:79], 0, v[30:31]
	v_add_co_u32_e32 v4, vcc, 0x800000, v2
	s_nop 1
	v_addc_co_u32_e32 v5, vcc, 0, v3, vcc
	global_load_dwordx4 v[42:45], v[4:5], off
	global_load_dwordx4 v[46:49], v[4:5], off offset:1024
	global_load_dwordx4 v[50:53], v[4:5], off offset:2048
	global_load_dwordx4 v[54:57], v[4:5], off offset:3072
	v_add_co_u32_e32 v6, vcc, 0x802000, v2
	s_nop 1
	v_addc_co_u32_e32 v7, vcc, 0, v3, vcc
	v_add_co_u32_e32 v78, vcc, s17, v2
	global_load_dwordx4 v[58:61], v[6:7], off
	global_load_dwordx4 v[26:29], v[6:7], off offset:1024
	global_load_dwordx4 v[22:25], v[6:7], off offset:2048
	global_load_dwordx4 v[18:21], v[6:7], off offset:3072
	v_addc_co_u32_e32 v79, vcc, 0, v3, vcc
	v_add_co_u32_e32 v80, vcc, s18, v2
	s_nop 1
	v_addc_co_u32_e32 v81, vcc, 0, v3, vcc
	global_load_dwordx4 v[62:65], v[78:79], off
	global_load_dwordx4 v[66:69], v[78:79], off offset:1024
	global_load_dwordx4 v[70:73], v[78:79], off offset:2048
	global_load_dwordx4 v[74:77], v[78:79], off offset:3072
	global_load_dwordx4 v[14:17], v[80:81], off
	global_load_dwordx4 v[10:13], v[80:81], off offset:1024
	global_load_dwordx4 v[6:9], v[80:81], off offset:2048
	global_load_dwordx4 v[2:5], v[80:81], off offset:3072
	s_waitcnt vmcnt(15)
	v_lshlrev_b32_e32 v83, 16, v42
	v_and_b32_e32 v84, 0xffff0000, v42
	v_lshlrev_b32_e32 v85, 16, v43
	v_and_b32_e32 v86, 0xffff0000, v43
	v_lshlrev_b32_e32 v89, 16, v45
	v_and_b32_e32 v90, 0xffff0000, v45
	s_waitcnt vmcnt(14)
	v_lshlrev_b32_e32 v97, 16, v49
	v_and_b32_e32 v98, 0xffff0000, v49
	v_lshlrev_b32_e32 v87, 16, v44
	v_and_b32_e32 v88, 0xffff0000, v44
	v_lshlrev_b32_e32 v91, 16, v46
	v_and_b32_e32 v92, 0xffff0000, v46
	v_lshlrev_b32_e32 v93, 16, v47
	v_and_b32_e32 v94, 0xffff0000, v47
	s_waitcnt vmcnt(13)
	v_lshlrev_b32_e32 v101, 16, v51
	v_and_b32_e32 v102, 0xffff0000, v51
	v_lshlrev_b32_e32 v103, 16, v52
	v_and_b32_e32 v104, 0xffff0000, v52
	v_max_f32_e64 v41, |v84|, |v84|
	v_max_f32_e64 v42, |v83|, |v83|
	v_max_f32_e64 v43, |v86|, |v86|
	v_max_f32_e64 v44, |v85|, |v85|
	v_max_f32_e64 v45, |v90|, |v90|
	v_max_f32_e64 v46, |v89|, |v89|
	v_max_f32_e64 v51, |v98|, |v98|
	v_max_f32_e64 v52, |v97|, |v97|
	v_lshlrev_b32_e32 v95, 16, v48
	v_and_b32_e32 v96, 0xffff0000, v48
	v_lshlrev_b32_e32 v99, 16, v50
	v_and_b32_e32 v100, 0xffff0000, v50
	v_max_f32_e64 v47, |v92|, |v92|
	v_max_f32_e64 v48, |v91|, |v91|
	v_max_f32_e64 v49, |v94|, |v94|
	v_max_f32_e64 v50, |v93|, |v93|
	v_max_f32_e32 v41, v42, v41
	v_max_f32_e32 v42, v44, v43
	v_max_f32_e32 v43, v46, v45
	v_max_f32_e32 v46, v52, v51
	v_max_f32_e32 v44, v48, v47
	v_max_f32_e32 v45, v50, v49
	v_max3_f32 v43, |v87|, |v88|, v43
	v_max3_f32 v46, |v95|, |v96|, v46
	v_lshlrev_b32_e32 v105, 16, v53
	v_max3_f32 v41, v41, v42, v43
	v_max3_f32 v42, v44, v45, v46
	v_and_b32_e32 v106, 0xffff0000, v53
	v_max3_f32 v41, v41, 0, v42
	v_max_f32_e64 v42, |v106|, |v106|
	v_max_f32_e64 v43, |v105|, |v105|
	s_waitcnt vmcnt(12)
	v_lshlrev_b32_e32 v107, 16, v54
	v_and_b32_e32 v108, 0xffff0000, v54
	v_max_f32_e32 v42, v43, v42
	v_max_f32_e64 v43, |v108|, |v108|
	v_max_f32_e64 v44, |v107|, |v107|
	v_lshlrev_b32_e32 v109, 16, v55
	v_and_b32_e32 v110, 0xffff0000, v55
	v_max_f32_e32 v43, v44, v43
	v_max_f32_e64 v44, |v110|, |v110|
	v_max_f32_e64 v45, |v109|, |v109|
	v_lshlrev_b32_e32 v113, 16, v57
	v_and_b32_e32 v114, 0xffff0000, v57
	v_max_f32_e32 v44, v45, v44
	v_max_f32_e64 v45, |v114|, |v114|
	v_max_f32_e64 v46, |v113|, |v113|
	v_max_f32_e64 v78, |v100|, |v100|
	v_max_f32_e64 v79, |v99|, |v99|
	v_max_f32_e64 v80, |v102|, |v102|
	v_max_f32_e64 v81, |v101|, |v101|
	v_lshlrev_b32_e32 v111, 16, v56
	v_and_b32_e32 v112, 0xffff0000, v56
	v_max_f32_e32 v45, v46, v45
	v_max_f32_e32 v47, v79, v78
	v_max_f32_e32 v48, v81, v80
	v_max3_f32 v42, |v103|, |v104|, v42
	v_max3_f32 v45, |v111|, |v112|, v45
	v_max3_f32 v42, v47, v48, v42
	v_max3_f32 v43, v43, v44, v45
	s_waitcnt vmcnt(7)
	v_lshlrev_b32_e32 v115, 16, v62
	v_and_b32_e32 v116, 0xffff0000, v62
	v_max3_f32 v41, v41, v42, v43
	v_max_f32_e64 v42, |v116|, |v116|
	v_max_f32_e64 v43, |v115|, |v115|
	v_lshlrev_b32_e32 v117, 16, v63
	v_and_b32_e32 v118, 0xffff0000, v63
	v_max_f32_e32 v42, v43, v42
	v_max_f32_e64 v43, |v118|, |v118|
	v_max_f32_e64 v44, |v117|, |v117|
	v_lshlrev_b32_e32 v121, 16, v65
	v_and_b32_e32 v122, 0xffff0000, v65
	v_max_f32_e32 v43, v44, v43
	v_max_f32_e64 v44, |v122|, |v122|
	v_max_f32_e64 v45, |v121|, |v121|
	v_lshlrev_b32_e32 v119, 16, v64
	v_and_b32_e32 v120, 0xffff0000, v64
	v_max_f32_e32 v44, v45, v44
	v_max3_f32 v44, |v119|, |v120|, v44
	s_waitcnt vmcnt(6)
	v_lshlrev_b32_e32 v123, 16, v66
	v_and_b32_e32 v124, 0xffff0000, v66
	v_max3_f32 v42, v42, v43, v44
	v_max_f32_e64 v43, |v124|, |v124|
	v_max_f32_e64 v44, |v123|, |v123|
	v_lshlrev_b32_e32 v125, 16, v67
	v_and_b32_e32 v126, 0xffff0000, v67
	v_max_f32_e32 v43, v44, v43
	v_max_f32_e64 v44, |v126|, |v126|
	v_max_f32_e64 v45, |v125|, |v125|
	v_lshlrev_b32_e32 v129, 16, v69
	v_and_b32_e32 v130, 0xffff0000, v69
	v_max_f32_e32 v44, v45, v44
	v_max_f32_e64 v45, |v130|, |v130|
	v_max_f32_e64 v46, |v129|, |v129|
	v_lshlrev_b32_e32 v127, 16, v68
	v_and_b32_e32 v128, 0xffff0000, v68
	v_max_f32_e32 v45, v46, v45
	v_max3_f32 v45, |v127|, |v128|, v45
	v_max3_f32 v43, v43, v44, v45
	s_waitcnt vmcnt(5)
	v_lshlrev_b32_e32 v131, 16, v70
	v_and_b32_e32 v132, 0xffff0000, v70
	v_max3_f32 v41, v41, v42, v43
	v_max_f32_e64 v42, |v132|, |v132|
	v_max_f32_e64 v43, |v131|, |v131|
	v_lshlrev_b32_e32 v133, 16, v71
	v_and_b32_e32 v134, 0xffff0000, v71
	v_max_f32_e32 v42, v43, v42
	v_max_f32_e64 v43, |v134|, |v134|
	v_max_f32_e64 v44, |v133|, |v133|
	v_lshlrev_b32_e32 v137, 16, v73
	v_and_b32_e32 v138, 0xffff0000, v73
	v_max_f32_e32 v43, v44, v43
	v_max_f32_e64 v44, |v138|, |v138|
	v_max_f32_e64 v45, |v137|, |v137|
	v_lshlrev_b32_e32 v135, 16, v72
	v_and_b32_e32 v136, 0xffff0000, v72
	v_max_f32_e32 v44, v45, v44
	v_max3_f32 v44, |v135|, |v136|, v44
	s_waitcnt vmcnt(4)
; __device__ __forceinline__ float bflo(unsigned w) { return __uint_as_float(w << 16); }
; __device__ __forceinline__ float bfhi(unsigned w) { return __uint_as_float(w & 0xffff0000u); }
; #pragma unroll
;     for (int j = 0; j < 8; ++j) mx = fmaxf(mx, fmaxf(fmaxf(fmaxf(fabsf(bflo(w[j].x)), fabsf(bfhi(w[j].x))), fmaxf(fabsf(bflo(w[j].y)), fabsf(bfhi(w[j].y)))), fmaxf(fmaxf(fabsf(bflo(w[j].z)), fabsf(bfhi(w[j].z))), fmaxf(fabsf(bflo(w[j].w)), fabsf(bfhi(w[j].w))))));
; #pragma unroll
;     for (int o = 1; o < 64; o <<= 1) mx = fmaxf(mx, __shfl_xor(mx, o));
;     return mx; }
	v_lshlrev_b32_e32 v139, 16, v74
	v_and_b32_e32 v140, 0xffff0000, v74
	v_max3_f32 v42, v42, v43, v44
	v_max_f32_e64 v43, |v140|, |v140|
	v_max_f32_e64 v44, |v139|, |v139|
	v_lshlrev_b32_e32 v141, 16, v75
	v_and_b32_e32 v142, 0xffff0000, v75
	v_max_f32_e32 v43, v44, v43
	v_max_f32_e64 v44, |v142|, |v142|
	v_max_f32_e64 v45, |v141|, |v141|
	v_lshlrev_b32_e32 v145, 16, v77
	v_and_b32_e32 v146, 0xffff0000, v77
	v_max_f32_e32 v44, v45, v44
	v_max_f32_e64 v45, |v146|, |v146|
	v_max_f32_e64 v46, |v145|, |v145|
	v_lshlrev_b32_e32 v143, 16, v76
	v_and_b32_e32 v144, 0xffff0000, v76
	v_max_f32_e32 v45, v46, v45
	v_max3_f32 v45, |v143|, |v144|, v45
	v_max3_f32 v43, v43, v44, v45
	v_lshlrev_b32_e32 v82, 16, v58
	v_and_b32_e32 v80, 0xffff0000, v58
	v_max3_f32 v147, v41, v42, v43
	v_max_f32_e64 v41, |v80|, |v80|
	v_max_f32_e64 v42, |v82|, |v82|
	v_lshlrev_b32_e32 v81, 16, v59
	v_and_b32_e32 v79, 0xffff0000, v59
	v_max_f32_e32 v41, v42, v41
	v_max_f32_e64 v42, |v79|, |v79|
	v_max_f32_e64 v43, |v81|, |v81|
	v_lshlrev_b32_e32 v76, 16, v61
	v_and_b32_e32 v75, 0xffff0000, v61
	v_max_f32_e32 v42, v43, v42
	v_max_f32_e64 v43, |v75|, |v75|
	v_max_f32_e64 v44, |v76|, |v76|
	v_lshlrev_b32_e32 v78, 16, v60
	v_and_b32_e32 v77, 0xffff0000, v60
	v_max_f32_e32 v43, v44, v43
	v_max3_f32 v43, |v78|, |v77|, v43
	v_lshlrev_b32_e32 v74, 16, v26
	v_and_b32_e32 v72, 0xffff0000, v26
	v_lshlrev_b32_e32 v68, 16, v29
	v_and_b32_e32 v67, 0xffff0000, v29
	v_max3_f32 v41, v41, v42, v43
	v_max_f32_e64 v26, |v72|, |v72|
	v_max_f32_e64 v42, |v74|, |v74|
	v_lshlrev_b32_e32 v73, 16, v27
	v_and_b32_e32 v71, 0xffff0000, v27
	v_lshlrev_b32_e32 v70, 16, v28
	v_and_b32_e32 v69, 0xffff0000, v28
	v_max_f32_e64 v28, |v67|, |v67|
	v_max_f32_e64 v29, |v68|, |v68|
	v_max_f32_e32 v26, v42, v26
	v_max_f32_e64 v27, |v71|, |v71|
	v_max_f32_e64 v42, |v73|, |v73|
	v_max_f32_e32 v28, v29, v28
	v_max_f32_e32 v27, v42, v27
	v_max3_f32 v28, |v70|, |v69|, v28
	v_lshlrev_b32_e32 v66, 16, v22
	v_and_b32_e32 v64, 0xffff0000, v22
	v_lshlrev_b32_e32 v60, 16, v25
	v_and_b32_e32 v59, 0xffff0000, v25
	v_max3_f32 v26, v26, v27, v28
	v_max_f32_e64 v22, |v64|, |v64|
	v_max_f32_e64 v27, |v66|, |v66|
	v_lshlrev_b32_e32 v65, 16, v23
	v_and_b32_e32 v63, 0xffff0000, v23
	v_lshlrev_b32_e32 v62, 16, v24
	v_and_b32_e32 v61, 0xffff0000, v24
	v_max_f32_e64 v24, |v59|, |v59|
	v_max_f32_e64 v25, |v60|, |v60|
	v_max_f32_e32 v22, v27, v22
	v_max_f32_e64 v23, |v63|, |v63|
	v_max_f32_e64 v27, |v65|, |v65|
	v_max_f32_e32 v24, v25, v24
	v_max_f32_e32 v23, v27, v23
	v_max3_f32 v24, |v62|, |v61|, v24
	v_lshlrev_b32_e32 v58, 16, v18
	v_and_b32_e32 v56, 0xffff0000, v18
	v_lshlrev_b32_e32 v52, 16, v21
	v_and_b32_e32 v51, 0xffff0000, v21
	v_max3_f32 v22, v22, v23, v24
	v_max_f32_e64 v18, |v56|, |v56|
	v_max_f32_e64 v23, |v58|, |v58|
	v_lshlrev_b32_e32 v57, 16, v19
	v_and_b32_e32 v55, 0xffff0000, v19
	v_lshlrev_b32_e32 v54, 16, v20
	v_and_b32_e32 v53, 0xffff0000, v20
	v_max_f32_e64 v20, |v51|, |v51|
	v_max_f32_e64 v21, |v52|, |v52|
	v_max_f32_e32 v18, v23, v18
	v_max_f32_e64 v19, |v55|, |v55|
	v_max_f32_e64 v23, |v57|, |v57|
	v_max_f32_e32 v20, v21, v20
	v_max_f32_e32 v19, v23, v19
	v_max3_f32 v20, |v54|, |v53|, v20
	s_waitcnt vmcnt(3)
	v_lshlrev_b32_e32 v50, 16, v14
	v_and_b32_e32 v48, 0xffff0000, v14
	v_lshlrev_b32_e32 v44, 16, v17
	v_and_b32_e32 v43, 0xffff0000, v17
	v_max3_f32 v18, v18, v19, v20
	v_max_f32_e64 v14, |v48|, |v48|
	v_max_f32_e64 v19, |v50|, |v50|
	v_lshlrev_b32_e32 v49, 16, v15
	v_and_b32_e32 v47, 0xffff0000, v15
	v_lshlrev_b32_e32 v46, 16, v16
	v_and_b32_e32 v45, 0xffff0000, v16
	v_max_f32_e64 v16, |v43|, |v43|
	v_max_f32_e64 v17, |v44|, |v44|
	v_max_f32_e32 v14, v19, v14
	v_max_f32_e64 v15, |v47|, |v47|
	v_max_f32_e64 v19, |v49|, |v49|
	v_max_f32_e32 v16, v17, v16
	v_max3_f32 v26, v41, 0, v26
	v_max_f32_e32 v15, v19, v15
	v_max3_f32 v16, |v46|, |v45|, v16
	s_waitcnt vmcnt(2)
	v_lshlrev_b32_e32 v42, 16, v10
	v_and_b32_e32 v29, 0xffff0000, v10
	v_lshlrev_b32_e32 v25, 16, v13
	v_and_b32_e32 v24, 0xffff0000, v13
	v_max3_f32 v18, v26, v22, v18
	v_max3_f32 v14, v14, v15, v16
	v_max_f32_e64 v10, |v29|, |v29|
	v_max_f32_e64 v15, |v42|, |v42|
	v_lshlrev_b32_e32 v41, 16, v11
	v_and_b32_e32 v28, 0xffff0000, v11
	v_lshlrev_b32_e32 v27, 16, v12
	v_and_b32_e32 v26, 0xffff0000, v12
	v_max_f32_e64 v12, |v24|, |v24|
	v_max_f32_e64 v13, |v25|, |v25|
	v_max_f32_e32 v10, v15, v10
	v_max_f32_e64 v11, |v28|, |v28|
	v_max_f32_e64 v15, |v41|, |v41|
	v_max_f32_e32 v12, v13, v12
	v_max_f32_e32 v11, v15, v11
	v_max3_f32 v12, |v27|, |v26|, v12
	v_max3_f32 v10, v10, v11, v12
	s_waitcnt vmcnt(1)
	v_lshlrev_b32_e32 v23, 16, v6
	v_and_b32_e32 v21, 0xffff0000, v6
	v_lshlrev_b32_e32 v17, 16, v9
	v_and_b32_e32 v16, 0xffff0000, v9
	v_max3_f32 v149, v18, v14, v10
	v_max_f32_e64 v6, |v21|, |v21|
	v_max_f32_e64 v10, |v23|, |v23|
	v_lshlrev_b32_e32 v22, 16, v7
	v_and_b32_e32 v20, 0xffff0000, v7
	v_lshlrev_b32_e32 v19, 16, v8
	v_and_b32_e32 v18, 0xffff0000, v8
	v_max_f32_e64 v8, |v16|, |v16|
	v_max_f32_e64 v9, |v17|, |v17|
	v_max_f32_e32 v6, v10, v6
	v_max_f32_e64 v7, |v20|, |v20|
	v_max_f32_e64 v10, |v22|, |v22|
	v_max_f32_e32 v8, v9, v8
	v_max_f32_e32 v7, v10, v7
	v_max3_f32 v8, |v19|, |v18|, v8
	v_max3_f32 v6, v6, v7, v8
	s_waitcnt vmcnt(0)
	v_lshlrev_b32_e32 v15, 16, v2
	v_and_b32_e32 v13, 0xffff0000, v2
	v_lshlrev_b32_e32 v9, 16, v5
	v_and_b32_e32 v8, 0xffff0000, v5
	v_max_f32_e64 v2, |v13|, |v13|
	v_max_f32_e64 v7, |v15|, |v15|
	v_lshlrev_b32_e32 v14, 16, v3
	v_and_b32_e32 v12, 0xffff0000, v3
	v_lshlrev_b32_e32 v11, 16, v4
	v_and_b32_e32 v10, 0xffff0000, v4
	v_max_f32_e64 v4, |v8|, |v8|
	v_max_f32_e64 v5, |v9|, |v9|
	v_max_f32_e32 v2, v7, v2
	v_max_f32_e64 v3, |v12|, |v12|
	v_max_f32_e64 v7, |v14|, |v14|
	v_max_f32_e32 v4, v5, v4
	v_max_f32_e32 v3, v7, v3
	v_max3_f32 v4, |v11|, |v10|, v4
	v_max3_f32 v2, v2, v3, v4
	v_max3_f32 v2, v149, v6, v2
	s_nop 1
	v_mov_b32_dpp v148, v147 quad_perm:[1,0,3,2] row_mask:0xf bank_mask:0xf
	s_nop 1
	v_mov_b32_dpp v3, v2 quad_perm:[1,0,3,2] row_mask:0xf bank_mask:0xf
	s_waitcnt lgkmcnt(0)
; __device__ __forceinline__ float bflo(unsigned w) { return __uint_as_float(w << 16); }
; __device__ __forceinline__ float bfhi(unsigned w) { return __uint_as_float(w & 0xffff0000u); }
;     ...
; #pragma unroll
;     for (int o = 1; o < 64; o <<= 1) mx = fmaxf(mx, __shfl_xor(mx, o));
;     return mx; }
; __device__ __forceinline__ void quant_store8(const u32x4 (&w)[8], float inv, signed char* dst, int lane) { u32x2* qp = (u32x2*)dst + lane;
; #pragma unroll
;     for (int j = 0; j < 8; ++j) { const unsigned ww[4] = {w[j].x, w[j].y, w[j].z, w[j].w}; unsigned o2[2];
; #pragma unroll
;         for (int h2 = 0; h2 < 2; ++h2) { const int q0 = (int)rintf(bflo(ww[2 * h2]) * inv), q1 = (int)rintf(bfhi(ww[2 * h2]) * inv), q2 = (int)rintf(bflo(ww[2 * h2 + 1]) * inv), q3 = (int)rintf(bfhi(ww[2 * h2 + 1]) * inv);
;             o2[h2] = (unsigned)(q0 & 255) | ((unsigned)(q1 & 255) << 8) | ((unsigned)(q2 & 255) << 16) | ((unsigned)(q3 & 255) << 24); }
;         u32x2 o; o.x = o2[0]; o.y = o2[1]; qp[64 * j] = o; } }
; __device__ __forceinline__ void quant_rows2(const bf16_t* s0, const bf16_t* s1, signed char* d0, signed char* d1, int lane, float& step0, float& step1) {
;     ...
;     step0 = fmaxf(absmax8(w0), 1e-30f) * (1.0f / 127.0f); step1 = fmaxf(absmax8(w1), 1e-30f) * (1.0f / 127.0f);
	v_max_f32_e32 v4, v148, v148
	s_waitcnt lgkmcnt(0)
	v_max_f32_e32 v3, v3, v3
	v_max_f32_e32 v4, v147, v4
	v_max_f32_e32 v2, v2, v3
	s_nop 1
	v_mov_b32_dpp v5, v4 quad_perm:[2,3,0,1] row_mask:0xf bank_mask:0xf
	s_nop 1
	v_mov_b32_dpp v3, v2 quad_perm:[2,3,0,1] row_mask:0xf bank_mask:0xf
	s_waitcnt lgkmcnt(0)
	v_max_f32_e32 v5, v5, v5
	s_waitcnt lgkmcnt(0)
	v_max_f32_e32 v3, v3, v3
	v_max_f32_e32 v4, v4, v5
	v_max_f32_e32 v2, v2, v3
	s_nop 1
	v_mov_b32_dpp v5, v4 row_half_mirror row_mask:0xf bank_mask:0xf
	s_nop 1
	v_mov_b32_dpp v3, v2 row_half_mirror row_mask:0xf bank_mask:0xf
	s_waitcnt lgkmcnt(0)
	v_max_f32_e32 v5, v5, v5
	s_waitcnt lgkmcnt(0)
	v_max_f32_e32 v3, v3, v3
	v_max_f32_e32 v4, v4, v5
	v_max_f32_e32 v2, v2, v3
	s_nop 1
	v_mov_b32_dpp v5, v4 row_mirror row_mask:0xf bank_mask:0xf
	s_nop 1
	v_mov_b32_dpp v3, v2 row_mirror row_mask:0xf bank_mask:0xf
	s_waitcnt lgkmcnt(0)
	v_max_f32_e32 v5, v5, v5
	s_waitcnt lgkmcnt(0)
	v_max_f32_e32 v3, v3, v3
	v_max_f32_e32 v4, v4, v5
	v_max_f32_e32 v2, v2, v3
	s_waitcnt lgkmcnt(0)
	s_waitcnt lgkmcnt(0)
	v_mov_b32_e32 v5, v4
	s_nop 1
	v_permlane16_swap_b32_e32 v4, v5
	s_nop 0
	v_max_f32_e32 v4, v4, v5
	v_mov_b32_e32 v3, v2
	s_nop 1
	v_permlane16_swap_b32_e32 v3, v2
	s_nop 0
	v_max_f32_e32 v3, v3, v2
	ds_bpermute_b32 v5, v39, v4
	ds_bpermute_b32 v6, v39, v3
	s_waitcnt lgkmcnt(1)
	v_max3_f32 v2, v4, v5, s19
	s_waitcnt lgkmcnt(0)
	v_max3_f32 v3, v3, v6, s19
	v_pk_mul_f32 v[2:3], v[2:3], s[6:7] op_sel_hi:[1,0]
	s_nop 0
	v_div_scale_f32 v4, s[14:15], v2, v2, 1.0
	v_rcp_f32_e32 v5, v4
	s_nop 0
	v_fma_f32 v6, -v4, v5, 1.0
	v_fmac_f32_e32 v5, v6, v5
	v_div_scale_f32 v6, vcc, 1.0, v2, 1.0
	v_mul_f32_e32 v7, v6, v5
	v_fma_f32 v147, -v4, v7, v6
	v_fmac_f32_e32 v7, v147, v5
	v_fma_f32 v4, -v4, v7, v6
	v_div_fmas_f32 v4, v4, v5, v7
	v_div_fixup_f32 v147, v4, v2, 1.0
	v_mul_f32_e32 v7, v147, v84
	v_mul_f32_e32 v6, v147, v83
	v_rndne_f32_e32 v7, v7
	v_mul_f32_e32 v83, v147, v85
	v_rndne_f32_e32 v6, v6
	v_cvt_i32_f32_e32 v7, v7
	v_rndne_f32_e32 v83, v83
	v_mul_f32_e32 v84, v147, v86
	v_cvt_i32_f32_e32 v6, v6
	v_cvt_i32_f32_sdwa v83, v83 dst_sel:WORD_1 dst_unused:UNUSED_PAD src0_sel:DWORD
	v_rndne_f32_e32 v84, v84
	v_cvt_i32_f32_sdwa v84, v84 dst_sel:BYTE_3 dst_unused:UNUSED_PAD src0_sel:DWORD
	v_lshlrev_b32_e32 v7, 8, v7
	v_and_b32_e32 v83, 0xff0000, v83
	v_perm_b32 v6, v7, v6, s20
	v_mul_f32_e32 v7, v147, v88
	v_or3_b32 v84, v6, v84, v83
	v_mul_f32_e32 v6, v147, v87
	v_rndne_f32_e32 v7, v7
	v_mul_f32_e32 v83, v147, v89
	v_rndne_f32_e32 v6, v6
	v_cvt_i32_f32_e32 v7, v7
	v_rndne_f32_e32 v83, v83
	v_mul_f32_e32 v85, v147, v90
	v_cvt_i32_f32_e32 v6, v6
	v_cvt_i32_f32_sdwa v83, v83 dst_sel:WORD_1 dst_unused:UNUSED_PAD src0_sel:DWORD
	v_rndne_f32_e32 v85, v85
	v_cvt_i32_f32_sdwa v85, v85 dst_sel:BYTE_3 dst_unused:UNUSED_PAD src0_sel:DWORD
	v_lshlrev_b32_e32 v7, 8, v7
	v_lshl_add_u64 v[4:5], s[78:79], 0, v[32:33]
	v_and_b32_e32 v83, 0xff0000, v83
	v_perm_b32 v6, v7, v6, s20
	v_or3_b32 v85, v6, v85, v83
	v_add_co_u32_e32 v6, vcc, s21, v4
	v_mul_f32_e32 v83, v147, v91
	s_nop 0
	v_addc_co_u32_e32 v7, vcc, 0, v5, vcc
	v_add_co_u32_e32 v4, vcc, s22, v4
	v_rndne_f32_e32 v83, v83
	s_nop 0
	v_addc_co_u32_e32 v5, vcc, 0, v5, vcc
	global_store_dwordx2 v[4:5], v[84:85], off offset:-4096
	v_mul_f32_e32 v84, v147, v92
	v_rndne_f32_e32 v84, v84
	v_mul_f32_e32 v85, v147, v93
	v_cvt_i32_f32_e32 v84, v84
	v_rndne_f32_e32 v85, v85
	v_mul_f32_e32 v86, v147, v94
	v_cvt_i32_f32_e32 v83, v83
	v_cvt_i32_f32_sdwa v85, v85 dst_sel:WORD_1 dst_unused:UNUSED_PAD src0_sel:DWORD
	v_rndne_f32_e32 v86, v86
	v_cvt_i32_f32_sdwa v86, v86 dst_sel:BYTE_3 dst_unused:UNUSED_PAD src0_sel:DWORD
	v_lshlrev_b32_e32 v84, 8, v84
	v_and_b32_e32 v85, 0xff0000, v85
	v_perm_b32 v83, v84, v83, s20
	v_or3_b32 v84, v83, v86, v85
	v_mul_f32_e32 v85, v147, v96
	v_mul_f32_e32 v83, v147, v95
	v_rndne_f32_e32 v85, v85
	v_mul_f32_e32 v86, v147, v97
	v_rndne_f32_e32 v83, v83
	v_cvt_i32_f32_e32 v85, v85
	v_rndne_f32_e32 v86, v86
	v_mul_f32_e32 v87, v147, v98
	v_cvt_i32_f32_e32 v83, v83
	v_cvt_i32_f32_sdwa v86, v86 dst_sel:WORD_1 dst_unused:UNUSED_PAD src0_sel:DWORD
	v_rndne_f32_e32 v87, v87
	v_cvt_i32_f32_sdwa v87, v87 dst_sel:BYTE_3 dst_unused:UNUSED_PAD src0_sel:DWORD
	v_lshlrev_b32_e32 v85, 8, v85
	v_and_b32_e32 v86, 0xff0000, v86
	v_perm_b32 v83, v85, v83, s20
	v_or3_b32 v85, v83, v87, v86
	global_store_dwordx2 v[6:7], v[84:85], off offset:512
	v_mul_f32_e32 v84, v147, v100
	v_mul_f32_e32 v83, v147, v99
	v_rndne_f32_e32 v84, v84
	v_mul_f32_e32 v85, v147, v101
	v_rndne_f32_e32 v83, v83
	v_cvt_i32_f32_e32 v84, v84
	v_rndne_f32_e32 v85, v85
	v_mul_f32_e32 v86, v147, v102
	v_cvt_i32_f32_e32 v83, v83
	v_cvt_i32_f32_sdwa v85, v85 dst_sel:WORD_1 dst_unused:UNUSED_PAD src0_sel:DWORD
	v_rndne_f32_e32 v86, v86
	v_cvt_i32_f32_sdwa v86, v86 dst_sel:BYTE_3 dst_unused:UNUSED_PAD src0_sel:DWORD
	v_lshlrev_b32_e32 v84, 8, v84
	v_and_b32_e32 v85, 0xff0000, v85
	v_perm_b32 v83, v84, v83, s20
	v_or3_b32 v84, v83, v86, v85
	v_mul_f32_e32 v85, v147, v104
	v_mul_f32_e32 v83, v147, v103
	v_rndne_f32_e32 v85, v85
	v_mul_f32_e32 v86, v147, v105
	v_rndne_f32_e32 v83, v83
	v_cvt_i32_f32_e32 v85, v85
	v_rndne_f32_e32 v86, v86
	v_mul_f32_e32 v87, v147, v106
	v_cvt_i32_f32_e32 v83, v83
	v_cvt_i32_f32_sdwa v86, v86 dst_sel:WORD_1 dst_unused:UNUSED_PAD src0_sel:DWORD
	v_rndne_f32_e32 v87, v87
	v_cvt_i32_f32_sdwa v87, v87 dst_sel:BYTE_3 dst_unused:UNUSED_PAD src0_sel:DWORD
	v_lshlrev_b32_e32 v85, 8, v85
	v_and_b32_e32 v86, 0xff0000, v86
	v_perm_b32 v83, v85, v83, s20
	v_or3_b32 v85, v83, v87, v86
	global_store_dwordx2 v[6:7], v[84:85], off offset:1024
	v_mul_f32_e32 v84, v147, v108
	v_mul_f32_e32 v83, v147, v107
; __device__ __forceinline__ float bflo(unsigned w) { return __uint_as_float(w << 16); }
; __device__ __forceinline__ float bfhi(unsigned w) { return __uint_as_float(w & 0xffff0000u); }
; __device__ __forceinline__ void quant_store8(const u32x4 (&w)[8], float inv, signed char* dst, int lane) { u32x2* qp = (u32x2*)dst + lane;
; #pragma unroll
;     for (int j = 0; j < 8; ++j) { const unsigned ww[4] = {w[j].x, w[j].y, w[j].z, w[j].w}; unsigned o2[2];
; #pragma unroll
;         for (int h2 = 0; h2 < 2; ++h2) { const int q0 = (int)rintf(bflo(ww[2 * h2]) * inv), q1 = (int)rintf(bfhi(ww[2 * h2]) * inv), q2 = (int)rintf(bflo(ww[2 * h2 + 1]) * inv), q3 = (int)rintf(bfhi(ww[2 * h2 + 1]) * inv);
;             o2[h2] = (unsigned)(q0 & 255) | ((unsigned)(q1 & 255) << 8) | ((unsigned)(q2 & 255) << 16) | ((unsigned)(q3 & 255) << 24); }
;         u32x2 o; o.x = o2[0]; o.y = o2[1]; qp[64 * j] = o; } }
	v_rndne_f32_e32 v84, v84
	v_mul_f32_e32 v85, v147, v109
	v_rndne_f32_e32 v83, v83
	v_cvt_i32_f32_e32 v84, v84
	v_rndne_f32_e32 v85, v85
	v_mul_f32_e32 v86, v147, v110
	v_cvt_i32_f32_e32 v83, v83
	v_cvt_i32_f32_sdwa v85, v85 dst_sel:WORD_1 dst_unused:UNUSED_PAD src0_sel:DWORD
	v_rndne_f32_e32 v86, v86
	v_cvt_i32_f32_sdwa v86, v86 dst_sel:BYTE_3 dst_unused:UNUSED_PAD src0_sel:DWORD
	v_lshlrev_b32_e32 v84, 8, v84
	v_and_b32_e32 v85, 0xff0000, v85
	v_perm_b32 v83, v84, v83, s20
	v_or3_b32 v84, v83, v86, v85
	v_mul_f32_e32 v85, v147, v112
	v_mul_f32_e32 v83, v147, v111
	v_rndne_f32_e32 v85, v85
	v_mul_f32_e32 v86, v147, v113
	v_rndne_f32_e32 v83, v83
	v_cvt_i32_f32_e32 v85, v85
	v_rndne_f32_e32 v86, v86
	v_mul_f32_e32 v87, v147, v114
	v_cvt_i32_f32_e32 v83, v83
	v_cvt_i32_f32_sdwa v86, v86 dst_sel:WORD_1 dst_unused:UNUSED_PAD src0_sel:DWORD
	v_rndne_f32_e32 v87, v87
	v_cvt_i32_f32_sdwa v87, v87 dst_sel:BYTE_3 dst_unused:UNUSED_PAD src0_sel:DWORD
	v_lshlrev_b32_e32 v85, 8, v85
	v_and_b32_e32 v86, 0xff0000, v86
	v_perm_b32 v83, v85, v83, s20
	v_or3_b32 v85, v83, v87, v86
	global_store_dwordx2 v[6:7], v[84:85], off offset:1536
	v_mul_f32_e32 v84, v147, v116
	v_mul_f32_e32 v83, v147, v115
	v_rndne_f32_e32 v84, v84
	v_mul_f32_e32 v85, v147, v117
	v_rndne_f32_e32 v83, v83
	v_cvt_i32_f32_e32 v84, v84
	v_rndne_f32_e32 v85, v85
	v_mul_f32_e32 v86, v147, v118
	v_cvt_i32_f32_e32 v83, v83
	v_cvt_i32_f32_sdwa v85, v85 dst_sel:WORD_1 dst_unused:UNUSED_PAD src0_sel:DWORD
	v_rndne_f32_e32 v86, v86
	v_cvt_i32_f32_sdwa v86, v86 dst_sel:BYTE_3 dst_unused:UNUSED_PAD src0_sel:DWORD
	v_lshlrev_b32_e32 v84, 8, v84
	v_and_b32_e32 v85, 0xff0000, v85
	v_perm_b32 v83, v84, v83, s20
	v_or3_b32 v84, v83, v86, v85
	v_mul_f32_e32 v85, v147, v120
	v_mul_f32_e32 v83, v147, v119
	v_rndne_f32_e32 v85, v85
	v_mul_f32_e32 v86, v147, v121
	v_rndne_f32_e32 v83, v83
	v_cvt_i32_f32_e32 v85, v85
	v_rndne_f32_e32 v86, v86
	v_mul_f32_e32 v87, v147, v122
	v_cvt_i32_f32_e32 v83, v83
	v_cvt_i32_f32_sdwa v86, v86 dst_sel:WORD_1 dst_unused:UNUSED_PAD src0_sel:DWORD
	v_rndne_f32_e32 v87, v87
	v_cvt_i32_f32_sdwa v87, v87 dst_sel:BYTE_3 dst_unused:UNUSED_PAD src0_sel:DWORD
	v_lshlrev_b32_e32 v85, 8, v85
	v_and_b32_e32 v86, 0xff0000, v86
	v_perm_b32 v83, v85, v83, s20
	v_or3_b32 v85, v83, v87, v86
	global_store_dwordx2 v[6:7], v[84:85], off offset:2048
	v_mul_f32_e32 v84, v147, v124
	v_mul_f32_e32 v83, v147, v123
	v_rndne_f32_e32 v84, v84
	v_mul_f32_e32 v85, v147, v125
	v_rndne_f32_e32 v83, v83
	v_cvt_i32_f32_e32 v84, v84
	v_rndne_f32_e32 v85, v85
	v_mul_f32_e32 v86, v147, v126
	v_cvt_i32_f32_e32 v83, v83
	v_cvt_i32_f32_sdwa v85, v85 dst_sel:WORD_1 dst_unused:UNUSED_PAD src0_sel:DWORD
	v_rndne_f32_e32 v86, v86
	v_cvt_i32_f32_sdwa v86, v86 dst_sel:BYTE_3 dst_unused:UNUSED_PAD src0_sel:DWORD
	v_lshlrev_b32_e32 v84, 8, v84
	v_and_b32_e32 v85, 0xff0000, v85
	v_perm_b32 v83, v84, v83, s20
	v_or3_b32 v84, v83, v86, v85
	v_mul_f32_e32 v85, v147, v128
	v_mul_f32_e32 v83, v147, v127
	v_rndne_f32_e32 v85, v85
	v_mul_f32_e32 v86, v147, v129
	v_rndne_f32_e32 v83, v83
	v_cvt_i32_f32_e32 v85, v85
	v_rndne_f32_e32 v86, v86
	v_mul_f32_e32 v87, v147, v130
	v_cvt_i32_f32_e32 v83, v83
	v_cvt_i32_f32_sdwa v86, v86 dst_sel:WORD_1 dst_unused:UNUSED_PAD src0_sel:DWORD
	v_rndne_f32_e32 v87, v87
	v_cvt_i32_f32_sdwa v87, v87 dst_sel:BYTE_3 dst_unused:UNUSED_PAD src0_sel:DWORD
	v_lshlrev_b32_e32 v85, 8, v85
	v_and_b32_e32 v86, 0xff0000, v86
	v_perm_b32 v83, v85, v83, s20
	v_or3_b32 v85, v83, v87, v86
	global_store_dwordx2 v[6:7], v[84:85], off offset:2560
	v_mul_f32_e32 v84, v147, v132
	v_mul_f32_e32 v83, v147, v131
	v_rndne_f32_e32 v84, v84
	v_mul_f32_e32 v85, v147, v133
	v_rndne_f32_e32 v83, v83
	v_cvt_i32_f32_e32 v84, v84
	v_rndne_f32_e32 v85, v85
	v_mul_f32_e32 v86, v147, v134
	v_cvt_i32_f32_e32 v83, v83
	v_cvt_i32_f32_sdwa v85, v85 dst_sel:WORD_1 dst_unused:UNUSED_PAD src0_sel:DWORD
	v_rndne_f32_e32 v86, v86
	v_cvt_i32_f32_sdwa v86, v86 dst_sel:BYTE_3 dst_unused:UNUSED_PAD src0_sel:DWORD
	v_lshlrev_b32_e32 v84, 8, v84
	v_and_b32_e32 v85, 0xff0000, v85
	v_perm_b32 v83, v84, v83, s20
	v_or3_b32 v84, v83, v86, v85
	v_mul_f32_e32 v85, v147, v136
	v_mul_f32_e32 v83, v147, v135
	v_rndne_f32_e32 v85, v85
	v_mul_f32_e32 v86, v147, v137
	v_rndne_f32_e32 v83, v83
	v_cvt_i32_f32_e32 v85, v85
	v_rndne_f32_e32 v86, v86
	v_mul_f32_e32 v87, v147, v138
	v_cvt_i32_f32_e32 v83, v83
	v_cvt_i32_f32_sdwa v86, v86 dst_sel:WORD_1 dst_unused:UNUSED_PAD src0_sel:DWORD
	v_rndne_f32_e32 v87, v87
	v_cvt_i32_f32_sdwa v87, v87 dst_sel:BYTE_3 dst_unused:UNUSED_PAD src0_sel:DWORD
	v_lshlrev_b32_e32 v85, 8, v85
	v_and_b32_e32 v86, 0xff0000, v86
	v_perm_b32 v83, v85, v83, s20
	v_or3_b32 v85, v83, v87, v86
	global_store_dwordx2 v[6:7], v[84:85], off offset:3072
	v_mul_f32_e32 v84, v147, v140
	v_mul_f32_e32 v83, v147, v139
	v_rndne_f32_e32 v84, v84
	v_mul_f32_e32 v85, v147, v141
	v_rndne_f32_e32 v83, v83
	v_cvt_i32_f32_e32 v84, v84
	v_rndne_f32_e32 v85, v85
	v_mul_f32_e32 v86, v147, v142
	v_cvt_i32_f32_e32 v83, v83
	v_cvt_i32_f32_sdwa v85, v85 dst_sel:WORD_1 dst_unused:UNUSED_PAD src0_sel:DWORD
	v_rndne_f32_e32 v86, v86
	v_cvt_i32_f32_sdwa v86, v86 dst_sel:BYTE_3 dst_unused:UNUSED_PAD src0_sel:DWORD
	v_lshlrev_b32_e32 v84, 8, v84
	v_and_b32_e32 v85, 0xff0000, v85
	v_perm_b32 v83, v84, v83, s20
	v_or3_b32 v84, v83, v86, v85
	v_mul_f32_e32 v85, v147, v144
	v_mul_f32_e32 v83, v147, v143
	v_rndne_f32_e32 v85, v85
	v_mul_f32_e32 v86, v147, v145
	v_rndne_f32_e32 v83, v83
	v_cvt_i32_f32_e32 v85, v85
	v_rndne_f32_e32 v86, v86
	v_mul_f32_e32 v87, v147, v146
	v_cvt_i32_f32_e32 v83, v83
	v_cvt_i32_f32_sdwa v86, v86 dst_sel:WORD_1 dst_unused:UNUSED_PAD src0_sel:DWORD
; __device__ __forceinline__ float bflo(unsigned w) { return __uint_as_float(w << 16); }
; __device__ __forceinline__ float bfhi(unsigned w) { return __uint_as_float(w & 0xffff0000u); }
; __device__ __forceinline__ void quant_store8(const u32x4 (&w)[8], float inv, signed char* dst, int lane) { u32x2* qp = (u32x2*)dst + lane;
; #pragma unroll
;     for (int j = 0; j < 8; ++j) { const unsigned ww[4] = {w[j].x, w[j].y, w[j].z, w[j].w}; unsigned o2[2];
; #pragma unroll
;         for (int h2 = 0; h2 < 2; ++h2) { const int q0 = (int)rintf(bflo(ww[2 * h2]) * inv), q1 = (int)rintf(bfhi(ww[2 * h2]) * inv), q2 = (int)rintf(bflo(ww[2 * h2 + 1]) * inv), q3 = (int)rintf(bfhi(ww[2 * h2 + 1]) * inv);
;             o2[h2] = (unsigned)(q0 & 255) | ((unsigned)(q1 & 255) << 8) | ((unsigned)(q2 & 255) << 16) | ((unsigned)(q3 & 255) << 24); }
;         u32x2 o; o.x = o2[0]; o.y = o2[1]; qp[64 * j] = o; } }
; __device__ __forceinline__ void quant_rows2(const bf16_t* s0, const bf16_t* s1, signed char* d0, signed char* d1, int lane, float& step0, float& step1) {
;     const u32x4* p0 = (const u32x4*)s0 + lane; const u32x4* p1 = (const u32x4*)s1 + lane; u32x4 w0[8], w1[8];
; #pragma unroll
;     for (int j = 0; j < 8; ++j) { w0[j] = p0[64 * j]; w1[j] = p1[64 * j]; }
;     step0 = fmaxf(absmax8(w0), 1e-30f) * (1.0f / 127.0f); step1 = fmaxf(absmax8(w1), 1e-30f) * (1.0f / 127.0f);
;     quant_store8(w0, 1.0f / step0, d0, lane); quant_store8(w1, 1.0f / step1, d1, lane);
	v_rndne_f32_e32 v87, v87
	v_cvt_i32_f32_sdwa v87, v87 dst_sel:BYTE_3 dst_unused:UNUSED_PAD src0_sel:DWORD
	v_div_scale_f32 v88, s[14:15], v3, v3, 1.0
	v_rcp_f32_e32 v89, v88
	v_lshlrev_b32_e32 v85, 8, v85
	v_and_b32_e32 v86, 0xff0000, v86
	v_perm_b32 v83, v85, v83, s20
	v_or3_b32 v85, v83, v87, v86
	global_store_dwordx2 v[6:7], v[84:85], off offset:3584
	v_fma_f32 v6, -v88, v89, 1.0
	v_fmac_f32_e32 v89, v6, v89
	v_div_scale_f32 v6, vcc, 1.0, v3, 1.0
	v_mul_f32_e32 v7, v6, v89
	v_fma_f32 v83, -v88, v7, v6
	v_fmac_f32_e32 v7, v83, v89
	v_fma_f32 v6, -v88, v7, v6
	v_div_fmas_f32 v6, v6, v89, v7
	v_div_fixup_f32 v83, v6, v3, 1.0
	v_mul_f32_e32 v7, v83, v80
	v_mul_f32_e32 v6, v83, v82
	v_rndne_f32_e32 v7, v7
	v_rndne_f32_e32 v6, v6
	v_cvt_i32_f32_e32 v7, v7
	v_cvt_i32_f32_e32 v6, v6
	v_mul_f32_e32 v77, v83, v77
	v_mul_f32_e32 v80, v83, v81
	v_lshlrev_b32_e32 v7, 8, v7
	v_perm_b32 v6, v7, v6, s20
	v_mul_f32_e32 v7, v83, v78
	v_rndne_f32_e32 v77, v77
	v_mul_f32_e32 v76, v83, v76
	v_rndne_f32_e32 v80, v80
	v_mul_f32_e32 v79, v83, v79
	v_rndne_f32_e32 v7, v7
	v_cvt_i32_f32_e32 v77, v77
	v_rndne_f32_e32 v76, v76
	v_mul_f32_e32 v75, v83, v75
	v_cvt_i32_f32_sdwa v80, v80 dst_sel:WORD_1 dst_unused:UNUSED_PAD src0_sel:DWORD
	v_rndne_f32_e32 v79, v79
	v_cvt_i32_f32_e32 v7, v7
	v_cvt_i32_f32_sdwa v76, v76 dst_sel:WORD_1 dst_unused:UNUSED_PAD src0_sel:DWORD
	v_rndne_f32_e32 v75, v75
	v_cvt_i32_f32_sdwa v79, v79 dst_sel:BYTE_3 dst_unused:UNUSED_PAD src0_sel:DWORD
	v_cvt_i32_f32_sdwa v75, v75 dst_sel:BYTE_3 dst_unused:UNUSED_PAD src0_sel:DWORD
	v_lshlrev_b32_e32 v77, 8, v77
	v_and_b32_e32 v80, 0xff0000, v80
	v_and_b32_e32 v76, 0xff0000, v76
	v_perm_b32 v7, v77, v7, s20
	v_or3_b32 v6, v6, v79, v80
	v_or3_b32 v7, v7, v75, v76
	global_store_dwordx2 v[4:5], v[6:7], off
	v_mul_f32_e32 v7, v83, v72
	v_mul_f32_e32 v6, v83, v74
	v_rndne_f32_e32 v7, v7
	v_rndne_f32_e32 v6, v6
	v_cvt_i32_f32_e32 v7, v7
	v_cvt_i32_f32_e32 v6, v6
	v_mul_f32_e32 v69, v83, v69
	v_mul_f32_e32 v72, v83, v73
	v_lshlrev_b32_e32 v7, 8, v7
	v_perm_b32 v6, v7, v6, s20
	v_mul_f32_e32 v7, v83, v70
	v_rndne_f32_e32 v69, v69
	v_mul_f32_e32 v68, v83, v68
	v_rndne_f32_e32 v72, v72
	v_mul_f32_e32 v71, v83, v71
	v_rndne_f32_e32 v7, v7
	v_cvt_i32_f32_e32 v69, v69
	v_rndne_f32_e32 v68, v68
	v_mul_f32_e32 v67, v83, v67
	v_cvt_i32_f32_sdwa v72, v72 dst_sel:WORD_1 dst_unused:UNUSED_PAD src0_sel:DWORD
	v_rndne_f32_e32 v71, v71
	v_cvt_i32_f32_e32 v7, v7
	v_cvt_i32_f32_sdwa v68, v68 dst_sel:WORD_1 dst_unused:UNUSED_PAD src0_sel:DWORD
	v_rndne_f32_e32 v67, v67
	v_cvt_i32_f32_sdwa v71, v71 dst_sel:BYTE_3 dst_unused:UNUSED_PAD src0_sel:DWORD
	v_cvt_i32_f32_sdwa v67, v67 dst_sel:BYTE_3 dst_unused:UNUSED_PAD src0_sel:DWORD
	v_lshlrev_b32_e32 v69, 8, v69
	v_and_b32_e32 v72, 0xff0000, v72
	v_and_b32_e32 v68, 0xff0000, v68
	v_perm_b32 v7, v69, v7, s20
	v_or3_b32 v6, v6, v71, v72
	v_or3_b32 v7, v7, v67, v68
	global_store_dwordx2 v[4:5], v[6:7], off offset:512
	v_mul_f32_e32 v7, v83, v64
	v_mul_f32_e32 v6, v83, v66
	v_rndne_f32_e32 v7, v7
	v_rndne_f32_e32 v6, v6
	v_cvt_i32_f32_e32 v7, v7
	v_cvt_i32_f32_e32 v6, v6
	v_mul_f32_e32 v61, v83, v61
	v_mul_f32_e32 v64, v83, v65
	v_lshlrev_b32_e32 v7, 8, v7
	v_perm_b32 v6, v7, v6, s20
	v_mul_f32_e32 v7, v83, v62
	v_rndne_f32_e32 v61, v61
	v_mul_f32_e32 v60, v83, v60
	v_rndne_f32_e32 v64, v64
	v_mul_f32_e32 v63, v83, v63
	v_rndne_f32_e32 v7, v7
	v_cvt_i32_f32_e32 v61, v61
	v_rndne_f32_e32 v60, v60
	v_mul_f32_e32 v59, v83, v59
	v_cvt_i32_f32_sdwa v64, v64 dst_sel:WORD_1 dst_unused:UNUSED_PAD src0_sel:DWORD
	v_rndne_f32_e32 v63, v63
	v_cvt_i32_f32_e32 v7, v7
	v_cvt_i32_f32_sdwa v60, v60 dst_sel:WORD_1 dst_unused:UNUSED_PAD src0_sel:DWORD
	v_rndne_f32_e32 v59, v59
	v_cvt_i32_f32_sdwa v63, v63 dst_sel:BYTE_3 dst_unused:UNUSED_PAD src0_sel:DWORD
	v_cvt_i32_f32_sdwa v59, v59 dst_sel:BYTE_3 dst_unused:UNUSED_PAD src0_sel:DWORD
	v_lshlrev_b32_e32 v61, 8, v61
	v_and_b32_e32 v64, 0xff0000, v64
	v_and_b32_e32 v60, 0xff0000, v60
	v_perm_b32 v7, v61, v7, s20
	v_or3_b32 v6, v6, v63, v64
	v_or3_b32 v7, v7, v59, v60
	global_store_dwordx2 v[4:5], v[6:7], off offset:1024
	v_mul_f32_e32 v7, v83, v56
	v_mul_f32_e32 v6, v83, v58
	v_rndne_f32_e32 v7, v7
	v_rndne_f32_e32 v6, v6
	v_cvt_i32_f32_e32 v7, v7
	v_cvt_i32_f32_e32 v6, v6
	v_mul_f32_e32 v53, v83, v53
	v_mul_f32_e32 v56, v83, v57
	v_lshlrev_b32_e32 v7, 8, v7
	v_perm_b32 v6, v7, v6, s20
	v_mul_f32_e32 v7, v83, v54
	v_rndne_f32_e32 v53, v53
	v_mul_f32_e32 v52, v83, v52
	v_rndne_f32_e32 v56, v56
	v_mul_f32_e32 v55, v83, v55
	v_rndne_f32_e32 v7, v7
	v_cvt_i32_f32_e32 v53, v53
	v_rndne_f32_e32 v52, v52
	v_mul_f32_e32 v51, v83, v51
	v_cvt_i32_f32_sdwa v56, v56 dst_sel:WORD_1 dst_unused:UNUSED_PAD src0_sel:DWORD
	v_rndne_f32_e32 v55, v55
	v_cvt_i32_f32_e32 v7, v7
	v_cvt_i32_f32_sdwa v52, v52 dst_sel:WORD_1 dst_unused:UNUSED_PAD src0_sel:DWORD
	v_rndne_f32_e32 v51, v51
	v_cvt_i32_f32_sdwa v55, v55 dst_sel:BYTE_3 dst_unused:UNUSED_PAD src0_sel:DWORD
	v_cvt_i32_f32_sdwa v51, v51 dst_sel:BYTE_3 dst_unused:UNUSED_PAD src0_sel:DWORD
; __device__ __forceinline__ float bflo(unsigned w) { return __uint_as_float(w << 16); }
; __device__ __forceinline__ float bfhi(unsigned w) { return __uint_as_float(w & 0xffff0000u); }
; __device__ __forceinline__ void quant_store8(const u32x4 (&w)[8], float inv, signed char* dst, int lane) { u32x2* qp = (u32x2*)dst + lane;
; #pragma unroll
;     for (int j = 0; j < 8; ++j) { const unsigned ww[4] = {w[j].x, w[j].y, w[j].z, w[j].w}; unsigned o2[2];
; #pragma unroll
;         for (int h2 = 0; h2 < 2; ++h2) { const int q0 = (int)rintf(bflo(ww[2 * h2]) * inv), q1 = (int)rintf(bfhi(ww[2 * h2]) * inv), q2 = (int)rintf(bflo(ww[2 * h2 + 1]) * inv), q3 = (int)rintf(bfhi(ww[2 * h2 + 1]) * inv);
;             o2[h2] = (unsigned)(q0 & 255) | ((unsigned)(q1 & 255) << 8) | ((unsigned)(q2 & 255) << 16) | ((unsigned)(q3 & 255) << 24); }
;         u32x2 o; o.x = o2[0]; o.y = o2[1]; qp[64 * j] = o; } }
; __global__ void __launch_bounds__(NWAVES * 64, 2) fwd(Args args) {
;     ...
;             for (int p = 0; p < 4; ++p) { const int n = 64 * bx + 8 * F.wave + 2 * p; float s0, s1;
;                 quant_rows2(W_inT + (size_t)(IN_Q0 + n) * DM, W_inT + (size_t)(IN_Q0 + n + 1) * DM, W_inq + (size_t)n * DM, W_inq + (size_t)(n + 1) * DM, F.lane, s0, s1);
;                 if (F.lane == 0) { colq[n] = s0; colq[n + 1] = s1; } }
	v_lshlrev_b32_e32 v53, 8, v53
	v_and_b32_e32 v56, 0xff0000, v56
	v_and_b32_e32 v52, 0xff0000, v52
	v_perm_b32 v7, v53, v7, s20
	v_or3_b32 v6, v6, v55, v56
	v_or3_b32 v7, v7, v51, v52
	global_store_dwordx2 v[4:5], v[6:7], off offset:1536
	v_mul_f32_e32 v7, v83, v48
	v_mul_f32_e32 v6, v83, v50
	v_rndne_f32_e32 v7, v7
	v_rndne_f32_e32 v6, v6
	v_cvt_i32_f32_e32 v7, v7
	v_cvt_i32_f32_e32 v6, v6
	v_mul_f32_e32 v45, v83, v45
	v_mul_f32_e32 v48, v83, v49
	v_lshlrev_b32_e32 v7, 8, v7
	v_perm_b32 v6, v7, v6, s20
	v_mul_f32_e32 v7, v83, v46
	v_rndne_f32_e32 v45, v45
	v_mul_f32_e32 v44, v83, v44
	v_rndne_f32_e32 v48, v48
	v_mul_f32_e32 v47, v83, v47
	v_rndne_f32_e32 v7, v7
	v_cvt_i32_f32_e32 v45, v45
	v_rndne_f32_e32 v44, v44
	v_mul_f32_e32 v43, v83, v43
	v_cvt_i32_f32_sdwa v48, v48 dst_sel:WORD_1 dst_unused:UNUSED_PAD src0_sel:DWORD
	v_rndne_f32_e32 v47, v47
	v_cvt_i32_f32_e32 v7, v7
	v_cvt_i32_f32_sdwa v44, v44 dst_sel:WORD_1 dst_unused:UNUSED_PAD src0_sel:DWORD
	v_rndne_f32_e32 v43, v43
	v_cvt_i32_f32_sdwa v47, v47 dst_sel:BYTE_3 dst_unused:UNUSED_PAD src0_sel:DWORD
	v_cvt_i32_f32_sdwa v43, v43 dst_sel:BYTE_3 dst_unused:UNUSED_PAD src0_sel:DWORD
	v_lshlrev_b32_e32 v45, 8, v45
	v_and_b32_e32 v48, 0xff0000, v48
	v_and_b32_e32 v44, 0xff0000, v44
	v_perm_b32 v7, v45, v7, s20
	v_or3_b32 v6, v6, v47, v48
	v_or3_b32 v7, v7, v43, v44
	global_store_dwordx2 v[4:5], v[6:7], off offset:2048
	v_mul_f32_e32 v7, v83, v29
	v_mul_f32_e32 v6, v83, v42
	v_rndne_f32_e32 v7, v7
	v_rndne_f32_e32 v6, v6
	v_cvt_i32_f32_e32 v7, v7
	v_cvt_i32_f32_e32 v6, v6
	v_mul_f32_e32 v26, v83, v26
	v_mul_f32_e32 v29, v83, v41
	v_lshlrev_b32_e32 v7, 8, v7
	v_perm_b32 v6, v7, v6, s20
	v_mul_f32_e32 v7, v83, v27
	v_rndne_f32_e32 v26, v26
	v_mul_f32_e32 v25, v83, v25
	v_rndne_f32_e32 v29, v29
	v_mul_f32_e32 v28, v83, v28
	v_rndne_f32_e32 v7, v7
	v_cvt_i32_f32_e32 v26, v26
	v_rndne_f32_e32 v25, v25
	v_mul_f32_e32 v24, v83, v24
	v_cvt_i32_f32_sdwa v29, v29 dst_sel:WORD_1 dst_unused:UNUSED_PAD src0_sel:DWORD
	v_rndne_f32_e32 v28, v28
	v_cvt_i32_f32_e32 v7, v7
	v_cvt_i32_f32_sdwa v25, v25 dst_sel:WORD_1 dst_unused:UNUSED_PAD src0_sel:DWORD
	v_rndne_f32_e32 v24, v24
	v_cvt_i32_f32_sdwa v28, v28 dst_sel:BYTE_3 dst_unused:UNUSED_PAD src0_sel:DWORD
	v_cvt_i32_f32_sdwa v24, v24 dst_sel:BYTE_3 dst_unused:UNUSED_PAD src0_sel:DWORD
	v_lshlrev_b32_e32 v26, 8, v26
	v_and_b32_e32 v29, 0xff0000, v29
	v_and_b32_e32 v25, 0xff0000, v25
	v_perm_b32 v7, v26, v7, s20
	v_or3_b32 v6, v6, v28, v29
	v_or3_b32 v7, v7, v24, v25
	global_store_dwordx2 v[4:5], v[6:7], off offset:2560
	v_mul_f32_e32 v7, v83, v21
	v_mul_f32_e32 v6, v83, v23
	v_rndne_f32_e32 v7, v7
	v_rndne_f32_e32 v6, v6
	v_cvt_i32_f32_e32 v7, v7
	v_cvt_i32_f32_e32 v6, v6
	v_mul_f32_e32 v18, v83, v18
	v_mul_f32_e32 v21, v83, v22
	v_lshlrev_b32_e32 v7, 8, v7
	v_perm_b32 v6, v7, v6, s20
	v_mul_f32_e32 v7, v83, v19
	v_rndne_f32_e32 v18, v18
	v_mul_f32_e32 v17, v83, v17
	v_rndne_f32_e32 v21, v21
	v_mul_f32_e32 v20, v83, v20
	v_rndne_f32_e32 v7, v7
	v_cvt_i32_f32_e32 v18, v18
	v_rndne_f32_e32 v17, v17
	v_mul_f32_e32 v16, v83, v16
	v_cvt_i32_f32_sdwa v21, v21 dst_sel:WORD_1 dst_unused:UNUSED_PAD src0_sel:DWORD
	v_rndne_f32_e32 v20, v20
	v_cvt_i32_f32_e32 v7, v7
	v_cvt_i32_f32_sdwa v17, v17 dst_sel:WORD_1 dst_unused:UNUSED_PAD src0_sel:DWORD
	v_rndne_f32_e32 v16, v16
	v_cvt_i32_f32_sdwa v20, v20 dst_sel:BYTE_3 dst_unused:UNUSED_PAD src0_sel:DWORD
	v_cvt_i32_f32_sdwa v16, v16 dst_sel:BYTE_3 dst_unused:UNUSED_PAD src0_sel:DWORD
	v_lshlrev_b32_e32 v18, 8, v18
	v_and_b32_e32 v21, 0xff0000, v21
	v_and_b32_e32 v17, 0xff0000, v17
	v_perm_b32 v7, v18, v7, s20
	v_or3_b32 v6, v6, v20, v21
	v_or3_b32 v7, v7, v16, v17
	global_store_dwordx2 v[4:5], v[6:7], off offset:3072
	v_mul_f32_e32 v7, v83, v13
	v_mul_f32_e32 v6, v83, v15
	v_rndne_f32_e32 v7, v7
	v_rndne_f32_e32 v6, v6
	v_cvt_i32_f32_e32 v7, v7
	v_cvt_i32_f32_e32 v6, v6
	v_mul_f32_e32 v10, v83, v10
	v_mul_f32_e32 v13, v83, v14
	v_lshlrev_b32_e32 v7, 8, v7
	v_perm_b32 v6, v7, v6, s20
	v_mul_f32_e32 v7, v83, v11
	v_rndne_f32_e32 v10, v10
	v_mul_f32_e32 v9, v83, v9
	v_rndne_f32_e32 v13, v13
	v_mul_f32_e32 v12, v83, v12
	v_rndne_f32_e32 v7, v7
	v_cvt_i32_f32_e32 v10, v10
	v_rndne_f32_e32 v9, v9
	v_mul_f32_e32 v8, v83, v8
	v_cvt_i32_f32_sdwa v13, v13 dst_sel:WORD_1 dst_unused:UNUSED_PAD src0_sel:DWORD
	v_rndne_f32_e32 v12, v12
	v_cvt_i32_f32_e32 v7, v7
	v_cvt_i32_f32_sdwa v9, v9 dst_sel:WORD_1 dst_unused:UNUSED_PAD src0_sel:DWORD
	v_rndne_f32_e32 v8, v8
	v_cvt_i32_f32_sdwa v12, v12 dst_sel:BYTE_3 dst_unused:UNUSED_PAD src0_sel:DWORD
	v_cvt_i32_f32_sdwa v8, v8 dst_sel:BYTE_3 dst_unused:UNUSED_PAD src0_sel:DWORD
	v_lshlrev_b32_e32 v10, 8, v10
	v_and_b32_e32 v13, 0xff0000, v13
	v_and_b32_e32 v9, 0xff0000, v9
	v_perm_b32 v7, v10, v7, s20
	v_or3_b32 v6, v6, v12, v13
	v_or3_b32 v7, v7, v8, v9
	global_store_dwordx2 v[4:5], v[6:7], off offset:3584
	s_and_saveexec_b64 s[14:15], s[4:5]
	s_cbranch_execz .LBB0_63
	s_add_u32 s24, s78, s7
	s_addc_u32 s25, s79, s16
	global_store_dwordx2 v40, v[2:3], s[24:25]
	s_branch .LBB0_63

; __device__ __forceinline__ float bflo(unsigned w) { return __uint_as_float(w << 16); }
; __device__ __forceinline__ float bfhi(unsigned w) { return __uint_as_float(w & 0xffff0000u); }
; #pragma unroll
;     for (int j = 0; j < 8; ++j) mx = fmaxf(mx, fmaxf(fmaxf(fmaxf(fabsf(bflo(w[j].x)), fabsf(bfhi(w[j].x))), fmaxf(fabsf(bflo(w[j].y)), fabsf(bfhi(w[j].y)))), fmaxf(fmaxf(fabsf(bflo(w[j].z)), fabsf(bfhi(w[j].z))), fmaxf(fabsf(bflo(w[j].w)), fabsf(bfhi(w[j].w))))));
; #pragma unroll
;     for (int o = 1; o < 64; o <<= 1) mx = fmaxf(mx, __shfl_xor(mx, o));
;     return mx; }
; __device__ __forceinline__ void quant_store8(const u32x4 (&w)[8], float inv, signed char* dst, int lane) { u32x2* qp = (u32x2*)dst + lane;
; #pragma unroll
;     for (int j = 0; j < 8; ++j) { const unsigned ww[4] = {w[j].x, w[j].y, w[j].z, w[j].w}; unsigned o2[2];
; #pragma unroll
;         for (int h2 = 0; h2 < 2; ++h2) { const int q0 = (int)rintf(bflo(ww[2 * h2]) * inv), q1 = (int)rintf(bfhi(ww[2 * h2]) * inv), q2 = (int)rintf(bflo(ww[2 * h2 + 1]) * inv), q3 = (int)rintf(bfhi(ww[2 * h2 + 1]) * inv);
;             o2[h2] = (unsigned)(q0 & 255) | ((unsigned)(q1 & 255) << 8) | ((unsigned)(q2 & 255) << 16) | ((unsigned)(q3 & 255) << 24); }
;         u32x2 o; o.x = o2[0]; o.y = o2[1]; qp[64 * j] = o; } }
; __device__ __forceinline__ void quant_rows2(const bf16_t* s0, const bf16_t* s1, signed char* d0, signed char* d1, int lane, float& step0, float& step1) {
;     const u32x4* p0 = (const u32x4*)s0 + lane; const u32x4* p1 = (const u32x4*)s1 + lane; u32x4 w0[8], w1[8];
; #pragma unroll
;     for (int j = 0; j < 8; ++j) { w0[j] = p0[64 * j]; w1[j] = p1[64 * j]; }
;     step0 = fmaxf(absmax8(w0), 1e-30f) * (1.0f / 127.0f); step1 = fmaxf(absmax8(w1), 1e-30f) * (1.0f / 127.0f);
.LBB0_160:
	v_lshl_add_u64 v[2:3], s[78:79], 0, v[30:31]
	v_add_co_u32_e32 v4, vcc, 0x10800000, v2
	s_nop 1
	v_addc_co_u32_e32 v5, vcc, 0, v3, vcc
	global_load_dwordx4 v[42:45], v[4:5], off
	global_load_dwordx4 v[46:49], v[4:5], off offset:1024
	global_load_dwordx4 v[50:53], v[4:5], off offset:2048
	global_load_dwordx4 v[54:57], v[4:5], off offset:3072
	v_add_co_u32_e32 v6, vcc, 0x10802000, v2
	s_nop 1
	v_addc_co_u32_e32 v7, vcc, 0, v3, vcc
	v_add_co_u32_e32 v4, vcc, s13, v2
	global_load_dwordx4 v[58:61], v[6:7], off
	global_load_dwordx4 v[26:29], v[6:7], off offset:1024
	global_load_dwordx4 v[22:25], v[6:7], off offset:2048
	global_load_dwordx4 v[18:21], v[6:7], off offset:3072
	v_addc_co_u32_e32 v5, vcc, 0, v3, vcc
	v_add_co_u32_e32 v2, vcc, s22, v2
	s_nop 1
	v_addc_co_u32_e32 v3, vcc, 0, v3, vcc
	global_load_dwordx4 v[62:65], v[4:5], off
	global_load_dwordx4 v[66:69], v[4:5], off offset:1024
	global_load_dwordx4 v[70:73], v[4:5], off offset:2048
	global_load_dwordx4 v[74:77], v[4:5], off offset:3072
	global_load_dwordx4 v[14:17], v[2:3], off
	global_load_dwordx4 v[10:13], v[2:3], off offset:1024
	global_load_dwordx4 v[6:9], v[2:3], off offset:2048
	s_nop 0
	global_load_dwordx4 v[2:5], v[2:3], off offset:3072
	s_waitcnt vmcnt(15)
	v_lshlrev_b32_e32 v83, 16, v42
	v_and_b32_e32 v84, 0xffff0000, v42
	v_lshlrev_b32_e32 v85, 16, v43
	v_and_b32_e32 v86, 0xffff0000, v43
	v_lshlrev_b32_e32 v89, 16, v45
	v_and_b32_e32 v90, 0xffff0000, v45
	s_waitcnt vmcnt(14)
	v_lshlrev_b32_e32 v97, 16, v49
	v_and_b32_e32 v98, 0xffff0000, v49
	v_lshlrev_b32_e32 v87, 16, v44
	v_and_b32_e32 v88, 0xffff0000, v44
	v_lshlrev_b32_e32 v91, 16, v46
	v_and_b32_e32 v92, 0xffff0000, v46
	v_lshlrev_b32_e32 v93, 16, v47
	v_and_b32_e32 v94, 0xffff0000, v47
	s_waitcnt vmcnt(13)
	v_lshlrev_b32_e32 v101, 16, v51
	v_and_b32_e32 v102, 0xffff0000, v51
	v_lshlrev_b32_e32 v103, 16, v52
	v_and_b32_e32 v104, 0xffff0000, v52
	v_max_f32_e64 v41, |v84|, |v84|
	v_max_f32_e64 v42, |v83|, |v83|
	v_max_f32_e64 v43, |v86|, |v86|
	v_max_f32_e64 v44, |v85|, |v85|
	v_max_f32_e64 v45, |v90|, |v90|
	v_max_f32_e64 v46, |v89|, |v89|
	v_max_f32_e64 v51, |v98|, |v98|
	v_max_f32_e64 v52, |v97|, |v97|
	v_lshlrev_b32_e32 v95, 16, v48
	v_and_b32_e32 v96, 0xffff0000, v48
	v_lshlrev_b32_e32 v99, 16, v50
	v_and_b32_e32 v100, 0xffff0000, v50
	v_max_f32_e64 v47, |v92|, |v92|
	v_max_f32_e64 v48, |v91|, |v91|
	v_max_f32_e64 v49, |v94|, |v94|
	v_max_f32_e64 v50, |v93|, |v93|
	v_max_f32_e32 v41, v42, v41
	v_max_f32_e32 v42, v44, v43
	v_max_f32_e32 v43, v46, v45
	v_max_f32_e32 v46, v52, v51
	v_max_f32_e32 v44, v48, v47
	v_max_f32_e32 v45, v50, v49
	v_max3_f32 v43, |v87|, |v88|, v43
	v_max3_f32 v46, |v95|, |v96|, v46
	v_lshlrev_b32_e32 v105, 16, v53
	v_max3_f32 v41, v41, v42, v43
	v_max3_f32 v42, v44, v45, v46
	v_and_b32_e32 v106, 0xffff0000, v53
	v_max3_f32 v41, v41, 0, v42
	v_max_f32_e64 v42, |v106|, |v106|
	v_max_f32_e64 v43, |v105|, |v105|
	s_waitcnt vmcnt(12)
	v_lshlrev_b32_e32 v107, 16, v54
	v_and_b32_e32 v108, 0xffff0000, v54
	v_max_f32_e32 v42, v43, v42
	v_max_f32_e64 v43, |v108|, |v108|
	v_max_f32_e64 v44, |v107|, |v107|
	v_lshlrev_b32_e32 v109, 16, v55
	v_and_b32_e32 v110, 0xffff0000, v55
	v_max_f32_e32 v43, v44, v43
	v_max_f32_e64 v44, |v110|, |v110|
	v_max_f32_e64 v45, |v109|, |v109|
	v_lshlrev_b32_e32 v113, 16, v57
	v_and_b32_e32 v114, 0xffff0000, v57
	v_max_f32_e32 v44, v45, v44
	v_max_f32_e64 v45, |v114|, |v114|
	v_max_f32_e64 v46, |v113|, |v113|
	v_max_f32_e64 v78, |v100|, |v100|
	v_max_f32_e64 v79, |v99|, |v99|
	v_max_f32_e64 v80, |v102|, |v102|
	v_max_f32_e64 v81, |v101|, |v101|
	v_lshlrev_b32_e32 v111, 16, v56
	v_and_b32_e32 v112, 0xffff0000, v56
	v_max_f32_e32 v45, v46, v45
	v_max_f32_e32 v47, v79, v78
	v_max_f32_e32 v48, v81, v80
	v_max3_f32 v42, |v103|, |v104|, v42
	v_max3_f32 v45, |v111|, |v112|, v45
	v_max3_f32 v42, v47, v48, v42
	v_max3_f32 v43, v43, v44, v45
	s_waitcnt vmcnt(7)
	v_lshlrev_b32_e32 v115, 16, v62
	v_and_b32_e32 v116, 0xffff0000, v62
	v_max3_f32 v41, v41, v42, v43
	v_max_f32_e64 v42, |v116|, |v116|
	v_max_f32_e64 v43, |v115|, |v115|
	v_lshlrev_b32_e32 v117, 16, v63
	v_and_b32_e32 v118, 0xffff0000, v63
	v_max_f32_e32 v42, v43, v42
	v_max_f32_e64 v43, |v118|, |v118|
	v_max_f32_e64 v44, |v117|, |v117|
	v_lshlrev_b32_e32 v121, 16, v65
	v_and_b32_e32 v122, 0xffff0000, v65
	v_max_f32_e32 v43, v44, v43
	v_max_f32_e64 v44, |v122|, |v122|
	v_max_f32_e64 v45, |v121|, |v121|
	v_lshlrev_b32_e32 v119, 16, v64
	v_and_b32_e32 v120, 0xffff0000, v64
	v_max_f32_e32 v44, v45, v44
	v_max3_f32 v44, |v119|, |v120|, v44
	s_waitcnt vmcnt(6)
	v_lshlrev_b32_e32 v123, 16, v66
	v_and_b32_e32 v124, 0xffff0000, v66
	v_max3_f32 v42, v42, v43, v44
	v_max_f32_e64 v43, |v124|, |v124|
	v_max_f32_e64 v44, |v123|, |v123|
	v_lshlrev_b32_e32 v125, 16, v67
	v_and_b32_e32 v126, 0xffff0000, v67
	v_max_f32_e32 v43, v44, v43
	v_max_f32_e64 v44, |v126|, |v126|
	v_max_f32_e64 v45, |v125|, |v125|
	v_lshlrev_b32_e32 v129, 16, v69
	v_and_b32_e32 v130, 0xffff0000, v69
	v_max_f32_e32 v44, v45, v44
	v_max_f32_e64 v45, |v130|, |v130|
	v_max_f32_e64 v46, |v129|, |v129|
	v_lshlrev_b32_e32 v127, 16, v68
	v_and_b32_e32 v128, 0xffff0000, v68
	v_max_f32_e32 v45, v46, v45
	v_max3_f32 v45, |v127|, |v128|, v45
	v_max3_f32 v43, v43, v44, v45
	s_waitcnt vmcnt(5)
	v_lshlrev_b32_e32 v131, 16, v70
	v_and_b32_e32 v132, 0xffff0000, v70
	v_max3_f32 v41, v41, v42, v43
	v_max_f32_e64 v42, |v132|, |v132|
	v_max_f32_e64 v43, |v131|, |v131|
	v_lshlrev_b32_e32 v133, 16, v71
	v_and_b32_e32 v137, 0xffff0000, v71
	v_max_f32_e32 v42, v43, v42
	v_max_f32_e64 v43, |v137|, |v137|
	v_max_f32_e64 v44, |v133|, |v133|
	v_lshlrev_b32_e32 v140, 16, v73
	v_and_b32_e32 v141, 0xffff0000, v73
	v_max_f32_e32 v43, v44, v43
	v_max_f32_e64 v44, |v141|, |v141|
	v_max_f32_e64 v45, |v140|, |v140|
	v_lshlrev_b32_e32 v138, 16, v72
	v_and_b32_e32 v139, 0xffff0000, v72
	v_max_f32_e32 v44, v45, v44
	v_max3_f32 v44, |v138|, |v139|, v44
	s_waitcnt vmcnt(4)
; __device__ __forceinline__ float bflo(unsigned w) { return __uint_as_float(w << 16); }
; __device__ __forceinline__ float bfhi(unsigned w) { return __uint_as_float(w & 0xffff0000u); }
; #pragma unroll
;     for (int j = 0; j < 8; ++j) mx = fmaxf(mx, fmaxf(fmaxf(fmaxf(fabsf(bflo(w[j].x)), fabsf(bfhi(w[j].x))), fmaxf(fabsf(bflo(w[j].y)), fabsf(bfhi(w[j].y)))), fmaxf(fmaxf(fabsf(bflo(w[j].z)), fabsf(bfhi(w[j].z))), fmaxf(fabsf(bflo(w[j].w)), fabsf(bfhi(w[j].w))))));
; #pragma unroll
;     for (int o = 1; o < 64; o <<= 1) mx = fmaxf(mx, __shfl_xor(mx, o));
;     return mx; }
	v_lshlrev_b32_e32 v142, 16, v74
	v_and_b32_e32 v143, 0xffff0000, v74
	v_max3_f32 v42, v42, v43, v44
	v_max_f32_e64 v43, |v143|, |v143|
	v_max_f32_e64 v44, |v142|, |v142|
	v_lshlrev_b32_e32 v144, 16, v75
	v_and_b32_e32 v145, 0xffff0000, v75
	v_max_f32_e32 v43, v44, v43
	v_max_f32_e64 v44, |v145|, |v145|
	v_max_f32_e64 v45, |v144|, |v144|
	v_lshlrev_b32_e32 v148, 16, v77
	v_and_b32_e32 v149, 0xffff0000, v77
	v_max_f32_e32 v44, v45, v44
	v_max_f32_e64 v45, |v149|, |v149|
	v_max_f32_e64 v46, |v148|, |v148|
	v_lshlrev_b32_e32 v146, 16, v76
	v_and_b32_e32 v147, 0xffff0000, v76
	v_max_f32_e32 v45, v46, v45
	v_max3_f32 v45, |v146|, |v147|, v45
	v_max3_f32 v43, v43, v44, v45
	v_lshlrev_b32_e32 v82, 16, v58
	v_and_b32_e32 v80, 0xffff0000, v58
	v_max3_f32 v156, v41, v42, v43
	v_max_f32_e64 v41, |v80|, |v80|
	v_max_f32_e64 v42, |v82|, |v82|
	v_lshlrev_b32_e32 v81, 16, v59
	v_and_b32_e32 v79, 0xffff0000, v59
	v_max_f32_e32 v41, v42, v41
	v_max_f32_e64 v42, |v79|, |v79|
	v_max_f32_e64 v43, |v81|, |v81|
	v_lshlrev_b32_e32 v76, 16, v61
	v_and_b32_e32 v75, 0xffff0000, v61
	v_max_f32_e32 v42, v43, v42
	v_max_f32_e64 v43, |v75|, |v75|
	v_max_f32_e64 v44, |v76|, |v76|
	v_lshlrev_b32_e32 v78, 16, v60
	v_and_b32_e32 v77, 0xffff0000, v60
	v_max_f32_e32 v43, v44, v43
	v_max3_f32 v43, |v78|, |v77|, v43
	v_lshlrev_b32_e32 v74, 16, v26
	v_and_b32_e32 v72, 0xffff0000, v26
	v_lshlrev_b32_e32 v68, 16, v29
	v_and_b32_e32 v67, 0xffff0000, v29
	v_max3_f32 v41, v41, v42, v43
	v_max_f32_e64 v26, |v72|, |v72|
	v_max_f32_e64 v42, |v74|, |v74|
	v_lshlrev_b32_e32 v73, 16, v27
	v_and_b32_e32 v71, 0xffff0000, v27
	v_lshlrev_b32_e32 v70, 16, v28
	v_and_b32_e32 v69, 0xffff0000, v28
	v_max_f32_e64 v28, |v67|, |v67|
	v_max_f32_e64 v29, |v68|, |v68|
	v_max_f32_e32 v26, v42, v26
	v_max_f32_e64 v27, |v71|, |v71|
	v_max_f32_e64 v42, |v73|, |v73|
	v_max_f32_e32 v28, v29, v28
	v_max_f32_e32 v27, v42, v27
	v_max3_f32 v28, |v70|, |v69|, v28
	v_lshlrev_b32_e32 v66, 16, v22
	v_and_b32_e32 v64, 0xffff0000, v22
	v_lshlrev_b32_e32 v60, 16, v25
	v_and_b32_e32 v59, 0xffff0000, v25
	v_max3_f32 v26, v26, v27, v28
	v_max_f32_e64 v22, |v64|, |v64|
	v_max_f32_e64 v27, |v66|, |v66|
	v_lshlrev_b32_e32 v65, 16, v23
	v_and_b32_e32 v63, 0xffff0000, v23
	v_lshlrev_b32_e32 v62, 16, v24
	v_and_b32_e32 v61, 0xffff0000, v24
	v_max_f32_e64 v24, |v59|, |v59|
	v_max_f32_e64 v25, |v60|, |v60|
	v_max_f32_e32 v22, v27, v22
	v_max_f32_e64 v23, |v63|, |v63|
	v_max_f32_e64 v27, |v65|, |v65|
	v_max_f32_e32 v24, v25, v24
	v_max_f32_e32 v23, v27, v23
	v_max3_f32 v24, |v62|, |v61|, v24
	v_lshlrev_b32_e32 v58, 16, v18
	v_and_b32_e32 v56, 0xffff0000, v18
	v_lshlrev_b32_e32 v52, 16, v21
	v_and_b32_e32 v51, 0xffff0000, v21
	v_max3_f32 v22, v22, v23, v24
	v_max_f32_e64 v18, |v56|, |v56|
	v_max_f32_e64 v23, |v58|, |v58|
	v_lshlrev_b32_e32 v57, 16, v19
	v_and_b32_e32 v55, 0xffff0000, v19
	v_lshlrev_b32_e32 v54, 16, v20
	v_and_b32_e32 v53, 0xffff0000, v20
	v_max_f32_e64 v20, |v51|, |v51|
	v_max_f32_e64 v21, |v52|, |v52|
	v_max_f32_e32 v18, v23, v18
	v_max_f32_e64 v19, |v55|, |v55|
	v_max_f32_e64 v23, |v57|, |v57|
	v_max_f32_e32 v20, v21, v20
	v_max_f32_e32 v19, v23, v19
	v_max3_f32 v20, |v54|, |v53|, v20
	s_waitcnt vmcnt(3)
	v_lshlrev_b32_e32 v50, 16, v14
	v_and_b32_e32 v48, 0xffff0000, v14
	v_lshlrev_b32_e32 v44, 16, v17
	v_and_b32_e32 v43, 0xffff0000, v17
	v_max3_f32 v18, v18, v19, v20
	v_max_f32_e64 v14, |v48|, |v48|
	v_max_f32_e64 v19, |v50|, |v50|
	v_lshlrev_b32_e32 v49, 16, v15
	v_and_b32_e32 v47, 0xffff0000, v15
	v_lshlrev_b32_e32 v46, 16, v16
	v_and_b32_e32 v45, 0xffff0000, v16
	v_max_f32_e64 v16, |v43|, |v43|
	v_max_f32_e64 v17, |v44|, |v44|
	v_max_f32_e32 v14, v19, v14
	v_max_f32_e64 v15, |v47|, |v47|
	v_max_f32_e64 v19, |v49|, |v49|
	v_max_f32_e32 v16, v17, v16
	v_max3_f32 v26, v41, 0, v26
	v_max_f32_e32 v15, v19, v15
	v_max3_f32 v16, |v46|, |v45|, v16
	s_waitcnt vmcnt(2)
	v_lshlrev_b32_e32 v42, 16, v10
	v_and_b32_e32 v29, 0xffff0000, v10
	v_lshlrev_b32_e32 v25, 16, v13
	v_and_b32_e32 v24, 0xffff0000, v13
	v_max3_f32 v18, v26, v22, v18
	v_max3_f32 v14, v14, v15, v16
	v_max_f32_e64 v10, |v29|, |v29|
	v_max_f32_e64 v15, |v42|, |v42|
	v_lshlrev_b32_e32 v41, 16, v11
	v_and_b32_e32 v28, 0xffff0000, v11
	v_lshlrev_b32_e32 v27, 16, v12
	v_and_b32_e32 v26, 0xffff0000, v12
	v_max_f32_e64 v12, |v24|, |v24|
	v_max_f32_e64 v13, |v25|, |v25|
	v_max_f32_e32 v10, v15, v10
	v_max_f32_e64 v11, |v28|, |v28|
	v_max_f32_e64 v15, |v41|, |v41|
	v_max_f32_e32 v12, v13, v12
	v_max_f32_e32 v11, v15, v11
	v_max3_f32 v12, |v27|, |v26|, v12
	v_max3_f32 v10, v10, v11, v12
	s_waitcnt vmcnt(1)
	v_lshlrev_b32_e32 v23, 16, v6
	v_and_b32_e32 v21, 0xffff0000, v6
	v_lshlrev_b32_e32 v17, 16, v9
	v_and_b32_e32 v16, 0xffff0000, v9
	v_max3_f32 v158, v18, v14, v10
	v_max_f32_e64 v6, |v21|, |v21|
	v_max_f32_e64 v10, |v23|, |v23|
	v_lshlrev_b32_e32 v22, 16, v7
	v_and_b32_e32 v20, 0xffff0000, v7
	v_lshlrev_b32_e32 v19, 16, v8
	v_and_b32_e32 v18, 0xffff0000, v8
	v_max_f32_e64 v8, |v16|, |v16|
	v_max_f32_e64 v9, |v17|, |v17|
	v_max_f32_e32 v6, v10, v6
	v_max_f32_e64 v7, |v20|, |v20|
	v_max_f32_e64 v10, |v22|, |v22|
	v_max_f32_e32 v8, v9, v8
	v_max_f32_e32 v7, v10, v7
	v_max3_f32 v8, |v19|, |v18|, v8
	v_max3_f32 v6, v6, v7, v8
	s_waitcnt vmcnt(0)
	v_lshlrev_b32_e32 v15, 16, v2
	v_and_b32_e32 v13, 0xffff0000, v2
	v_lshlrev_b32_e32 v9, 16, v5
	v_and_b32_e32 v8, 0xffff0000, v5
	v_max_f32_e64 v2, |v13|, |v13|
	v_max_f32_e64 v7, |v15|, |v15|
	v_lshlrev_b32_e32 v14, 16, v3
	v_and_b32_e32 v12, 0xffff0000, v3
	v_lshlrev_b32_e32 v11, 16, v4
	v_and_b32_e32 v10, 0xffff0000, v4
	v_max_f32_e64 v4, |v8|, |v8|
	v_max_f32_e64 v5, |v9|, |v9|
	v_max_f32_e32 v2, v7, v2
	v_max_f32_e64 v3, |v12|, |v12|
	v_max_f32_e64 v7, |v14|, |v14|
	v_max_f32_e32 v4, v5, v4
	v_max_f32_e32 v3, v7, v3
	v_max3_f32 v4, |v11|, |v10|, v4
	v_max3_f32 v2, v2, v3, v4
	v_max3_f32 v2, v158, v6, v2
	s_nop 1
	v_mov_b32_dpp v157, v156 quad_perm:[1,0,3,2] row_mask:0xf bank_mask:0xf
	s_nop 1
	v_mov_b32_dpp v3, v2 quad_perm:[1,0,3,2] row_mask:0xf bank_mask:0xf
	s_waitcnt lgkmcnt(0)
; __device__ __forceinline__ float bflo(unsigned w) { return __uint_as_float(w << 16); }
; __device__ __forceinline__ float bfhi(unsigned w) { return __uint_as_float(w & 0xffff0000u); }
; #pragma unroll
;     for (int j = 0; j < 8; ++j) mx = fmaxf(mx, fmaxf(fmaxf(fmaxf(fabsf(bflo(w[j].x)), fabsf(bfhi(w[j].x))), fmaxf(fabsf(bflo(w[j].y)), fabsf(bfhi(w[j].y)))), fmaxf(fmaxf(fabsf(bflo(w[j].z)), fabsf(bfhi(w[j].z))), fmaxf(fabsf(bflo(w[j].w)), fabsf(bfhi(w[j].w))))));
; #pragma unroll
;     for (int o = 1; o < 64; o <<= 1) mx = fmaxf(mx, __shfl_xor(mx, o));
;     return mx; }
; __device__ __forceinline__ void quant_store8(const u32x4 (&w)[8], float inv, signed char* dst, int lane) { u32x2* qp = (u32x2*)dst + lane;
; #pragma unroll
;     for (int j = 0; j < 8; ++j) { const unsigned ww[4] = {w[j].x, w[j].y, w[j].z, w[j].w}; unsigned o2[2];
; #pragma unroll
;         for (int h2 = 0; h2 < 2; ++h2) { const int q0 = (int)rintf(bflo(ww[2 * h2]) * inv), q1 = (int)rintf(bfhi(ww[2 * h2]) * inv), q2 = (int)rintf(bflo(ww[2 * h2 + 1]) * inv), q3 = (int)rintf(bfhi(ww[2 * h2 + 1]) * inv);
;             o2[h2] = (unsigned)(q0 & 255) | ((unsigned)(q1 & 255) << 8) | ((unsigned)(q2 & 255) << 16) | ((unsigned)(q3 & 255) << 24); }
;         u32x2 o; o.x = o2[0]; o.y = o2[1]; qp[64 * j] = o; } }
; __device__ __forceinline__ void quant_rows2(const bf16_t* s0, const bf16_t* s1, signed char* d0, signed char* d1, int lane, float& step0, float& step1) {
;     const u32x4* p0 = (const u32x4*)s0 + lane; const u32x4* p1 = (const u32x4*)s1 + lane; u32x4 w0[8], w1[8];
; #pragma unroll
;     for (int j = 0; j < 8; ++j) { w0[j] = p0[64 * j]; w1[j] = p1[64 * j]; }
;     step0 = fmaxf(absmax8(w0), 1e-30f) * (1.0f / 127.0f); step1 = fmaxf(absmax8(w1), 1e-30f) * (1.0f / 127.0f);
;     quant_store8(w0, 1.0f / step0, d0, lane); quant_store8(w1, 1.0f / step1, d1, lane);
	v_max_f32_e32 v4, v157, v157
	s_waitcnt lgkmcnt(0)
	v_max_f32_e32 v3, v3, v3
	v_max_f32_e32 v4, v156, v4
	v_max_f32_e32 v2, v2, v3
	s_nop 1
	v_mov_b32_dpp v5, v4 quad_perm:[2,3,0,1] row_mask:0xf bank_mask:0xf
	s_nop 1
	v_mov_b32_dpp v3, v2 quad_perm:[2,3,0,1] row_mask:0xf bank_mask:0xf
	s_waitcnt lgkmcnt(0)
	v_max_f32_e32 v5, v5, v5
	s_waitcnt lgkmcnt(0)
	v_max_f32_e32 v3, v3, v3
	v_max_f32_e32 v4, v4, v5
	v_max_f32_e32 v2, v2, v3
	s_nop 1
	v_mov_b32_dpp v5, v4 row_half_mirror row_mask:0xf bank_mask:0xf
	s_nop 1
	v_mov_b32_dpp v3, v2 row_half_mirror row_mask:0xf bank_mask:0xf
	s_waitcnt lgkmcnt(0)
	v_max_f32_e32 v5, v5, v5
	s_waitcnt lgkmcnt(0)
	v_max_f32_e32 v3, v3, v3
	v_max_f32_e32 v4, v4, v5
	v_max_f32_e32 v2, v2, v3
	s_nop 1
	v_mov_b32_dpp v5, v4 row_mirror row_mask:0xf bank_mask:0xf
	s_nop 1
	v_mov_b32_dpp v3, v2 row_mirror row_mask:0xf bank_mask:0xf
	s_waitcnt lgkmcnt(0)
	v_max_f32_e32 v5, v5, v5
	s_waitcnt lgkmcnt(0)
	v_max_f32_e32 v3, v3, v3
	v_max_f32_e32 v4, v4, v5
	v_max_f32_e32 v2, v2, v3
	s_waitcnt lgkmcnt(0)
	s_waitcnt lgkmcnt(0)
	v_mov_b32_e32 v5, v4
	s_nop 1
	v_permlane16_swap_b32_e32 v4, v5
	s_nop 0
	v_max_f32_e32 v4, v4, v5
	v_mov_b32_e32 v3, v2
	s_nop 1
	v_permlane16_swap_b32_e32 v3, v2
	s_nop 0
	v_max_f32_e32 v3, v3, v2
	ds_bpermute_b32 v5, v39, v4
	ds_bpermute_b32 v6, v39, v3
	s_waitcnt lgkmcnt(1)
	v_max3_f32 v2, v4, v5, s23
	s_waitcnt lgkmcnt(0)
	v_max3_f32 v3, v3, v6, s23
	v_pk_mul_f32 v[2:3], v[2:3], s[6:7] op_sel_hi:[1,0]
	s_nop 0
	v_div_scale_f32 v4, s[10:11], v2, v2, 1.0
	v_rcp_f32_e32 v5, v4
	s_nop 0
	v_fma_f32 v6, -v4, v5, 1.0
	v_fmac_f32_e32 v5, v6, v5
	v_div_scale_f32 v6, vcc, 1.0, v2, 1.0
	v_mul_f32_e32 v7, v6, v5
	v_fma_f32 v156, -v4, v7, v6
	v_fmac_f32_e32 v7, v156, v5
	v_fma_f32 v4, -v4, v7, v6
	v_div_fmas_f32 v4, v4, v5, v7
	v_div_fixup_f32 v156, v4, v2, 1.0
	v_mul_f32_e32 v7, v156, v84
	v_mul_f32_e32 v6, v156, v83
	v_rndne_f32_e32 v7, v7
	v_mul_f32_e32 v83, v156, v85
	v_rndne_f32_e32 v6, v6
	v_cvt_i32_f32_e32 v7, v7
	v_rndne_f32_e32 v83, v83
	v_mul_f32_e32 v84, v156, v86
	v_cvt_i32_f32_e32 v6, v6
	v_cvt_i32_f32_sdwa v83, v83 dst_sel:WORD_1 dst_unused:UNUSED_PAD src0_sel:DWORD
	v_rndne_f32_e32 v84, v84
	v_cvt_i32_f32_sdwa v84, v84 dst_sel:BYTE_3 dst_unused:UNUSED_PAD src0_sel:DWORD
	v_lshlrev_b32_e32 v7, 8, v7
	v_and_b32_e32 v83, 0xff0000, v83
	v_perm_b32 v6, v7, v6, s26
	v_mul_f32_e32 v7, v156, v88
	v_or3_b32 v84, v6, v84, v83
	v_mul_f32_e32 v6, v156, v87
	v_rndne_f32_e32 v7, v7
	v_mul_f32_e32 v83, v156, v89
	v_rndne_f32_e32 v6, v6
	v_cvt_i32_f32_e32 v7, v7
	v_rndne_f32_e32 v83, v83
	v_mul_f32_e32 v85, v156, v90
	v_cvt_i32_f32_e32 v6, v6
	v_cvt_i32_f32_sdwa v83, v83 dst_sel:WORD_1 dst_unused:UNUSED_PAD src0_sel:DWORD
	v_rndne_f32_e32 v85, v85
	v_cvt_i32_f32_sdwa v85, v85 dst_sel:BYTE_3 dst_unused:UNUSED_PAD src0_sel:DWORD
	v_lshlrev_b32_e32 v7, 8, v7
	v_lshl_add_u64 v[4:5], v[32:33], 0, s[0:1]
	v_and_b32_e32 v83, 0xff0000, v83
	v_perm_b32 v6, v7, v6, s26
	v_or3_b32 v85, v6, v85, v83
	v_add_co_u32_e32 v6, vcc, s27, v4
	v_mul_f32_e32 v83, v156, v91
	s_nop 0
	v_addc_co_u32_e32 v7, vcc, 0, v5, vcc
	v_add_co_u32_e32 v4, vcc, s28, v4
	v_rndne_f32_e32 v83, v83
	s_nop 0
	v_addc_co_u32_e32 v5, vcc, 0, v5, vcc
	global_store_dwordx2 v[4:5], v[84:85], off offset:-4096
	v_mul_f32_e32 v84, v156, v92
	v_rndne_f32_e32 v84, v84
	v_mul_f32_e32 v85, v156, v93
	v_cvt_i32_f32_e32 v84, v84
	v_rndne_f32_e32 v85, v85
	v_mul_f32_e32 v86, v156, v94
	v_cvt_i32_f32_e32 v83, v83
	v_cvt_i32_f32_sdwa v85, v85 dst_sel:WORD_1 dst_unused:UNUSED_PAD src0_sel:DWORD
	v_rndne_f32_e32 v86, v86
	v_cvt_i32_f32_sdwa v86, v86 dst_sel:BYTE_3 dst_unused:UNUSED_PAD src0_sel:DWORD
	v_lshlrev_b32_e32 v84, 8, v84
	v_and_b32_e32 v85, 0xff0000, v85
	v_perm_b32 v83, v84, v83, s26
	v_or3_b32 v84, v83, v86, v85
	v_mul_f32_e32 v85, v156, v96
	v_mul_f32_e32 v83, v156, v95
	v_rndne_f32_e32 v85, v85
	v_mul_f32_e32 v86, v156, v97
	v_rndne_f32_e32 v83, v83
	v_cvt_i32_f32_e32 v85, v85
	v_rndne_f32_e32 v86, v86
	v_mul_f32_e32 v87, v156, v98
	v_cvt_i32_f32_e32 v83, v83
	v_cvt_i32_f32_sdwa v86, v86 dst_sel:WORD_1 dst_unused:UNUSED_PAD src0_sel:DWORD
	v_rndne_f32_e32 v87, v87
	v_cvt_i32_f32_sdwa v87, v87 dst_sel:BYTE_3 dst_unused:UNUSED_PAD src0_sel:DWORD
	v_lshlrev_b32_e32 v85, 8, v85
	v_and_b32_e32 v86, 0xff0000, v86
	v_perm_b32 v83, v85, v83, s26
	v_or3_b32 v85, v83, v87, v86
	global_store_dwordx2 v[6:7], v[84:85], off offset:512
	v_mul_f32_e32 v84, v156, v100
	v_mul_f32_e32 v83, v156, v99
	v_rndne_f32_e32 v84, v84
	v_mul_f32_e32 v85, v156, v101
	v_rndne_f32_e32 v83, v83
	v_cvt_i32_f32_e32 v84, v84
	v_rndne_f32_e32 v85, v85
	v_mul_f32_e32 v86, v156, v102
	v_cvt_i32_f32_e32 v83, v83
	v_cvt_i32_f32_sdwa v85, v85 dst_sel:WORD_1 dst_unused:UNUSED_PAD src0_sel:DWORD
	v_rndne_f32_e32 v86, v86
	v_cvt_i32_f32_sdwa v86, v86 dst_sel:BYTE_3 dst_unused:UNUSED_PAD src0_sel:DWORD
	v_lshlrev_b32_e32 v84, 8, v84
	v_and_b32_e32 v85, 0xff0000, v85
	v_perm_b32 v83, v84, v83, s26
	v_or3_b32 v84, v83, v86, v85
	v_mul_f32_e32 v85, v156, v104
	v_mul_f32_e32 v83, v156, v103
	v_rndne_f32_e32 v85, v85
	v_mul_f32_e32 v86, v156, v105
	v_rndne_f32_e32 v83, v83
	v_cvt_i32_f32_e32 v85, v85
	v_rndne_f32_e32 v86, v86
	v_mul_f32_e32 v87, v156, v106
	v_cvt_i32_f32_e32 v83, v83
	v_cvt_i32_f32_sdwa v86, v86 dst_sel:WORD_1 dst_unused:UNUSED_PAD src0_sel:DWORD
	v_rndne_f32_e32 v87, v87
	v_cvt_i32_f32_sdwa v87, v87 dst_sel:BYTE_3 dst_unused:UNUSED_PAD src0_sel:DWORD
	v_lshlrev_b32_e32 v85, 8, v85
	v_and_b32_e32 v86, 0xff0000, v86
	v_perm_b32 v83, v85, v83, s26
	v_or3_b32 v85, v83, v87, v86
	global_store_dwordx2 v[6:7], v[84:85], off offset:1024
	v_mul_f32_e32 v84, v156, v108
	v_mul_f32_e32 v83, v156, v107
; __device__ __forceinline__ float bflo(unsigned w) { return __uint_as_float(w << 16); }
; __device__ __forceinline__ float bfhi(unsigned w) { return __uint_as_float(w & 0xffff0000u); }
; __device__ __forceinline__ void quant_store8(const u32x4 (&w)[8], float inv, signed char* dst, int lane) { u32x2* qp = (u32x2*)dst + lane;
; #pragma unroll
;     for (int j = 0; j < 8; ++j) { const unsigned ww[4] = {w[j].x, w[j].y, w[j].z, w[j].w}; unsigned o2[2];
; #pragma unroll
;         for (int h2 = 0; h2 < 2; ++h2) { const int q0 = (int)rintf(bflo(ww[2 * h2]) * inv), q1 = (int)rintf(bfhi(ww[2 * h2]) * inv), q2 = (int)rintf(bflo(ww[2 * h2 + 1]) * inv), q3 = (int)rintf(bfhi(ww[2 * h2 + 1]) * inv);
;             o2[h2] = (unsigned)(q0 & 255) | ((unsigned)(q1 & 255) << 8) | ((unsigned)(q2 & 255) << 16) | ((unsigned)(q3 & 255) << 24); }
;         u32x2 o; o.x = o2[0]; o.y = o2[1]; qp[64 * j] = o; } }
	v_rndne_f32_e32 v84, v84
	v_mul_f32_e32 v85, v156, v109
	v_rndne_f32_e32 v83, v83
	v_cvt_i32_f32_e32 v84, v84
	v_rndne_f32_e32 v85, v85
	v_mul_f32_e32 v86, v156, v110
	v_cvt_i32_f32_e32 v83, v83
	v_cvt_i32_f32_sdwa v85, v85 dst_sel:WORD_1 dst_unused:UNUSED_PAD src0_sel:DWORD
	v_rndne_f32_e32 v86, v86
	v_cvt_i32_f32_sdwa v86, v86 dst_sel:BYTE_3 dst_unused:UNUSED_PAD src0_sel:DWORD
	v_lshlrev_b32_e32 v84, 8, v84
	v_and_b32_e32 v85, 0xff0000, v85
	v_perm_b32 v83, v84, v83, s26
	v_or3_b32 v84, v83, v86, v85
	v_mul_f32_e32 v85, v156, v112
	v_mul_f32_e32 v83, v156, v111
	v_rndne_f32_e32 v85, v85
	v_mul_f32_e32 v86, v156, v113
	v_rndne_f32_e32 v83, v83
	v_cvt_i32_f32_e32 v85, v85
	v_rndne_f32_e32 v86, v86
	v_mul_f32_e32 v87, v156, v114
	v_cvt_i32_f32_e32 v83, v83
	v_cvt_i32_f32_sdwa v86, v86 dst_sel:WORD_1 dst_unused:UNUSED_PAD src0_sel:DWORD
	v_rndne_f32_e32 v87, v87
	v_cvt_i32_f32_sdwa v87, v87 dst_sel:BYTE_3 dst_unused:UNUSED_PAD src0_sel:DWORD
	v_lshlrev_b32_e32 v85, 8, v85
	v_and_b32_e32 v86, 0xff0000, v86
	v_perm_b32 v83, v85, v83, s26
	v_or3_b32 v85, v83, v87, v86
	global_store_dwordx2 v[6:7], v[84:85], off offset:1536
	v_mul_f32_e32 v84, v156, v116
	v_mul_f32_e32 v83, v156, v115
	v_rndne_f32_e32 v84, v84
	v_mul_f32_e32 v85, v156, v117
	v_rndne_f32_e32 v83, v83
	v_cvt_i32_f32_e32 v84, v84
	v_rndne_f32_e32 v85, v85
	v_mul_f32_e32 v86, v156, v118
	v_cvt_i32_f32_e32 v83, v83
	v_cvt_i32_f32_sdwa v85, v85 dst_sel:WORD_1 dst_unused:UNUSED_PAD src0_sel:DWORD
	v_rndne_f32_e32 v86, v86
	v_cvt_i32_f32_sdwa v86, v86 dst_sel:BYTE_3 dst_unused:UNUSED_PAD src0_sel:DWORD
	v_lshlrev_b32_e32 v84, 8, v84
	v_and_b32_e32 v85, 0xff0000, v85
	v_perm_b32 v83, v84, v83, s26
	v_or3_b32 v84, v83, v86, v85
	v_mul_f32_e32 v85, v156, v120
	v_mul_f32_e32 v83, v156, v119
	v_rndne_f32_e32 v85, v85
	v_mul_f32_e32 v86, v156, v121
	v_rndne_f32_e32 v83, v83
	v_cvt_i32_f32_e32 v85, v85
	v_rndne_f32_e32 v86, v86
	v_mul_f32_e32 v87, v156, v122
	v_cvt_i32_f32_e32 v83, v83
	v_cvt_i32_f32_sdwa v86, v86 dst_sel:WORD_1 dst_unused:UNUSED_PAD src0_sel:DWORD
	v_rndne_f32_e32 v87, v87
	v_cvt_i32_f32_sdwa v87, v87 dst_sel:BYTE_3 dst_unused:UNUSED_PAD src0_sel:DWORD
	v_lshlrev_b32_e32 v85, 8, v85
	v_and_b32_e32 v86, 0xff0000, v86
	v_perm_b32 v83, v85, v83, s26
	v_or3_b32 v85, v83, v87, v86
	global_store_dwordx2 v[6:7], v[84:85], off offset:2048
	v_mul_f32_e32 v84, v156, v124
	v_mul_f32_e32 v83, v156, v123
	v_rndne_f32_e32 v84, v84
	v_mul_f32_e32 v85, v156, v125
	v_rndne_f32_e32 v83, v83
	v_cvt_i32_f32_e32 v84, v84
	v_rndne_f32_e32 v85, v85
	v_mul_f32_e32 v86, v156, v126
	v_cvt_i32_f32_e32 v83, v83
	v_cvt_i32_f32_sdwa v85, v85 dst_sel:WORD_1 dst_unused:UNUSED_PAD src0_sel:DWORD
	v_rndne_f32_e32 v86, v86
	v_cvt_i32_f32_sdwa v86, v86 dst_sel:BYTE_3 dst_unused:UNUSED_PAD src0_sel:DWORD
	v_lshlrev_b32_e32 v84, 8, v84
	v_and_b32_e32 v85, 0xff0000, v85
	v_perm_b32 v83, v84, v83, s26
	v_or3_b32 v84, v83, v86, v85
	v_mul_f32_e32 v85, v156, v128
	v_mul_f32_e32 v83, v156, v127
	v_rndne_f32_e32 v85, v85
	v_mul_f32_e32 v86, v156, v129
	v_rndne_f32_e32 v83, v83
	v_cvt_i32_f32_e32 v85, v85
	v_rndne_f32_e32 v86, v86
	v_mul_f32_e32 v87, v156, v130
	v_cvt_i32_f32_e32 v83, v83
	v_cvt_i32_f32_sdwa v86, v86 dst_sel:WORD_1 dst_unused:UNUSED_PAD src0_sel:DWORD
	v_rndne_f32_e32 v87, v87
	v_cvt_i32_f32_sdwa v87, v87 dst_sel:BYTE_3 dst_unused:UNUSED_PAD src0_sel:DWORD
	v_lshlrev_b32_e32 v85, 8, v85
	v_and_b32_e32 v86, 0xff0000, v86
	v_perm_b32 v83, v85, v83, s26
	v_or3_b32 v85, v83, v87, v86
	global_store_dwordx2 v[6:7], v[84:85], off offset:2560
	v_mul_f32_e32 v84, v156, v132
	v_mul_f32_e32 v83, v156, v131
	v_rndne_f32_e32 v84, v84
	v_mul_f32_e32 v85, v156, v133
	v_rndne_f32_e32 v83, v83
	v_cvt_i32_f32_e32 v84, v84
	v_rndne_f32_e32 v85, v85
	v_mul_f32_e32 v86, v156, v137
	v_cvt_i32_f32_e32 v83, v83
	v_cvt_i32_f32_sdwa v85, v85 dst_sel:WORD_1 dst_unused:UNUSED_PAD src0_sel:DWORD
	v_rndne_f32_e32 v86, v86
	v_cvt_i32_f32_sdwa v86, v86 dst_sel:BYTE_3 dst_unused:UNUSED_PAD src0_sel:DWORD
	v_lshlrev_b32_e32 v84, 8, v84
	v_and_b32_e32 v85, 0xff0000, v85
	v_perm_b32 v83, v84, v83, s26
	v_or3_b32 v84, v83, v86, v85
	v_mul_f32_e32 v85, v156, v139
	v_mul_f32_e32 v83, v156, v138
	v_rndne_f32_e32 v85, v85
	v_mul_f32_e32 v86, v156, v140
	v_rndne_f32_e32 v83, v83
	v_cvt_i32_f32_e32 v85, v85
	v_rndne_f32_e32 v86, v86
	v_mul_f32_e32 v87, v156, v141
	v_cvt_i32_f32_e32 v83, v83
	v_cvt_i32_f32_sdwa v86, v86 dst_sel:WORD_1 dst_unused:UNUSED_PAD src0_sel:DWORD
	v_rndne_f32_e32 v87, v87
	v_cvt_i32_f32_sdwa v87, v87 dst_sel:BYTE_3 dst_unused:UNUSED_PAD src0_sel:DWORD
	v_lshlrev_b32_e32 v85, 8, v85
	v_and_b32_e32 v86, 0xff0000, v86
	v_perm_b32 v83, v85, v83, s26
	v_or3_b32 v85, v83, v87, v86
	global_store_dwordx2 v[6:7], v[84:85], off offset:3072
	v_mul_f32_e32 v84, v156, v143
	v_mul_f32_e32 v83, v156, v142
	v_rndne_f32_e32 v84, v84
	v_mul_f32_e32 v85, v156, v144
	v_rndne_f32_e32 v83, v83
	v_cvt_i32_f32_e32 v84, v84
	v_rndne_f32_e32 v85, v85
	v_mul_f32_e32 v86, v156, v145
	v_cvt_i32_f32_e32 v83, v83
	v_cvt_i32_f32_sdwa v85, v85 dst_sel:WORD_1 dst_unused:UNUSED_PAD src0_sel:DWORD
	v_rndne_f32_e32 v86, v86
	v_cvt_i32_f32_sdwa v86, v86 dst_sel:BYTE_3 dst_unused:UNUSED_PAD src0_sel:DWORD
	v_lshlrev_b32_e32 v84, 8, v84
	v_and_b32_e32 v85, 0xff0000, v85
	v_perm_b32 v83, v84, v83, s26
	v_or3_b32 v84, v83, v86, v85
	v_mul_f32_e32 v85, v156, v147
	v_mul_f32_e32 v83, v156, v146
	v_rndne_f32_e32 v85, v85
	v_mul_f32_e32 v86, v156, v148
	v_rndne_f32_e32 v83, v83
	v_cvt_i32_f32_e32 v85, v85
	v_rndne_f32_e32 v86, v86
	v_mul_f32_e32 v87, v156, v149
	v_cvt_i32_f32_e32 v83, v83
	v_cvt_i32_f32_sdwa v86, v86 dst_sel:WORD_1 dst_unused:UNUSED_PAD src0_sel:DWORD
; __device__ __forceinline__ float bflo(unsigned w) { return __uint_as_float(w << 16); }
; __device__ __forceinline__ float bfhi(unsigned w) { return __uint_as_float(w & 0xffff0000u); }
; __device__ __forceinline__ void quant_store8(const u32x4 (&w)[8], float inv, signed char* dst, int lane) { u32x2* qp = (u32x2*)dst + lane;
; #pragma unroll
;     for (int j = 0; j < 8; ++j) { const unsigned ww[4] = {w[j].x, w[j].y, w[j].z, w[j].w}; unsigned o2[2];
; #pragma unroll
;         for (int h2 = 0; h2 < 2; ++h2) { const int q0 = (int)rintf(bflo(ww[2 * h2]) * inv), q1 = (int)rintf(bfhi(ww[2 * h2]) * inv), q2 = (int)rintf(bflo(ww[2 * h2 + 1]) * inv), q3 = (int)rintf(bfhi(ww[2 * h2 + 1]) * inv);
;             o2[h2] = (unsigned)(q0 & 255) | ((unsigned)(q1 & 255) << 8) | ((unsigned)(q2 & 255) << 16) | ((unsigned)(q3 & 255) << 24); }
;         u32x2 o; o.x = o2[0]; o.y = o2[1]; qp[64 * j] = o; } }
; __device__ __forceinline__ void quant_rows2(const bf16_t* s0, const bf16_t* s1, signed char* d0, signed char* d1, int lane, float& step0, float& step1) {
;     const u32x4* p0 = (const u32x4*)s0 + lane; const u32x4* p1 = (const u32x4*)s1 + lane; u32x4 w0[8], w1[8];
; #pragma unroll
;     for (int j = 0; j < 8; ++j) { w0[j] = p0[64 * j]; w1[j] = p1[64 * j]; }
;     step0 = fmaxf(absmax8(w0), 1e-30f) * (1.0f / 127.0f); step1 = fmaxf(absmax8(w1), 1e-30f) * (1.0f / 127.0f);
;     quant_store8(w0, 1.0f / step0, d0, lane); quant_store8(w1, 1.0f / step1, d1, lane);
	v_rndne_f32_e32 v87, v87
	v_cvt_i32_f32_sdwa v87, v87 dst_sel:BYTE_3 dst_unused:UNUSED_PAD src0_sel:DWORD
	v_div_scale_f32 v88, s[10:11], v3, v3, 1.0
	v_rcp_f32_e32 v89, v88
	v_lshlrev_b32_e32 v85, 8, v85
	v_and_b32_e32 v86, 0xff0000, v86
	v_perm_b32 v83, v85, v83, s26
	v_or3_b32 v85, v83, v87, v86
	global_store_dwordx2 v[6:7], v[84:85], off offset:3584
	v_fma_f32 v6, -v88, v89, 1.0
	v_fmac_f32_e32 v89, v6, v89
	v_div_scale_f32 v6, vcc, 1.0, v3, 1.0
	v_mul_f32_e32 v7, v6, v89
	v_fma_f32 v83, -v88, v7, v6
	v_fmac_f32_e32 v7, v83, v89
	v_fma_f32 v6, -v88, v7, v6
	v_div_fmas_f32 v6, v6, v89, v7
	v_div_fixup_f32 v83, v6, v3, 1.0
	v_mul_f32_e32 v7, v83, v80
	v_mul_f32_e32 v6, v83, v82
	v_rndne_f32_e32 v7, v7
	v_rndne_f32_e32 v6, v6
	v_cvt_i32_f32_e32 v7, v7
	v_cvt_i32_f32_e32 v6, v6
	v_mul_f32_e32 v77, v83, v77
	v_mul_f32_e32 v80, v83, v81
	v_lshlrev_b32_e32 v7, 8, v7
	v_perm_b32 v6, v7, v6, s26
	v_mul_f32_e32 v7, v83, v78
	v_rndne_f32_e32 v77, v77
	v_mul_f32_e32 v76, v83, v76
	v_rndne_f32_e32 v80, v80
	v_mul_f32_e32 v79, v83, v79
	v_rndne_f32_e32 v7, v7
	v_cvt_i32_f32_e32 v77, v77
	v_rndne_f32_e32 v76, v76
	v_mul_f32_e32 v75, v83, v75
	v_cvt_i32_f32_sdwa v80, v80 dst_sel:WORD_1 dst_unused:UNUSED_PAD src0_sel:DWORD
	v_rndne_f32_e32 v79, v79
	v_cvt_i32_f32_e32 v7, v7
	v_cvt_i32_f32_sdwa v76, v76 dst_sel:WORD_1 dst_unused:UNUSED_PAD src0_sel:DWORD
	v_rndne_f32_e32 v75, v75
	v_cvt_i32_f32_sdwa v79, v79 dst_sel:BYTE_3 dst_unused:UNUSED_PAD src0_sel:DWORD
	v_cvt_i32_f32_sdwa v75, v75 dst_sel:BYTE_3 dst_unused:UNUSED_PAD src0_sel:DWORD
	v_lshlrev_b32_e32 v77, 8, v77
	v_and_b32_e32 v80, 0xff0000, v80
	v_and_b32_e32 v76, 0xff0000, v76
	v_perm_b32 v7, v77, v7, s26
	v_or3_b32 v6, v6, v79, v80
	v_or3_b32 v7, v7, v75, v76
	global_store_dwordx2 v[4:5], v[6:7], off
	v_mul_f32_e32 v7, v83, v72
	v_mul_f32_e32 v6, v83, v74
	v_rndne_f32_e32 v7, v7
	v_rndne_f32_e32 v6, v6
	v_cvt_i32_f32_e32 v7, v7
	v_cvt_i32_f32_e32 v6, v6
	v_mul_f32_e32 v69, v83, v69
	v_mul_f32_e32 v72, v83, v73
	v_lshlrev_b32_e32 v7, 8, v7
	v_perm_b32 v6, v7, v6, s26
	v_mul_f32_e32 v7, v83, v70
	v_rndne_f32_e32 v69, v69
	v_mul_f32_e32 v68, v83, v68
	v_rndne_f32_e32 v72, v72
	v_mul_f32_e32 v71, v83, v71
	v_rndne_f32_e32 v7, v7
	v_cvt_i32_f32_e32 v69, v69
	v_rndne_f32_e32 v68, v68
	v_mul_f32_e32 v67, v83, v67
	v_cvt_i32_f32_sdwa v72, v72 dst_sel:WORD_1 dst_unused:UNUSED_PAD src0_sel:DWORD
	v_rndne_f32_e32 v71, v71
	v_cvt_i32_f32_e32 v7, v7
	v_cvt_i32_f32_sdwa v68, v68 dst_sel:WORD_1 dst_unused:UNUSED_PAD src0_sel:DWORD
	v_rndne_f32_e32 v67, v67
	v_cvt_i32_f32_sdwa v71, v71 dst_sel:BYTE_3 dst_unused:UNUSED_PAD src0_sel:DWORD
	v_cvt_i32_f32_sdwa v67, v67 dst_sel:BYTE_3 dst_unused:UNUSED_PAD src0_sel:DWORD
	v_lshlrev_b32_e32 v69, 8, v69
	v_and_b32_e32 v72, 0xff0000, v72
	v_and_b32_e32 v68, 0xff0000, v68
	v_perm_b32 v7, v69, v7, s26
	v_or3_b32 v6, v6, v71, v72
	v_or3_b32 v7, v7, v67, v68
	global_store_dwordx2 v[4:5], v[6:7], off offset:512
	v_mul_f32_e32 v7, v83, v64
	v_mul_f32_e32 v6, v83, v66
	v_rndne_f32_e32 v7, v7
	v_rndne_f32_e32 v6, v6
	v_cvt_i32_f32_e32 v7, v7
	v_cvt_i32_f32_e32 v6, v6
	v_mul_f32_e32 v61, v83, v61
	v_mul_f32_e32 v64, v83, v65
	v_lshlrev_b32_e32 v7, 8, v7
	v_perm_b32 v6, v7, v6, s26
	v_mul_f32_e32 v7, v83, v62
	v_rndne_f32_e32 v61, v61
	v_mul_f32_e32 v60, v83, v60
	v_rndne_f32_e32 v64, v64
	v_mul_f32_e32 v63, v83, v63
	v_rndne_f32_e32 v7, v7
	v_cvt_i32_f32_e32 v61, v61
	v_rndne_f32_e32 v60, v60
	v_mul_f32_e32 v59, v83, v59
	v_cvt_i32_f32_sdwa v64, v64 dst_sel:WORD_1 dst_unused:UNUSED_PAD src0_sel:DWORD
	v_rndne_f32_e32 v63, v63
	v_cvt_i32_f32_e32 v7, v7
	v_cvt_i32_f32_sdwa v60, v60 dst_sel:WORD_1 dst_unused:UNUSED_PAD src0_sel:DWORD
	v_rndne_f32_e32 v59, v59
	v_cvt_i32_f32_sdwa v63, v63 dst_sel:BYTE_3 dst_unused:UNUSED_PAD src0_sel:DWORD
	v_cvt_i32_f32_sdwa v59, v59 dst_sel:BYTE_3 dst_unused:UNUSED_PAD src0_sel:DWORD
	v_lshlrev_b32_e32 v61, 8, v61
	v_and_b32_e32 v64, 0xff0000, v64
	v_and_b32_e32 v60, 0xff0000, v60
	v_perm_b32 v7, v61, v7, s26
	v_or3_b32 v6, v6, v63, v64
	v_or3_b32 v7, v7, v59, v60
	global_store_dwordx2 v[4:5], v[6:7], off offset:1024
	v_mul_f32_e32 v7, v83, v56
	v_mul_f32_e32 v6, v83, v58
	v_rndne_f32_e32 v7, v7
	v_rndne_f32_e32 v6, v6
	v_cvt_i32_f32_e32 v7, v7
	v_cvt_i32_f32_e32 v6, v6
	v_mul_f32_e32 v53, v83, v53
	v_mul_f32_e32 v56, v83, v57
	v_lshlrev_b32_e32 v7, 8, v7
	v_perm_b32 v6, v7, v6, s26
	v_mul_f32_e32 v7, v83, v54
	v_rndne_f32_e32 v53, v53
	v_mul_f32_e32 v52, v83, v52
	v_rndne_f32_e32 v56, v56
	v_mul_f32_e32 v55, v83, v55
	v_rndne_f32_e32 v7, v7
	v_cvt_i32_f32_e32 v53, v53
	v_rndne_f32_e32 v52, v52
	v_mul_f32_e32 v51, v83, v51
	v_cvt_i32_f32_sdwa v56, v56 dst_sel:WORD_1 dst_unused:UNUSED_PAD src0_sel:DWORD
	v_rndne_f32_e32 v55, v55
	v_cvt_i32_f32_e32 v7, v7
	v_cvt_i32_f32_sdwa v52, v52 dst_sel:WORD_1 dst_unused:UNUSED_PAD src0_sel:DWORD
	v_rndne_f32_e32 v51, v51
	v_cvt_i32_f32_sdwa v55, v55 dst_sel:BYTE_3 dst_unused:UNUSED_PAD src0_sel:DWORD
	v_cvt_i32_f32_sdwa v51, v51 dst_sel:BYTE_3 dst_unused:UNUSED_PAD src0_sel:DWORD
; __device__ __forceinline__ float bflo(unsigned w) { return __uint_as_float(w << 16); }
; __device__ __forceinline__ float bfhi(unsigned w) { return __uint_as_float(w & 0xffff0000u); }
; __device__ __forceinline__ void quant_store8(const u32x4 (&w)[8], float inv, signed char* dst, int lane) { u32x2* qp = (u32x2*)dst + lane;
; #pragma unroll
;     for (int j = 0; j < 8; ++j) { const unsigned ww[4] = {w[j].x, w[j].y, w[j].z, w[j].w}; unsigned o2[2];
; #pragma unroll
;         for (int h2 = 0; h2 < 2; ++h2) { const int q0 = (int)rintf(bflo(ww[2 * h2]) * inv), q1 = (int)rintf(bfhi(ww[2 * h2]) * inv), q2 = (int)rintf(bflo(ww[2 * h2 + 1]) * inv), q3 = (int)rintf(bfhi(ww[2 * h2 + 1]) * inv);
;             o2[h2] = (unsigned)(q0 & 255) | ((unsigned)(q1 & 255) << 8) | ((unsigned)(q2 & 255) << 16) | ((unsigned)(q3 & 255) << 24); }
;         u32x2 o; o.x = o2[0]; o.y = o2[1]; qp[64 * j] = o; } }
	v_lshlrev_b32_e32 v53, 8, v53
	v_and_b32_e32 v56, 0xff0000, v56
	v_and_b32_e32 v52, 0xff0000, v52
	v_perm_b32 v7, v53, v7, s26
	v_or3_b32 v6, v6, v55, v56
	v_or3_b32 v7, v7, v51, v52
	global_store_dwordx2 v[4:5], v[6:7], off offset:1536
	v_mul_f32_e32 v7, v83, v48
	v_mul_f32_e32 v6, v83, v50
	v_rndne_f32_e32 v7, v7
	v_rndne_f32_e32 v6, v6
	v_cvt_i32_f32_e32 v7, v7
	v_cvt_i32_f32_e32 v6, v6
	v_mul_f32_e32 v45, v83, v45
	v_mul_f32_e32 v48, v83, v49
	v_lshlrev_b32_e32 v7, 8, v7
	v_perm_b32 v6, v7, v6, s26
	v_mul_f32_e32 v7, v83, v46
	v_rndne_f32_e32 v45, v45
	v_mul_f32_e32 v44, v83, v44
	v_rndne_f32_e32 v48, v48
	v_mul_f32_e32 v47, v83, v47
	v_rndne_f32_e32 v7, v7
	v_cvt_i32_f32_e32 v45, v45
	v_rndne_f32_e32 v44, v44
	v_mul_f32_e32 v43, v83, v43
	v_cvt_i32_f32_sdwa v48, v48 dst_sel:WORD_1 dst_unused:UNUSED_PAD src0_sel:DWORD
	v_rndne_f32_e32 v47, v47
	v_cvt_i32_f32_e32 v7, v7
	v_cvt_i32_f32_sdwa v44, v44 dst_sel:WORD_1 dst_unused:UNUSED_PAD src0_sel:DWORD
	v_rndne_f32_e32 v43, v43
	v_cvt_i32_f32_sdwa v47, v47 dst_sel:BYTE_3 dst_unused:UNUSED_PAD src0_sel:DWORD
	v_cvt_i32_f32_sdwa v43, v43 dst_sel:BYTE_3 dst_unused:UNUSED_PAD src0_sel:DWORD
	v_lshlrev_b32_e32 v45, 8, v45
	v_and_b32_e32 v48, 0xff0000, v48
	v_and_b32_e32 v44, 0xff0000, v44
	v_perm_b32 v7, v45, v7, s26
	v_or3_b32 v6, v6, v47, v48
	v_or3_b32 v7, v7, v43, v44
	global_store_dwordx2 v[4:5], v[6:7], off offset:2048
	v_mul_f32_e32 v7, v83, v29
	v_mul_f32_e32 v6, v83, v42
	v_rndne_f32_e32 v7, v7
	v_rndne_f32_e32 v6, v6
	v_cvt_i32_f32_e32 v7, v7
	v_cvt_i32_f32_e32 v6, v6
	v_mul_f32_e32 v26, v83, v26
	v_mul_f32_e32 v29, v83, v41
	v_lshlrev_b32_e32 v7, 8, v7
	v_perm_b32 v6, v7, v6, s26
	v_mul_f32_e32 v7, v83, v27
	v_rndne_f32_e32 v26, v26
	v_mul_f32_e32 v25, v83, v25
	v_rndne_f32_e32 v29, v29
	v_mul_f32_e32 v28, v83, v28
	v_rndne_f32_e32 v7, v7
	v_cvt_i32_f32_e32 v26, v26
	v_rndne_f32_e32 v25, v25
	v_mul_f32_e32 v24, v83, v24
	v_cvt_i32_f32_sdwa v29, v29 dst_sel:WORD_1 dst_unused:UNUSED_PAD src0_sel:DWORD
	v_rndne_f32_e32 v28, v28
	v_cvt_i32_f32_e32 v7, v7
	v_cvt_i32_f32_sdwa v25, v25 dst_sel:WORD_1 dst_unused:UNUSED_PAD src0_sel:DWORD
	v_rndne_f32_e32 v24, v24
	v_cvt_i32_f32_sdwa v28, v28 dst_sel:BYTE_3 dst_unused:UNUSED_PAD src0_sel:DWORD
	v_cvt_i32_f32_sdwa v24, v24 dst_sel:BYTE_3 dst_unused:UNUSED_PAD src0_sel:DWORD
	v_lshlrev_b32_e32 v26, 8, v26
	v_and_b32_e32 v29, 0xff0000, v29
	v_and_b32_e32 v25, 0xff0000, v25
	v_perm_b32 v7, v26, v7, s26
	v_or3_b32 v6, v6, v28, v29
	v_or3_b32 v7, v7, v24, v25
	global_store_dwordx2 v[4:5], v[6:7], off offset:2560
	v_mul_f32_e32 v7, v83, v21
	v_mul_f32_e32 v6, v83, v23
	v_rndne_f32_e32 v7, v7
	v_rndne_f32_e32 v6, v6
	v_cvt_i32_f32_e32 v7, v7
	v_cvt_i32_f32_e32 v6, v6
	v_mul_f32_e32 v18, v83, v18
	v_mul_f32_e32 v21, v83, v22
	v_lshlrev_b32_e32 v7, 8, v7
	v_perm_b32 v6, v7, v6, s26
	v_mul_f32_e32 v7, v83, v19
	v_rndne_f32_e32 v18, v18
	v_mul_f32_e32 v17, v83, v17
	v_rndne_f32_e32 v21, v21
	v_mul_f32_e32 v20, v83, v20
	v_rndne_f32_e32 v7, v7
	v_cvt_i32_f32_e32 v18, v18
	v_rndne_f32_e32 v17, v17
	v_mul_f32_e32 v16, v83, v16
	v_cvt_i32_f32_sdwa v21, v21 dst_sel:WORD_1 dst_unused:UNUSED_PAD src0_sel:DWORD
	v_rndne_f32_e32 v20, v20
	v_cvt_i32_f32_e32 v7, v7
	v_cvt_i32_f32_sdwa v17, v17 dst_sel:WORD_1 dst_unused:UNUSED_PAD src0_sel:DWORD
	v_rndne_f32_e32 v16, v16
	v_cvt_i32_f32_sdwa v20, v20 dst_sel:BYTE_3 dst_unused:UNUSED_PAD src0_sel:DWORD
	v_cvt_i32_f32_sdwa v16, v16 dst_sel:BYTE_3 dst_unused:UNUSED_PAD src0_sel:DWORD
	v_lshlrev_b32_e32 v18, 8, v18
	v_and_b32_e32 v21, 0xff0000, v21
	v_and_b32_e32 v17, 0xff0000, v17
	v_perm_b32 v7, v18, v7, s26
	v_or3_b32 v6, v6, v20, v21
	v_or3_b32 v7, v7, v16, v17
	global_store_dwordx2 v[4:5], v[6:7], off offset:3072
	v_mul_f32_e32 v7, v83, v13
	v_mul_f32_e32 v6, v83, v15
	v_rndne_f32_e32 v7, v7
	v_rndne_f32_e32 v6, v6
	v_cvt_i32_f32_e32 v7, v7
	v_cvt_i32_f32_e32 v6, v6
	v_mul_f32_e32 v10, v83, v10
	v_mul_f32_e32 v13, v83, v14
	v_lshlrev_b32_e32 v7, 8, v7
	v_perm_b32 v6, v7, v6, s26
	v_mul_f32_e32 v7, v83, v11
	v_rndne_f32_e32 v10, v10
	v_mul_f32_e32 v9, v83, v9
	v_rndne_f32_e32 v13, v13
	v_mul_f32_e32 v12, v83, v12
	v_rndne_f32_e32 v7, v7
	v_cvt_i32_f32_e32 v10, v10
	v_rndne_f32_e32 v9, v9
	v_mul_f32_e32 v8, v83, v8
	v_cvt_i32_f32_sdwa v13, v13 dst_sel:WORD_1 dst_unused:UNUSED_PAD src0_sel:DWORD
	v_rndne_f32_e32 v12, v12
	v_cvt_i32_f32_e32 v7, v7
	v_cvt_i32_f32_sdwa v9, v9 dst_sel:WORD_1 dst_unused:UNUSED_PAD src0_sel:DWORD
	v_rndne_f32_e32 v8, v8
	v_cvt_i32_f32_sdwa v12, v12 dst_sel:BYTE_3 dst_unused:UNUSED_PAD src0_sel:DWORD
	v_cvt_i32_f32_sdwa v8, v8 dst_sel:BYTE_3 dst_unused:UNUSED_PAD src0_sel:DWORD
	v_lshlrev_b32_e32 v10, 8, v10
	v_and_b32_e32 v13, 0xff0000, v13
	v_and_b32_e32 v9, 0xff0000, v9
	v_perm_b32 v7, v10, v7, s26
	v_or3_b32 v6, v6, v12, v13
	v_or3_b32 v7, v7, v8, v9
	global_store_dwordx2 v[4:5], v[6:7], off offset:3584
	s_and_saveexec_b64 s[10:11], s[4:5]
	s_cbranch_execz .LBB0_159
	s_add_u32 s30, s78, s7
	s_addc_u32 s31, s79, s12
	global_store_dwordx2 v40, v[2:3], s[30:31]
	s_branch .LBB0_159

; __device__ __forceinline__ float bflo(unsigned w) { return __uint_as_float(w << 16); }
; __device__ __forceinline__ float bfhi(unsigned w) { return __uint_as_float(w & 0xffff0000u); }
; #pragma unroll
;     for (int j = 0; j < 8; ++j) mx = fmaxf(mx, fmaxf(fmaxf(fmaxf(fabsf(bflo(w[j].x)), fabsf(bfhi(w[j].x))), fmaxf(fabsf(bflo(w[j].y)), fabsf(bfhi(w[j].y)))), fmaxf(fmaxf(fabsf(bflo(w[j].z)), fabsf(bfhi(w[j].z))), fmaxf(fabsf(bflo(w[j].w)), fabsf(bfhi(w[j].w))))));
; #pragma unroll
;     for (int o = 1; o < 64; o <<= 1) mx = fmaxf(mx, __shfl_xor(mx, o));
;     return mx; }
; __device__ __forceinline__ void quant_store8(const u32x4 (&w)[8], float inv, signed char* dst, int lane) { u32x2* qp = (u32x2*)dst + lane;
; #pragma unroll
;     for (int j = 0; j < 8; ++j) { const unsigned ww[4] = {w[j].x, w[j].y, w[j].z, w[j].w}; unsigned o2[2];
; #pragma unroll
;         for (int h2 = 0; h2 < 2; ++h2) { const int q0 = (int)rintf(bflo(ww[2 * h2]) * inv), q1 = (int)rintf(bfhi(ww[2 * h2]) * inv), q2 = (int)rintf(bflo(ww[2 * h2 + 1]) * inv), q3 = (int)rintf(bfhi(ww[2 * h2 + 1]) * inv);
;             o2[h2] = (unsigned)(q0 & 255) | ((unsigned)(q1 & 255) << 8) | ((unsigned)(q2 & 255) << 16) | ((unsigned)(q3 & 255) << 24); }
;         u32x2 o; o.x = o2[0]; o.y = o2[1]; qp[64 * j] = o; } }
; __device__ __forceinline__ void quant_rows2(const bf16_t* s0, const bf16_t* s1, signed char* d0, signed char* d1, int lane, float& step0, float& step1) {
;     const u32x4* p0 = (const u32x4*)s0 + lane; const u32x4* p1 = (const u32x4*)s1 + lane; u32x4 w0[8], w1[8];
; #pragma unroll
;     for (int j = 0; j < 8; ++j) { w0[j] = p0[64 * j]; w1[j] = p1[64 * j]; }
;     step0 = fmaxf(absmax8(w0), 1e-30f) * (1.0f / 127.0f); step1 = fmaxf(absmax8(w1), 1e-30f) * (1.0f / 127.0f);
.LBB0_272:
	v_lshl_add_u64 v[2:3], s[78:79], 0, v[30:31]
	v_add_co_u32_e32 v4, vcc, 0x10800000, v2
	s_nop 1
	v_addc_co_u32_e32 v5, vcc, 0, v3, vcc
	global_load_dwordx4 v[42:45], v[4:5], off
	global_load_dwordx4 v[46:49], v[4:5], off offset:1024
	global_load_dwordx4 v[50:53], v[4:5], off offset:2048
	global_load_dwordx4 v[54:57], v[4:5], off offset:3072
	v_add_co_u32_e32 v6, vcc, 0x10802000, v2
	s_nop 1
	v_addc_co_u32_e32 v7, vcc, 0, v3, vcc
	v_add_co_u32_e32 v4, vcc, s23, v2
	global_load_dwordx4 v[58:61], v[6:7], off
	global_load_dwordx4 v[26:29], v[6:7], off offset:1024
	global_load_dwordx4 v[22:25], v[6:7], off offset:2048
	global_load_dwordx4 v[18:21], v[6:7], off offset:3072
	v_addc_co_u32_e32 v5, vcc, 0, v3, vcc
	v_add_co_u32_e32 v2, vcc, s24, v2
	s_nop 1
	v_addc_co_u32_e32 v3, vcc, 0, v3, vcc
	global_load_dwordx4 v[62:65], v[4:5], off
	global_load_dwordx4 v[66:69], v[4:5], off offset:1024
	global_load_dwordx4 v[70:73], v[4:5], off offset:2048
	global_load_dwordx4 v[74:77], v[4:5], off offset:3072
	global_load_dwordx4 v[14:17], v[2:3], off
	global_load_dwordx4 v[10:13], v[2:3], off offset:1024
	global_load_dwordx4 v[6:9], v[2:3], off offset:2048
	s_nop 0
	global_load_dwordx4 v[2:5], v[2:3], off offset:3072
	s_waitcnt vmcnt(15)
	v_lshlrev_b32_e32 v83, 16, v42
	v_and_b32_e32 v84, 0xffff0000, v42
	v_lshlrev_b32_e32 v85, 16, v43
	v_and_b32_e32 v86, 0xffff0000, v43
	v_lshlrev_b32_e32 v89, 16, v45
	v_and_b32_e32 v90, 0xffff0000, v45
	s_waitcnt vmcnt(14)
	v_lshlrev_b32_e32 v97, 16, v49
	v_and_b32_e32 v98, 0xffff0000, v49
	v_lshlrev_b32_e32 v87, 16, v44
	v_and_b32_e32 v88, 0xffff0000, v44
	v_lshlrev_b32_e32 v91, 16, v46
	v_and_b32_e32 v92, 0xffff0000, v46
	v_lshlrev_b32_e32 v93, 16, v47
	v_and_b32_e32 v94, 0xffff0000, v47
	s_waitcnt vmcnt(13)
	v_lshlrev_b32_e32 v101, 16, v51
	v_and_b32_e32 v102, 0xffff0000, v51
	v_lshlrev_b32_e32 v103, 16, v52
	v_and_b32_e32 v104, 0xffff0000, v52
	v_max_f32_e64 v41, |v84|, |v84|
	v_max_f32_e64 v42, |v83|, |v83|
	v_max_f32_e64 v43, |v86|, |v86|
	v_max_f32_e64 v44, |v85|, |v85|
	v_max_f32_e64 v45, |v90|, |v90|
	v_max_f32_e64 v46, |v89|, |v89|
	v_max_f32_e64 v51, |v98|, |v98|
	v_max_f32_e64 v52, |v97|, |v97|
	v_lshlrev_b32_e32 v95, 16, v48
	v_and_b32_e32 v96, 0xffff0000, v48
	v_lshlrev_b32_e32 v99, 16, v50
	v_and_b32_e32 v100, 0xffff0000, v50
	v_max_f32_e64 v47, |v92|, |v92|
	v_max_f32_e64 v48, |v91|, |v91|
	v_max_f32_e64 v49, |v94|, |v94|
	v_max_f32_e64 v50, |v93|, |v93|
	v_max_f32_e32 v41, v42, v41
	v_max_f32_e32 v42, v44, v43
	v_max_f32_e32 v43, v46, v45
	v_max_f32_e32 v46, v52, v51
	v_max_f32_e32 v44, v48, v47
	v_max_f32_e32 v45, v50, v49
	v_max3_f32 v43, |v87|, |v88|, v43
	v_max3_f32 v46, |v95|, |v96|, v46
	v_lshlrev_b32_e32 v105, 16, v53
	v_max3_f32 v41, v41, v42, v43
	v_max3_f32 v42, v44, v45, v46
	v_and_b32_e32 v106, 0xffff0000, v53
	v_max3_f32 v41, v41, 0, v42
	v_max_f32_e64 v42, |v106|, |v106|
	v_max_f32_e64 v43, |v105|, |v105|
	s_waitcnt vmcnt(12)
	v_lshlrev_b32_e32 v107, 16, v54
	v_and_b32_e32 v108, 0xffff0000, v54
	v_max_f32_e32 v42, v43, v42
	v_max_f32_e64 v43, |v108|, |v108|
	v_max_f32_e64 v44, |v107|, |v107|
	v_lshlrev_b32_e32 v109, 16, v55
	v_and_b32_e32 v110, 0xffff0000, v55
	v_max_f32_e32 v43, v44, v43
	v_max_f32_e64 v44, |v110|, |v110|
	v_max_f32_e64 v45, |v109|, |v109|
	v_lshlrev_b32_e32 v113, 16, v57
	v_and_b32_e32 v114, 0xffff0000, v57
	v_max_f32_e32 v44, v45, v44
	v_max_f32_e64 v45, |v114|, |v114|
	v_max_f32_e64 v46, |v113|, |v113|
	v_max_f32_e64 v78, |v100|, |v100|
	v_max_f32_e64 v79, |v99|, |v99|
	v_max_f32_e64 v80, |v102|, |v102|
	v_max_f32_e64 v81, |v101|, |v101|
	v_lshlrev_b32_e32 v111, 16, v56
	v_and_b32_e32 v112, 0xffff0000, v56
	v_max_f32_e32 v45, v46, v45
	v_max_f32_e32 v47, v79, v78
	v_max_f32_e32 v48, v81, v80
	v_max3_f32 v42, |v103|, |v104|, v42
	v_max3_f32 v45, |v111|, |v112|, v45
	v_max3_f32 v42, v47, v48, v42
	v_max3_f32 v43, v43, v44, v45
	s_waitcnt vmcnt(7)
	v_lshlrev_b32_e32 v115, 16, v62
	v_and_b32_e32 v116, 0xffff0000, v62
	v_max3_f32 v41, v41, v42, v43
	v_max_f32_e64 v42, |v116|, |v116|
	v_max_f32_e64 v43, |v115|, |v115|
	v_lshlrev_b32_e32 v117, 16, v63
	v_and_b32_e32 v118, 0xffff0000, v63
	v_max_f32_e32 v42, v43, v42
	v_max_f32_e64 v43, |v118|, |v118|
	v_max_f32_e64 v44, |v117|, |v117|
	v_lshlrev_b32_e32 v121, 16, v65
	v_and_b32_e32 v122, 0xffff0000, v65
	v_max_f32_e32 v43, v44, v43
	v_max_f32_e64 v44, |v122|, |v122|
	v_max_f32_e64 v45, |v121|, |v121|
	v_lshlrev_b32_e32 v119, 16, v64
	v_and_b32_e32 v120, 0xffff0000, v64
	v_max_f32_e32 v44, v45, v44
	v_max3_f32 v44, |v119|, |v120|, v44
	s_waitcnt vmcnt(6)
	v_lshlrev_b32_e32 v123, 16, v66
	v_and_b32_e32 v124, 0xffff0000, v66
	v_max3_f32 v42, v42, v43, v44
	v_max_f32_e64 v43, |v124|, |v124|
	v_max_f32_e64 v44, |v123|, |v123|
	v_lshlrev_b32_e32 v125, 16, v67
	v_and_b32_e32 v126, 0xffff0000, v67
	v_max_f32_e32 v43, v44, v43
	v_max_f32_e64 v44, |v126|, |v126|
	v_max_f32_e64 v45, |v125|, |v125|
	v_lshlrev_b32_e32 v129, 16, v69
	v_and_b32_e32 v130, 0xffff0000, v69
	v_max_f32_e32 v44, v45, v44
	v_max_f32_e64 v45, |v130|, |v130|
	v_max_f32_e64 v46, |v129|, |v129|
	v_lshlrev_b32_e32 v127, 16, v68
	v_and_b32_e32 v128, 0xffff0000, v68
	v_max_f32_e32 v45, v46, v45
	v_max3_f32 v45, |v127|, |v128|, v45
	v_max3_f32 v43, v43, v44, v45
	s_waitcnt vmcnt(5)
	v_lshlrev_b32_e32 v131, 16, v70
	v_and_b32_e32 v132, 0xffff0000, v70
	v_max3_f32 v41, v41, v42, v43
	v_max_f32_e64 v42, |v132|, |v132|
	v_max_f32_e64 v43, |v131|, |v131|
	v_lshlrev_b32_e32 v133, 16, v71
	v_and_b32_e32 v137, 0xffff0000, v71
	v_max_f32_e32 v42, v43, v42
	v_max_f32_e64 v43, |v137|, |v137|
	v_max_f32_e64 v44, |v133|, |v133|
	v_lshlrev_b32_e32 v140, 16, v73
	v_and_b32_e32 v141, 0xffff0000, v73
	v_max_f32_e32 v43, v44, v43
	v_max_f32_e64 v44, |v141|, |v141|
	v_max_f32_e64 v45, |v140|, |v140|
	v_lshlrev_b32_e32 v138, 16, v72
	v_and_b32_e32 v139, 0xffff0000, v72
	v_max_f32_e32 v44, v45, v44
	v_max3_f32 v44, |v138|, |v139|, v44
	s_waitcnt vmcnt(4)
; __device__ __forceinline__ float bflo(unsigned w) { return __uint_as_float(w << 16); }
; __device__ __forceinline__ float bfhi(unsigned w) { return __uint_as_float(w & 0xffff0000u); }
; #pragma unroll
;     for (int j = 0; j < 8; ++j) mx = fmaxf(mx, fmaxf(fmaxf(fmaxf(fabsf(bflo(w[j].x)), fabsf(bfhi(w[j].x))), fmaxf(fabsf(bflo(w[j].y)), fabsf(bfhi(w[j].y)))), fmaxf(fmaxf(fabsf(bflo(w[j].z)), fabsf(bfhi(w[j].z))), fmaxf(fabsf(bflo(w[j].w)), fabsf(bfhi(w[j].w))))));
; #pragma unroll
;     for (int o = 1; o < 64; o <<= 1) mx = fmaxf(mx, __shfl_xor(mx, o));
;     return mx; }
	v_lshlrev_b32_e32 v142, 16, v74
	v_and_b32_e32 v143, 0xffff0000, v74
	v_max3_f32 v42, v42, v43, v44
	v_max_f32_e64 v43, |v143|, |v143|
	v_max_f32_e64 v44, |v142|, |v142|
	v_lshlrev_b32_e32 v144, 16, v75
	v_and_b32_e32 v145, 0xffff0000, v75
	v_max_f32_e32 v43, v44, v43
	v_max_f32_e64 v44, |v145|, |v145|
	v_max_f32_e64 v45, |v144|, |v144|
	v_lshlrev_b32_e32 v148, 16, v77
	v_and_b32_e32 v149, 0xffff0000, v77
	v_max_f32_e32 v44, v45, v44
	v_max_f32_e64 v45, |v149|, |v149|
	v_max_f32_e64 v46, |v148|, |v148|
	v_lshlrev_b32_e32 v146, 16, v76
	v_and_b32_e32 v147, 0xffff0000, v76
	v_max_f32_e32 v45, v46, v45
	v_max3_f32 v45, |v146|, |v147|, v45
	v_max3_f32 v43, v43, v44, v45
	v_lshlrev_b32_e32 v82, 16, v58
	v_and_b32_e32 v80, 0xffff0000, v58
	v_max3_f32 v157, v41, v42, v43
	v_max_f32_e64 v41, |v80|, |v80|
	v_max_f32_e64 v42, |v82|, |v82|
	v_lshlrev_b32_e32 v81, 16, v59
	v_and_b32_e32 v79, 0xffff0000, v59
	v_max_f32_e32 v41, v42, v41
	v_max_f32_e64 v42, |v79|, |v79|
	v_max_f32_e64 v43, |v81|, |v81|
	v_lshlrev_b32_e32 v76, 16, v61
	v_and_b32_e32 v75, 0xffff0000, v61
	v_max_f32_e32 v42, v43, v42
	v_max_f32_e64 v43, |v75|, |v75|
	v_max_f32_e64 v44, |v76|, |v76|
	v_lshlrev_b32_e32 v78, 16, v60
	v_and_b32_e32 v77, 0xffff0000, v60
	v_max_f32_e32 v43, v44, v43
	v_max3_f32 v43, |v78|, |v77|, v43
	v_lshlrev_b32_e32 v74, 16, v26
	v_and_b32_e32 v72, 0xffff0000, v26
	v_lshlrev_b32_e32 v68, 16, v29
	v_and_b32_e32 v67, 0xffff0000, v29
	v_max3_f32 v41, v41, v42, v43
	v_max_f32_e64 v26, |v72|, |v72|
	v_max_f32_e64 v42, |v74|, |v74|
	v_lshlrev_b32_e32 v73, 16, v27
	v_and_b32_e32 v71, 0xffff0000, v27
	v_lshlrev_b32_e32 v70, 16, v28
	v_and_b32_e32 v69, 0xffff0000, v28
	v_max_f32_e64 v28, |v67|, |v67|
	v_max_f32_e64 v29, |v68|, |v68|
	v_max_f32_e32 v26, v42, v26
	v_max_f32_e64 v27, |v71|, |v71|
	v_max_f32_e64 v42, |v73|, |v73|
	v_max_f32_e32 v28, v29, v28
	v_max_f32_e32 v27, v42, v27
	v_max3_f32 v28, |v70|, |v69|, v28
	v_lshlrev_b32_e32 v66, 16, v22
	v_and_b32_e32 v64, 0xffff0000, v22
	v_lshlrev_b32_e32 v60, 16, v25
	v_and_b32_e32 v59, 0xffff0000, v25
	v_max3_f32 v26, v26, v27, v28
	v_max_f32_e64 v22, |v64|, |v64|
	v_max_f32_e64 v27, |v66|, |v66|
	v_lshlrev_b32_e32 v65, 16, v23
	v_and_b32_e32 v63, 0xffff0000, v23
	v_lshlrev_b32_e32 v62, 16, v24
	v_and_b32_e32 v61, 0xffff0000, v24
	v_max_f32_e64 v24, |v59|, |v59|
	v_max_f32_e64 v25, |v60|, |v60|
	v_max_f32_e32 v22, v27, v22
	v_max_f32_e64 v23, |v63|, |v63|
	v_max_f32_e64 v27, |v65|, |v65|
	v_max_f32_e32 v24, v25, v24
	v_max_f32_e32 v23, v27, v23
	v_max3_f32 v24, |v62|, |v61|, v24
	v_lshlrev_b32_e32 v58, 16, v18
	v_and_b32_e32 v56, 0xffff0000, v18
	v_lshlrev_b32_e32 v52, 16, v21
	v_and_b32_e32 v51, 0xffff0000, v21
	v_max3_f32 v22, v22, v23, v24
	v_max_f32_e64 v18, |v56|, |v56|
	v_max_f32_e64 v23, |v58|, |v58|
	v_lshlrev_b32_e32 v57, 16, v19
	v_and_b32_e32 v55, 0xffff0000, v19
	v_lshlrev_b32_e32 v54, 16, v20
	v_and_b32_e32 v53, 0xffff0000, v20
	v_max_f32_e64 v20, |v51|, |v51|
	v_max_f32_e64 v21, |v52|, |v52|
	v_max_f32_e32 v18, v23, v18
	v_max_f32_e64 v19, |v55|, |v55|
	v_max_f32_e64 v23, |v57|, |v57|
	v_max_f32_e32 v20, v21, v20
	v_max_f32_e32 v19, v23, v19
	v_max3_f32 v20, |v54|, |v53|, v20
	s_waitcnt vmcnt(3)
	v_lshlrev_b32_e32 v50, 16, v14
	v_and_b32_e32 v48, 0xffff0000, v14
	v_lshlrev_b32_e32 v44, 16, v17
	v_and_b32_e32 v43, 0xffff0000, v17
	v_max3_f32 v18, v18, v19, v20
	v_max_f32_e64 v14, |v48|, |v48|
	v_max_f32_e64 v19, |v50|, |v50|
	v_lshlrev_b32_e32 v49, 16, v15
	v_and_b32_e32 v47, 0xffff0000, v15
	v_lshlrev_b32_e32 v46, 16, v16
	v_and_b32_e32 v45, 0xffff0000, v16
	v_max_f32_e64 v16, |v43|, |v43|
	v_max_f32_e64 v17, |v44|, |v44|
	v_max_f32_e32 v14, v19, v14
	v_max_f32_e64 v15, |v47|, |v47|
	v_max_f32_e64 v19, |v49|, |v49|
	v_max_f32_e32 v16, v17, v16
	v_max3_f32 v26, v41, 0, v26
	v_max_f32_e32 v15, v19, v15
	v_max3_f32 v16, |v46|, |v45|, v16
	s_waitcnt vmcnt(2)
	v_lshlrev_b32_e32 v42, 16, v10
	v_and_b32_e32 v29, 0xffff0000, v10
	v_lshlrev_b32_e32 v25, 16, v13
	v_and_b32_e32 v24, 0xffff0000, v13
	v_max3_f32 v18, v26, v22, v18
	v_max3_f32 v14, v14, v15, v16
	v_max_f32_e64 v10, |v29|, |v29|
	v_max_f32_e64 v15, |v42|, |v42|
	v_lshlrev_b32_e32 v41, 16, v11
	v_and_b32_e32 v28, 0xffff0000, v11
	v_lshlrev_b32_e32 v27, 16, v12
	v_and_b32_e32 v26, 0xffff0000, v12
	v_max_f32_e64 v12, |v24|, |v24|
	v_max_f32_e64 v13, |v25|, |v25|
	v_max_f32_e32 v10, v15, v10
	v_max_f32_e64 v11, |v28|, |v28|
	v_max_f32_e64 v15, |v41|, |v41|
	v_max_f32_e32 v12, v13, v12
	v_max_f32_e32 v11, v15, v11
	v_max3_f32 v12, |v27|, |v26|, v12
	v_max3_f32 v10, v10, v11, v12
	s_waitcnt vmcnt(1)
	v_lshlrev_b32_e32 v23, 16, v6
	v_and_b32_e32 v21, 0xffff0000, v6
	v_lshlrev_b32_e32 v17, 16, v9
	v_and_b32_e32 v16, 0xffff0000, v9
	v_max3_f32 v160, v18, v14, v10
	v_max_f32_e64 v6, |v21|, |v21|
	v_max_f32_e64 v10, |v23|, |v23|
	v_lshlrev_b32_e32 v22, 16, v7
	v_and_b32_e32 v20, 0xffff0000, v7
	v_lshlrev_b32_e32 v19, 16, v8
	v_and_b32_e32 v18, 0xffff0000, v8
	v_max_f32_e64 v8, |v16|, |v16|
	v_max_f32_e64 v9, |v17|, |v17|
	v_max_f32_e32 v6, v10, v6
	v_max_f32_e64 v7, |v20|, |v20|
	v_max_f32_e64 v10, |v22|, |v22|
	v_max_f32_e32 v8, v9, v8
	v_max_f32_e32 v7, v10, v7
	v_max3_f32 v8, |v19|, |v18|, v8
	v_max3_f32 v6, v6, v7, v8
	s_waitcnt vmcnt(0)
	v_lshlrev_b32_e32 v15, 16, v2
	v_and_b32_e32 v13, 0xffff0000, v2
	v_lshlrev_b32_e32 v9, 16, v5
	v_and_b32_e32 v8, 0xffff0000, v5
	v_max_f32_e64 v2, |v13|, |v13|
	v_max_f32_e64 v7, |v15|, |v15|
	v_lshlrev_b32_e32 v14, 16, v3
	v_and_b32_e32 v12, 0xffff0000, v3
	v_lshlrev_b32_e32 v11, 16, v4
	v_and_b32_e32 v10, 0xffff0000, v4
	v_max_f32_e64 v4, |v8|, |v8|
	v_max_f32_e64 v5, |v9|, |v9|
	v_max_f32_e32 v2, v7, v2
	v_max_f32_e64 v3, |v12|, |v12|
	v_max_f32_e64 v7, |v14|, |v14|
	v_max_f32_e32 v4, v5, v4
	v_max_f32_e32 v3, v7, v3
	v_max3_f32 v4, |v11|, |v10|, v4
	v_max3_f32 v2, v2, v3, v4
	v_max3_f32 v2, v160, v6, v2
	s_nop 1
	v_mov_b32_dpp v158, v157 quad_perm:[1,0,3,2] row_mask:0xf bank_mask:0xf
	s_nop 1
	v_mov_b32_dpp v3, v2 quad_perm:[1,0,3,2] row_mask:0xf bank_mask:0xf
	s_waitcnt lgkmcnt(0)
; __device__ __forceinline__ float bflo(unsigned w) { return __uint_as_float(w << 16); }
; __device__ __forceinline__ float bfhi(unsigned w) { return __uint_as_float(w & 0xffff0000u); }
; #pragma unroll
;     for (int j = 0; j < 8; ++j) mx = fmaxf(mx, fmaxf(fmaxf(fmaxf(fabsf(bflo(w[j].x)), fabsf(bfhi(w[j].x))), fmaxf(fabsf(bflo(w[j].y)), fabsf(bfhi(w[j].y)))), fmaxf(fmaxf(fabsf(bflo(w[j].z)), fabsf(bfhi(w[j].z))), fmaxf(fabsf(bflo(w[j].w)), fabsf(bfhi(w[j].w))))));
; #pragma unroll
;     for (int o = 1; o < 64; o <<= 1) mx = fmaxf(mx, __shfl_xor(mx, o));
;     return mx; }
; __device__ __forceinline__ void quant_store8(const u32x4 (&w)[8], float inv, signed char* dst, int lane) { u32x2* qp = (u32x2*)dst + lane;
; #pragma unroll
;     for (int j = 0; j < 8; ++j) { const unsigned ww[4] = {w[j].x, w[j].y, w[j].z, w[j].w}; unsigned o2[2];
; #pragma unroll
;         for (int h2 = 0; h2 < 2; ++h2) { const int q0 = (int)rintf(bflo(ww[2 * h2]) * inv), q1 = (int)rintf(bfhi(ww[2 * h2]) * inv), q2 = (int)rintf(bflo(ww[2 * h2 + 1]) * inv), q3 = (int)rintf(bfhi(ww[2 * h2 + 1]) * inv);
;             o2[h2] = (unsigned)(q0 & 255) | ((unsigned)(q1 & 255) << 8) | ((unsigned)(q2 & 255) << 16) | ((unsigned)(q3 & 255) << 24); }
;         u32x2 o; o.x = o2[0]; o.y = o2[1]; qp[64 * j] = o; } }
; __device__ __forceinline__ void quant_rows2(const bf16_t* s0, const bf16_t* s1, signed char* d0, signed char* d1, int lane, float& step0, float& step1) {
;     const u32x4* p0 = (const u32x4*)s0 + lane; const u32x4* p1 = (const u32x4*)s1 + lane; u32x4 w0[8], w1[8];
; #pragma unroll
;     for (int j = 0; j < 8; ++j) { w0[j] = p0[64 * j]; w1[j] = p1[64 * j]; }
;     step0 = fmaxf(absmax8(w0), 1e-30f) * (1.0f / 127.0f); step1 = fmaxf(absmax8(w1), 1e-30f) * (1.0f / 127.0f);
;     quant_store8(w0, 1.0f / step0, d0, lane); quant_store8(w1, 1.0f / step1, d1, lane);
	v_max_f32_e32 v4, v158, v158
	s_waitcnt lgkmcnt(0)
	v_max_f32_e32 v3, v3, v3
	v_max_f32_e32 v4, v157, v4
	v_max_f32_e32 v2, v2, v3
	s_nop 1
	v_mov_b32_dpp v5, v4 quad_perm:[2,3,0,1] row_mask:0xf bank_mask:0xf
	s_nop 1
	v_mov_b32_dpp v3, v2 quad_perm:[2,3,0,1] row_mask:0xf bank_mask:0xf
	s_waitcnt lgkmcnt(0)
	v_max_f32_e32 v5, v5, v5
	s_waitcnt lgkmcnt(0)
	v_max_f32_e32 v3, v3, v3
	v_max_f32_e32 v4, v4, v5
	v_max_f32_e32 v2, v2, v3
	s_nop 1
	v_mov_b32_dpp v5, v4 row_half_mirror row_mask:0xf bank_mask:0xf
	s_nop 1
	v_mov_b32_dpp v3, v2 row_half_mirror row_mask:0xf bank_mask:0xf
	s_waitcnt lgkmcnt(0)
	v_max_f32_e32 v5, v5, v5
	s_waitcnt lgkmcnt(0)
	v_max_f32_e32 v3, v3, v3
	v_max_f32_e32 v4, v4, v5
	v_max_f32_e32 v2, v2, v3
	s_nop 1
	v_mov_b32_dpp v5, v4 row_mirror row_mask:0xf bank_mask:0xf
	s_nop 1
	v_mov_b32_dpp v3, v2 row_mirror row_mask:0xf bank_mask:0xf
	s_waitcnt lgkmcnt(0)
	v_max_f32_e32 v5, v5, v5
	s_waitcnt lgkmcnt(0)
	v_max_f32_e32 v3, v3, v3
	v_max_f32_e32 v4, v4, v5
	v_max_f32_e32 v2, v2, v3
	s_waitcnt lgkmcnt(0)
	s_waitcnt lgkmcnt(0)
	v_mov_b32_e32 v5, v4
	s_nop 1
	v_permlane16_swap_b32_e32 v4, v5
	s_nop 0
	v_max_f32_e32 v4, v4, v5
	v_mov_b32_e32 v3, v2
	s_nop 1
	v_permlane16_swap_b32_e32 v3, v2
	s_nop 0
	v_max_f32_e32 v3, v3, v2
	ds_bpermute_b32 v5, v39, v4
	ds_bpermute_b32 v6, v39, v3
	s_waitcnt lgkmcnt(1)
	v_max3_f32 v2, v4, v5, s25
	s_waitcnt lgkmcnt(0)
	v_max3_f32 v3, v3, v6, s25
	v_pk_mul_f32 v[2:3], v[2:3], s[8:9] op_sel_hi:[1,0]
	s_nop 0
	v_div_scale_f32 v4, s[12:13], v2, v2, 1.0
	v_rcp_f32_e32 v5, v4
	s_nop 0
	v_fma_f32 v6, -v4, v5, 1.0
	v_fmac_f32_e32 v5, v6, v5
	v_div_scale_f32 v6, vcc, 1.0, v2, 1.0
	v_mul_f32_e32 v7, v6, v5
	v_fma_f32 v157, -v4, v7, v6
	v_fmac_f32_e32 v7, v157, v5
	v_fma_f32 v4, -v4, v7, v6
	v_div_fmas_f32 v4, v4, v5, v7
	v_div_fixup_f32 v157, v4, v2, 1.0
	v_mul_f32_e32 v7, v157, v84
	v_mul_f32_e32 v6, v157, v83
	v_rndne_f32_e32 v7, v7
	v_mul_f32_e32 v83, v157, v85
	v_rndne_f32_e32 v6, v6
	v_cvt_i32_f32_e32 v7, v7
	v_rndne_f32_e32 v83, v83
	v_mul_f32_e32 v84, v157, v86
	v_cvt_i32_f32_e32 v6, v6
	v_cvt_i32_f32_sdwa v83, v83 dst_sel:WORD_1 dst_unused:UNUSED_PAD src0_sel:DWORD
	v_rndne_f32_e32 v84, v84
	v_cvt_i32_f32_sdwa v84, v84 dst_sel:BYTE_3 dst_unused:UNUSED_PAD src0_sel:DWORD
	v_lshlrev_b32_e32 v7, 8, v7
	v_and_b32_e32 v83, 0xff0000, v83
	v_perm_b32 v6, v7, v6, s28
	v_mul_f32_e32 v7, v157, v88
	v_or3_b32 v84, v6, v84, v83
	v_mul_f32_e32 v6, v157, v87
	v_rndne_f32_e32 v7, v7
	v_mul_f32_e32 v83, v157, v89
	v_rndne_f32_e32 v6, v6
	v_cvt_i32_f32_e32 v7, v7
	v_rndne_f32_e32 v83, v83
	v_mul_f32_e32 v85, v157, v90
	v_cvt_i32_f32_e32 v6, v6
	v_cvt_i32_f32_sdwa v83, v83 dst_sel:WORD_1 dst_unused:UNUSED_PAD src0_sel:DWORD
	v_rndne_f32_e32 v85, v85
	v_cvt_i32_f32_sdwa v85, v85 dst_sel:BYTE_3 dst_unused:UNUSED_PAD src0_sel:DWORD
	v_lshlrev_b32_e32 v7, 8, v7
	v_lshl_add_u64 v[4:5], v[32:33], 0, s[0:1]
	v_and_b32_e32 v83, 0xff0000, v83
	v_perm_b32 v6, v7, v6, s28
	v_or3_b32 v85, v6, v85, v83
	v_add_co_u32_e32 v6, vcc, s29, v4
	v_mul_f32_e32 v83, v157, v91
	s_nop 0
	v_addc_co_u32_e32 v7, vcc, 0, v5, vcc
	v_add_co_u32_e32 v4, vcc, s30, v4
	v_rndne_f32_e32 v83, v83
	s_nop 0
	v_addc_co_u32_e32 v5, vcc, 0, v5, vcc
	global_store_dwordx2 v[4:5], v[84:85], off offset:-4096
	v_mul_f32_e32 v84, v157, v92
	v_rndne_f32_e32 v84, v84
	v_mul_f32_e32 v85, v157, v93
	v_cvt_i32_f32_e32 v84, v84
	v_rndne_f32_e32 v85, v85
	v_mul_f32_e32 v86, v157, v94
	v_cvt_i32_f32_e32 v83, v83
	v_cvt_i32_f32_sdwa v85, v85 dst_sel:WORD_1 dst_unused:UNUSED_PAD src0_sel:DWORD
	v_rndne_f32_e32 v86, v86
	v_cvt_i32_f32_sdwa v86, v86 dst_sel:BYTE_3 dst_unused:UNUSED_PAD src0_sel:DWORD
	v_lshlrev_b32_e32 v84, 8, v84
	v_and_b32_e32 v85, 0xff0000, v85
	v_perm_b32 v83, v84, v83, s28
	v_or3_b32 v84, v83, v86, v85
	v_mul_f32_e32 v85, v157, v96
	v_mul_f32_e32 v83, v157, v95
	v_rndne_f32_e32 v85, v85
	v_mul_f32_e32 v86, v157, v97
	v_rndne_f32_e32 v83, v83
	v_cvt_i32_f32_e32 v85, v85
	v_rndne_f32_e32 v86, v86
	v_mul_f32_e32 v87, v157, v98
	v_cvt_i32_f32_e32 v83, v83
	v_cvt_i32_f32_sdwa v86, v86 dst_sel:WORD_1 dst_unused:UNUSED_PAD src0_sel:DWORD
	v_rndne_f32_e32 v87, v87
	v_cvt_i32_f32_sdwa v87, v87 dst_sel:BYTE_3 dst_unused:UNUSED_PAD src0_sel:DWORD
	v_lshlrev_b32_e32 v85, 8, v85
	v_and_b32_e32 v86, 0xff0000, v86
	v_perm_b32 v83, v85, v83, s28
	v_or3_b32 v85, v83, v87, v86
	global_store_dwordx2 v[6:7], v[84:85], off offset:512
	v_mul_f32_e32 v84, v157, v100
	v_mul_f32_e32 v83, v157, v99
	v_rndne_f32_e32 v84, v84
	v_mul_f32_e32 v85, v157, v101
	v_rndne_f32_e32 v83, v83
	v_cvt_i32_f32_e32 v84, v84
	v_rndne_f32_e32 v85, v85
	v_mul_f32_e32 v86, v157, v102
	v_cvt_i32_f32_e32 v83, v83
	v_cvt_i32_f32_sdwa v85, v85 dst_sel:WORD_1 dst_unused:UNUSED_PAD src0_sel:DWORD
	v_rndne_f32_e32 v86, v86
	v_cvt_i32_f32_sdwa v86, v86 dst_sel:BYTE_3 dst_unused:UNUSED_PAD src0_sel:DWORD
	v_lshlrev_b32_e32 v84, 8, v84
	v_and_b32_e32 v85, 0xff0000, v85
	v_perm_b32 v83, v84, v83, s28
	v_or3_b32 v84, v83, v86, v85
	v_mul_f32_e32 v85, v157, v104
	v_mul_f32_e32 v83, v157, v103
	v_rndne_f32_e32 v85, v85
	v_mul_f32_e32 v86, v157, v105
	v_rndne_f32_e32 v83, v83
	v_cvt_i32_f32_e32 v85, v85
	v_rndne_f32_e32 v86, v86
	v_mul_f32_e32 v87, v157, v106
	v_cvt_i32_f32_e32 v83, v83
	v_cvt_i32_f32_sdwa v86, v86 dst_sel:WORD_1 dst_unused:UNUSED_PAD src0_sel:DWORD
	v_rndne_f32_e32 v87, v87
	v_cvt_i32_f32_sdwa v87, v87 dst_sel:BYTE_3 dst_unused:UNUSED_PAD src0_sel:DWORD
	v_lshlrev_b32_e32 v85, 8, v85
	v_and_b32_e32 v86, 0xff0000, v86
	v_perm_b32 v83, v85, v83, s28
	v_or3_b32 v85, v83, v87, v86
	global_store_dwordx2 v[6:7], v[84:85], off offset:1024
	v_mul_f32_e32 v84, v157, v108
	v_mul_f32_e32 v83, v157, v107
; __device__ __forceinline__ float bflo(unsigned w) { return __uint_as_float(w << 16); }
; __device__ __forceinline__ float bfhi(unsigned w) { return __uint_as_float(w & 0xffff0000u); }
; __device__ __forceinline__ void quant_store8(const u32x4 (&w)[8], float inv, signed char* dst, int lane) { u32x2* qp = (u32x2*)dst + lane;
; #pragma unroll
;     for (int j = 0; j < 8; ++j) { const unsigned ww[4] = {w[j].x, w[j].y, w[j].z, w[j].w}; unsigned o2[2];
; #pragma unroll
;         for (int h2 = 0; h2 < 2; ++h2) { const int q0 = (int)rintf(bflo(ww[2 * h2]) * inv), q1 = (int)rintf(bfhi(ww[2 * h2]) * inv), q2 = (int)rintf(bflo(ww[2 * h2 + 1]) * inv), q3 = (int)rintf(bfhi(ww[2 * h2 + 1]) * inv);
;             o2[h2] = (unsigned)(q0 & 255) | ((unsigned)(q1 & 255) << 8) | ((unsigned)(q2 & 255) << 16) | ((unsigned)(q3 & 255) << 24); }
;         u32x2 o; o.x = o2[0]; o.y = o2[1]; qp[64 * j] = o; } }
	v_rndne_f32_e32 v84, v84
	v_mul_f32_e32 v85, v157, v109
	v_rndne_f32_e32 v83, v83
	v_cvt_i32_f32_e32 v84, v84
	v_rndne_f32_e32 v85, v85
	v_mul_f32_e32 v86, v157, v110
	v_cvt_i32_f32_e32 v83, v83
	v_cvt_i32_f32_sdwa v85, v85 dst_sel:WORD_1 dst_unused:UNUSED_PAD src0_sel:DWORD
	v_rndne_f32_e32 v86, v86
	v_cvt_i32_f32_sdwa v86, v86 dst_sel:BYTE_3 dst_unused:UNUSED_PAD src0_sel:DWORD
	v_lshlrev_b32_e32 v84, 8, v84
	v_and_b32_e32 v85, 0xff0000, v85
	v_perm_b32 v83, v84, v83, s28
	v_or3_b32 v84, v83, v86, v85
	v_mul_f32_e32 v85, v157, v112
	v_mul_f32_e32 v83, v157, v111
	v_rndne_f32_e32 v85, v85
	v_mul_f32_e32 v86, v157, v113
	v_rndne_f32_e32 v83, v83
	v_cvt_i32_f32_e32 v85, v85
	v_rndne_f32_e32 v86, v86
	v_mul_f32_e32 v87, v157, v114
	v_cvt_i32_f32_e32 v83, v83
	v_cvt_i32_f32_sdwa v86, v86 dst_sel:WORD_1 dst_unused:UNUSED_PAD src0_sel:DWORD
	v_rndne_f32_e32 v87, v87
	v_cvt_i32_f32_sdwa v87, v87 dst_sel:BYTE_3 dst_unused:UNUSED_PAD src0_sel:DWORD
	v_lshlrev_b32_e32 v85, 8, v85
	v_and_b32_e32 v86, 0xff0000, v86
	v_perm_b32 v83, v85, v83, s28
	v_or3_b32 v85, v83, v87, v86
	global_store_dwordx2 v[6:7], v[84:85], off offset:1536
	v_mul_f32_e32 v84, v157, v116
	v_mul_f32_e32 v83, v157, v115
	v_rndne_f32_e32 v84, v84
	v_mul_f32_e32 v85, v157, v117
	v_rndne_f32_e32 v83, v83
	v_cvt_i32_f32_e32 v84, v84
	v_rndne_f32_e32 v85, v85
	v_mul_f32_e32 v86, v157, v118
	v_cvt_i32_f32_e32 v83, v83
	v_cvt_i32_f32_sdwa v85, v85 dst_sel:WORD_1 dst_unused:UNUSED_PAD src0_sel:DWORD
	v_rndne_f32_e32 v86, v86
	v_cvt_i32_f32_sdwa v86, v86 dst_sel:BYTE_3 dst_unused:UNUSED_PAD src0_sel:DWORD
	v_lshlrev_b32_e32 v84, 8, v84
	v_and_b32_e32 v85, 0xff0000, v85
	v_perm_b32 v83, v84, v83, s28
	v_or3_b32 v84, v83, v86, v85
	v_mul_f32_e32 v85, v157, v120
	v_mul_f32_e32 v83, v157, v119
	v_rndne_f32_e32 v85, v85
	v_mul_f32_e32 v86, v157, v121
	v_rndne_f32_e32 v83, v83
	v_cvt_i32_f32_e32 v85, v85
	v_rndne_f32_e32 v86, v86
	v_mul_f32_e32 v87, v157, v122
	v_cvt_i32_f32_e32 v83, v83
	v_cvt_i32_f32_sdwa v86, v86 dst_sel:WORD_1 dst_unused:UNUSED_PAD src0_sel:DWORD
	v_rndne_f32_e32 v87, v87
	v_cvt_i32_f32_sdwa v87, v87 dst_sel:BYTE_3 dst_unused:UNUSED_PAD src0_sel:DWORD
	v_lshlrev_b32_e32 v85, 8, v85
	v_and_b32_e32 v86, 0xff0000, v86
	v_perm_b32 v83, v85, v83, s28
	v_or3_b32 v85, v83, v87, v86
	global_store_dwordx2 v[6:7], v[84:85], off offset:2048
	v_mul_f32_e32 v84, v157, v124
	v_mul_f32_e32 v83, v157, v123
	v_rndne_f32_e32 v84, v84
	v_mul_f32_e32 v85, v157, v125
	v_rndne_f32_e32 v83, v83
	v_cvt_i32_f32_e32 v84, v84
	v_rndne_f32_e32 v85, v85
	v_mul_f32_e32 v86, v157, v126
	v_cvt_i32_f32_e32 v83, v83
	v_cvt_i32_f32_sdwa v85, v85 dst_sel:WORD_1 dst_unused:UNUSED_PAD src0_sel:DWORD
	v_rndne_f32_e32 v86, v86
	v_cvt_i32_f32_sdwa v86, v86 dst_sel:BYTE_3 dst_unused:UNUSED_PAD src0_sel:DWORD
	v_lshlrev_b32_e32 v84, 8, v84
	v_and_b32_e32 v85, 0xff0000, v85
	v_perm_b32 v83, v84, v83, s28
	v_or3_b32 v84, v83, v86, v85
	v_mul_f32_e32 v85, v157, v128
	v_mul_f32_e32 v83, v157, v127
	v_rndne_f32_e32 v85, v85
	v_mul_f32_e32 v86, v157, v129
	v_rndne_f32_e32 v83, v83
	v_cvt_i32_f32_e32 v85, v85
	v_rndne_f32_e32 v86, v86
	v_mul_f32_e32 v87, v157, v130
	v_cvt_i32_f32_e32 v83, v83
	v_cvt_i32_f32_sdwa v86, v86 dst_sel:WORD_1 dst_unused:UNUSED_PAD src0_sel:DWORD
	v_rndne_f32_e32 v87, v87
	v_cvt_i32_f32_sdwa v87, v87 dst_sel:BYTE_3 dst_unused:UNUSED_PAD src0_sel:DWORD
	v_lshlrev_b32_e32 v85, 8, v85
	v_and_b32_e32 v86, 0xff0000, v86
	v_perm_b32 v83, v85, v83, s28
	v_or3_b32 v85, v83, v87, v86
	global_store_dwordx2 v[6:7], v[84:85], off offset:2560
	v_mul_f32_e32 v84, v157, v132
	v_mul_f32_e32 v83, v157, v131
	v_rndne_f32_e32 v84, v84
	v_mul_f32_e32 v85, v157, v133
	v_rndne_f32_e32 v83, v83
	v_cvt_i32_f32_e32 v84, v84
	v_rndne_f32_e32 v85, v85
	v_mul_f32_e32 v86, v157, v137
	v_cvt_i32_f32_e32 v83, v83
	v_cvt_i32_f32_sdwa v85, v85 dst_sel:WORD_1 dst_unused:UNUSED_PAD src0_sel:DWORD
	v_rndne_f32_e32 v86, v86
	v_cvt_i32_f32_sdwa v86, v86 dst_sel:BYTE_3 dst_unused:UNUSED_PAD src0_sel:DWORD
	v_lshlrev_b32_e32 v84, 8, v84
	v_and_b32_e32 v85, 0xff0000, v85
	v_perm_b32 v83, v84, v83, s28
	v_or3_b32 v84, v83, v86, v85
	v_mul_f32_e32 v85, v157, v139
	v_mul_f32_e32 v83, v157, v138
	v_rndne_f32_e32 v85, v85
	v_mul_f32_e32 v86, v157, v140
	v_rndne_f32_e32 v83, v83
	v_cvt_i32_f32_e32 v85, v85
	v_rndne_f32_e32 v86, v86
	v_mul_f32_e32 v87, v157, v141
	v_cvt_i32_f32_e32 v83, v83
	v_cvt_i32_f32_sdwa v86, v86 dst_sel:WORD_1 dst_unused:UNUSED_PAD src0_sel:DWORD
	v_rndne_f32_e32 v87, v87
	v_cvt_i32_f32_sdwa v87, v87 dst_sel:BYTE_3 dst_unused:UNUSED_PAD src0_sel:DWORD
	v_lshlrev_b32_e32 v85, 8, v85
	v_and_b32_e32 v86, 0xff0000, v86
	v_perm_b32 v83, v85, v83, s28
	v_or3_b32 v85, v83, v87, v86
	global_store_dwordx2 v[6:7], v[84:85], off offset:3072
	v_mul_f32_e32 v84, v157, v143
	v_mul_f32_e32 v83, v157, v142
	v_rndne_f32_e32 v84, v84
	v_mul_f32_e32 v85, v157, v144
	v_rndne_f32_e32 v83, v83
	v_cvt_i32_f32_e32 v84, v84
	v_rndne_f32_e32 v85, v85
	v_mul_f32_e32 v86, v157, v145
	v_cvt_i32_f32_e32 v83, v83
	v_cvt_i32_f32_sdwa v85, v85 dst_sel:WORD_1 dst_unused:UNUSED_PAD src0_sel:DWORD
	v_rndne_f32_e32 v86, v86
	v_cvt_i32_f32_sdwa v86, v86 dst_sel:BYTE_3 dst_unused:UNUSED_PAD src0_sel:DWORD
	v_lshlrev_b32_e32 v84, 8, v84
	v_and_b32_e32 v85, 0xff0000, v85
	v_perm_b32 v83, v84, v83, s28
	v_or3_b32 v84, v83, v86, v85
	v_mul_f32_e32 v85, v157, v147
	v_mul_f32_e32 v83, v157, v146
	v_rndne_f32_e32 v85, v85
	v_mul_f32_e32 v86, v157, v148
	v_rndne_f32_e32 v83, v83
	v_cvt_i32_f32_e32 v85, v85
	v_rndne_f32_e32 v86, v86
	v_mul_f32_e32 v87, v157, v149
	v_cvt_i32_f32_e32 v83, v83
	v_cvt_i32_f32_sdwa v86, v86 dst_sel:WORD_1 dst_unused:UNUSED_PAD src0_sel:DWORD
; __device__ __forceinline__ float bflo(unsigned w) { return __uint_as_float(w << 16); }
; __device__ __forceinline__ float bfhi(unsigned w) { return __uint_as_float(w & 0xffff0000u); }
; __device__ __forceinline__ void quant_store8(const u32x4 (&w)[8], float inv, signed char* dst, int lane) { u32x2* qp = (u32x2*)dst + lane;
; #pragma unroll
;     for (int j = 0; j < 8; ++j) { const unsigned ww[4] = {w[j].x, w[j].y, w[j].z, w[j].w}; unsigned o2[2];
; #pragma unroll
;         for (int h2 = 0; h2 < 2; ++h2) { const int q0 = (int)rintf(bflo(ww[2 * h2]) * inv), q1 = (int)rintf(bfhi(ww[2 * h2]) * inv), q2 = (int)rintf(bflo(ww[2 * h2 + 1]) * inv), q3 = (int)rintf(bfhi(ww[2 * h2 + 1]) * inv);
;             o2[h2] = (unsigned)(q0 & 255) | ((unsigned)(q1 & 255) << 8) | ((unsigned)(q2 & 255) << 16) | ((unsigned)(q3 & 255) << 24); }
;         u32x2 o; o.x = o2[0]; o.y = o2[1]; qp[64 * j] = o; } }
; __device__ __forceinline__ void quant_rows2(const bf16_t* s0, const bf16_t* s1, signed char* d0, signed char* d1, int lane, float& step0, float& step1) {
;     const u32x4* p0 = (const u32x4*)s0 + lane; const u32x4* p1 = (const u32x4*)s1 + lane; u32x4 w0[8], w1[8];
; #pragma unroll
;     for (int j = 0; j < 8; ++j) { w0[j] = p0[64 * j]; w1[j] = p1[64 * j]; }
;     step0 = fmaxf(absmax8(w0), 1e-30f) * (1.0f / 127.0f); step1 = fmaxf(absmax8(w1), 1e-30f) * (1.0f / 127.0f);
;     quant_store8(w0, 1.0f / step0, d0, lane); quant_store8(w1, 1.0f / step1, d1, lane);
	v_rndne_f32_e32 v87, v87
	v_cvt_i32_f32_sdwa v87, v87 dst_sel:BYTE_3 dst_unused:UNUSED_PAD src0_sel:DWORD
	v_div_scale_f32 v88, s[12:13], v3, v3, 1.0
	v_rcp_f32_e32 v89, v88
	v_lshlrev_b32_e32 v85, 8, v85
	v_and_b32_e32 v86, 0xff0000, v86
	v_perm_b32 v83, v85, v83, s28
	v_or3_b32 v85, v83, v87, v86
	global_store_dwordx2 v[6:7], v[84:85], off offset:3584
	v_fma_f32 v6, -v88, v89, 1.0
	v_fmac_f32_e32 v89, v6, v89
	v_div_scale_f32 v6, vcc, 1.0, v3, 1.0
	v_mul_f32_e32 v7, v6, v89
	v_fma_f32 v83, -v88, v7, v6
	v_fmac_f32_e32 v7, v83, v89
	v_fma_f32 v6, -v88, v7, v6
	v_div_fmas_f32 v6, v6, v89, v7
	v_div_fixup_f32 v83, v6, v3, 1.0
	v_mul_f32_e32 v7, v83, v80
	v_mul_f32_e32 v6, v83, v82
	v_rndne_f32_e32 v7, v7
	v_rndne_f32_e32 v6, v6
	v_cvt_i32_f32_e32 v7, v7
	v_cvt_i32_f32_e32 v6, v6
	v_mul_f32_e32 v77, v83, v77
	v_mul_f32_e32 v80, v83, v81
	v_lshlrev_b32_e32 v7, 8, v7
	v_perm_b32 v6, v7, v6, s28
	v_mul_f32_e32 v7, v83, v78
	v_rndne_f32_e32 v77, v77
	v_mul_f32_e32 v76, v83, v76
	v_rndne_f32_e32 v80, v80
	v_mul_f32_e32 v79, v83, v79
	v_rndne_f32_e32 v7, v7
	v_cvt_i32_f32_e32 v77, v77
	v_rndne_f32_e32 v76, v76
	v_mul_f32_e32 v75, v83, v75
	v_cvt_i32_f32_sdwa v80, v80 dst_sel:WORD_1 dst_unused:UNUSED_PAD src0_sel:DWORD
	v_rndne_f32_e32 v79, v79
	v_cvt_i32_f32_e32 v7, v7
	v_cvt_i32_f32_sdwa v76, v76 dst_sel:WORD_1 dst_unused:UNUSED_PAD src0_sel:DWORD
	v_rndne_f32_e32 v75, v75
	v_cvt_i32_f32_sdwa v79, v79 dst_sel:BYTE_3 dst_unused:UNUSED_PAD src0_sel:DWORD
	v_cvt_i32_f32_sdwa v75, v75 dst_sel:BYTE_3 dst_unused:UNUSED_PAD src0_sel:DWORD
	v_lshlrev_b32_e32 v77, 8, v77
	v_and_b32_e32 v80, 0xff0000, v80
	v_and_b32_e32 v76, 0xff0000, v76
	v_perm_b32 v7, v77, v7, s28
	v_or3_b32 v6, v6, v79, v80
	v_or3_b32 v7, v7, v75, v76
	global_store_dwordx2 v[4:5], v[6:7], off
	v_mul_f32_e32 v7, v83, v72
	v_mul_f32_e32 v6, v83, v74
	v_rndne_f32_e32 v7, v7
	v_rndne_f32_e32 v6, v6
	v_cvt_i32_f32_e32 v7, v7
	v_cvt_i32_f32_e32 v6, v6
	v_mul_f32_e32 v69, v83, v69
	v_mul_f32_e32 v72, v83, v73
	v_lshlrev_b32_e32 v7, 8, v7
	v_perm_b32 v6, v7, v6, s28
	v_mul_f32_e32 v7, v83, v70
	v_rndne_f32_e32 v69, v69
	v_mul_f32_e32 v68, v83, v68
	v_rndne_f32_e32 v72, v72
	v_mul_f32_e32 v71, v83, v71
	v_rndne_f32_e32 v7, v7
	v_cvt_i32_f32_e32 v69, v69
	v_rndne_f32_e32 v68, v68
	v_mul_f32_e32 v67, v83, v67
	v_cvt_i32_f32_sdwa v72, v72 dst_sel:WORD_1 dst_unused:UNUSED_PAD src0_sel:DWORD
	v_rndne_f32_e32 v71, v71
	v_cvt_i32_f32_e32 v7, v7
	v_cvt_i32_f32_sdwa v68, v68 dst_sel:WORD_1 dst_unused:UNUSED_PAD src0_sel:DWORD
	v_rndne_f32_e32 v67, v67
	v_cvt_i32_f32_sdwa v71, v71 dst_sel:BYTE_3 dst_unused:UNUSED_PAD src0_sel:DWORD
	v_cvt_i32_f32_sdwa v67, v67 dst_sel:BYTE_3 dst_unused:UNUSED_PAD src0_sel:DWORD
	v_lshlrev_b32_e32 v69, 8, v69
	v_and_b32_e32 v72, 0xff0000, v72
	v_and_b32_e32 v68, 0xff0000, v68
	v_perm_b32 v7, v69, v7, s28
	v_or3_b32 v6, v6, v71, v72
	v_or3_b32 v7, v7, v67, v68
	global_store_dwordx2 v[4:5], v[6:7], off offset:512
	v_mul_f32_e32 v7, v83, v64
	v_mul_f32_e32 v6, v83, v66
	v_rndne_f32_e32 v7, v7
	v_rndne_f32_e32 v6, v6
	v_cvt_i32_f32_e32 v7, v7
	v_cvt_i32_f32_e32 v6, v6
	v_mul_f32_e32 v61, v83, v61
	v_mul_f32_e32 v64, v83, v65
	v_lshlrev_b32_e32 v7, 8, v7
	v_perm_b32 v6, v7, v6, s28
	v_mul_f32_e32 v7, v83, v62
	v_rndne_f32_e32 v61, v61
	v_mul_f32_e32 v60, v83, v60
	v_rndne_f32_e32 v64, v64
	v_mul_f32_e32 v63, v83, v63
	v_rndne_f32_e32 v7, v7
	v_cvt_i32_f32_e32 v61, v61
	v_rndne_f32_e32 v60, v60
	v_mul_f32_e32 v59, v83, v59
	v_cvt_i32_f32_sdwa v64, v64 dst_sel:WORD_1 dst_unused:UNUSED_PAD src0_sel:DWORD
	v_rndne_f32_e32 v63, v63
	v_cvt_i32_f32_e32 v7, v7
	v_cvt_i32_f32_sdwa v60, v60 dst_sel:WORD_1 dst_unused:UNUSED_PAD src0_sel:DWORD
	v_rndne_f32_e32 v59, v59
	v_cvt_i32_f32_sdwa v63, v63 dst_sel:BYTE_3 dst_unused:UNUSED_PAD src0_sel:DWORD
	v_cvt_i32_f32_sdwa v59, v59 dst_sel:BYTE_3 dst_unused:UNUSED_PAD src0_sel:DWORD
	v_lshlrev_b32_e32 v61, 8, v61
	v_and_b32_e32 v64, 0xff0000, v64
	v_and_b32_e32 v60, 0xff0000, v60
	v_perm_b32 v7, v61, v7, s28
	v_or3_b32 v6, v6, v63, v64
	v_or3_b32 v7, v7, v59, v60
	global_store_dwordx2 v[4:5], v[6:7], off offset:1024
	v_mul_f32_e32 v7, v83, v56
	v_mul_f32_e32 v6, v83, v58
	v_rndne_f32_e32 v7, v7
	v_rndne_f32_e32 v6, v6
	v_cvt_i32_f32_e32 v7, v7
	v_cvt_i32_f32_e32 v6, v6
	v_mul_f32_e32 v53, v83, v53
	v_mul_f32_e32 v56, v83, v57
	v_lshlrev_b32_e32 v7, 8, v7
	v_perm_b32 v6, v7, v6, s28
	v_mul_f32_e32 v7, v83, v54
	v_rndne_f32_e32 v53, v53
	v_mul_f32_e32 v52, v83, v52
	v_rndne_f32_e32 v56, v56
	v_mul_f32_e32 v55, v83, v55
	v_rndne_f32_e32 v7, v7
	v_cvt_i32_f32_e32 v53, v53
	v_rndne_f32_e32 v52, v52
	v_mul_f32_e32 v51, v83, v51
	v_cvt_i32_f32_sdwa v56, v56 dst_sel:WORD_1 dst_unused:UNUSED_PAD src0_sel:DWORD
	v_rndne_f32_e32 v55, v55
	v_cvt_i32_f32_e32 v7, v7
	v_cvt_i32_f32_sdwa v52, v52 dst_sel:WORD_1 dst_unused:UNUSED_PAD src0_sel:DWORD
	v_rndne_f32_e32 v51, v51
	v_cvt_i32_f32_sdwa v55, v55 dst_sel:BYTE_3 dst_unused:UNUSED_PAD src0_sel:DWORD
	v_cvt_i32_f32_sdwa v51, v51 dst_sel:BYTE_3 dst_unused:UNUSED_PAD src0_sel:DWORD
; __device__ __forceinline__ float bflo(unsigned w) { return __uint_as_float(w << 16); }
; __device__ __forceinline__ float bfhi(unsigned w) { return __uint_as_float(w & 0xffff0000u); }
; __device__ __forceinline__ void quant_store8(const u32x4 (&w)[8], float inv, signed char* dst, int lane) { u32x2* qp = (u32x2*)dst + lane;
; #pragma unroll
;     for (int j = 0; j < 8; ++j) { const unsigned ww[4] = {w[j].x, w[j].y, w[j].z, w[j].w}; unsigned o2[2];
; #pragma unroll
;         for (int h2 = 0; h2 < 2; ++h2) { const int q0 = (int)rintf(bflo(ww[2 * h2]) * inv), q1 = (int)rintf(bfhi(ww[2 * h2]) * inv), q2 = (int)rintf(bflo(ww[2 * h2 + 1]) * inv), q3 = (int)rintf(bfhi(ww[2 * h2 + 1]) * inv);
;             o2[h2] = (unsigned)(q0 & 255) | ((unsigned)(q1 & 255) << 8) | ((unsigned)(q2 & 255) << 16) | ((unsigned)(q3 & 255) << 24); }
;         u32x2 o; o.x = o2[0]; o.y = o2[1]; qp[64 * j] = o; } }
	v_lshlrev_b32_e32 v53, 8, v53
	v_and_b32_e32 v56, 0xff0000, v56
	v_and_b32_e32 v52, 0xff0000, v52
	v_perm_b32 v7, v53, v7, s28
	v_or3_b32 v6, v6, v55, v56
	v_or3_b32 v7, v7, v51, v52
	global_store_dwordx2 v[4:5], v[6:7], off offset:1536
	v_mul_f32_e32 v7, v83, v48
	v_mul_f32_e32 v6, v83, v50
	v_rndne_f32_e32 v7, v7
	v_rndne_f32_e32 v6, v6
	v_cvt_i32_f32_e32 v7, v7
	v_cvt_i32_f32_e32 v6, v6
	v_mul_f32_e32 v45, v83, v45
	v_mul_f32_e32 v48, v83, v49
	v_lshlrev_b32_e32 v7, 8, v7
	v_perm_b32 v6, v7, v6, s28
	v_mul_f32_e32 v7, v83, v46
	v_rndne_f32_e32 v45, v45
	v_mul_f32_e32 v44, v83, v44
	v_rndne_f32_e32 v48, v48
	v_mul_f32_e32 v47, v83, v47
	v_rndne_f32_e32 v7, v7
	v_cvt_i32_f32_e32 v45, v45
	v_rndne_f32_e32 v44, v44
	v_mul_f32_e32 v43, v83, v43
	v_cvt_i32_f32_sdwa v48, v48 dst_sel:WORD_1 dst_unused:UNUSED_PAD src0_sel:DWORD
	v_rndne_f32_e32 v47, v47
	v_cvt_i32_f32_e32 v7, v7
	v_cvt_i32_f32_sdwa v44, v44 dst_sel:WORD_1 dst_unused:UNUSED_PAD src0_sel:DWORD
	v_rndne_f32_e32 v43, v43
	v_cvt_i32_f32_sdwa v47, v47 dst_sel:BYTE_3 dst_unused:UNUSED_PAD src0_sel:DWORD
	v_cvt_i32_f32_sdwa v43, v43 dst_sel:BYTE_3 dst_unused:UNUSED_PAD src0_sel:DWORD
	v_lshlrev_b32_e32 v45, 8, v45
	v_and_b32_e32 v48, 0xff0000, v48
	v_and_b32_e32 v44, 0xff0000, v44
	v_perm_b32 v7, v45, v7, s28
	v_or3_b32 v6, v6, v47, v48
	v_or3_b32 v7, v7, v43, v44
	global_store_dwordx2 v[4:5], v[6:7], off offset:2048
	v_mul_f32_e32 v7, v83, v29
	v_mul_f32_e32 v6, v83, v42
	v_rndne_f32_e32 v7, v7
	v_rndne_f32_e32 v6, v6
	v_cvt_i32_f32_e32 v7, v7
	v_cvt_i32_f32_e32 v6, v6
	v_mul_f32_e32 v26, v83, v26
	v_mul_f32_e32 v29, v83, v41
	v_lshlrev_b32_e32 v7, 8, v7
	v_perm_b32 v6, v7, v6, s28
	v_mul_f32_e32 v7, v83, v27
	v_rndne_f32_e32 v26, v26
	v_mul_f32_e32 v25, v83, v25
	v_rndne_f32_e32 v29, v29
	v_mul_f32_e32 v28, v83, v28
	v_rndne_f32_e32 v7, v7
	v_cvt_i32_f32_e32 v26, v26
	v_rndne_f32_e32 v25, v25
	v_mul_f32_e32 v24, v83, v24
	v_cvt_i32_f32_sdwa v29, v29 dst_sel:WORD_1 dst_unused:UNUSED_PAD src0_sel:DWORD
	v_rndne_f32_e32 v28, v28
	v_cvt_i32_f32_e32 v7, v7
	v_cvt_i32_f32_sdwa v25, v25 dst_sel:WORD_1 dst_unused:UNUSED_PAD src0_sel:DWORD
	v_rndne_f32_e32 v24, v24
	v_cvt_i32_f32_sdwa v28, v28 dst_sel:BYTE_3 dst_unused:UNUSED_PAD src0_sel:DWORD
	v_cvt_i32_f32_sdwa v24, v24 dst_sel:BYTE_3 dst_unused:UNUSED_PAD src0_sel:DWORD
	v_lshlrev_b32_e32 v26, 8, v26
	v_and_b32_e32 v29, 0xff0000, v29
	v_and_b32_e32 v25, 0xff0000, v25
	v_perm_b32 v7, v26, v7, s28
	v_or3_b32 v6, v6, v28, v29
	v_or3_b32 v7, v7, v24, v25
	global_store_dwordx2 v[4:5], v[6:7], off offset:2560
	v_mul_f32_e32 v7, v83, v21
	v_mul_f32_e32 v6, v83, v23
	v_rndne_f32_e32 v7, v7
	v_rndne_f32_e32 v6, v6
	v_cvt_i32_f32_e32 v7, v7
	v_cvt_i32_f32_e32 v6, v6
	v_mul_f32_e32 v18, v83, v18
	v_mul_f32_e32 v21, v83, v22
	v_lshlrev_b32_e32 v7, 8, v7
	v_perm_b32 v6, v7, v6, s28
	v_mul_f32_e32 v7, v83, v19
	v_rndne_f32_e32 v18, v18
	v_mul_f32_e32 v17, v83, v17
	v_rndne_f32_e32 v21, v21
	v_mul_f32_e32 v20, v83, v20
	v_rndne_f32_e32 v7, v7
	v_cvt_i32_f32_e32 v18, v18
	v_rndne_f32_e32 v17, v17
	v_mul_f32_e32 v16, v83, v16
	v_cvt_i32_f32_sdwa v21, v21 dst_sel:WORD_1 dst_unused:UNUSED_PAD src0_sel:DWORD
	v_rndne_f32_e32 v20, v20
	v_cvt_i32_f32_e32 v7, v7
	v_cvt_i32_f32_sdwa v17, v17 dst_sel:WORD_1 dst_unused:UNUSED_PAD src0_sel:DWORD
	v_rndne_f32_e32 v16, v16
	v_cvt_i32_f32_sdwa v20, v20 dst_sel:BYTE_3 dst_unused:UNUSED_PAD src0_sel:DWORD
	v_cvt_i32_f32_sdwa v16, v16 dst_sel:BYTE_3 dst_unused:UNUSED_PAD src0_sel:DWORD
	v_lshlrev_b32_e32 v18, 8, v18
	v_and_b32_e32 v21, 0xff0000, v21
	v_and_b32_e32 v17, 0xff0000, v17
	v_perm_b32 v7, v18, v7, s28
	v_or3_b32 v6, v6, v20, v21
	v_or3_b32 v7, v7, v16, v17
	global_store_dwordx2 v[4:5], v[6:7], off offset:3072
	v_mul_f32_e32 v7, v83, v13
	v_mul_f32_e32 v6, v83, v15
	v_rndne_f32_e32 v7, v7
	v_rndne_f32_e32 v6, v6
	v_cvt_i32_f32_e32 v7, v7
	v_cvt_i32_f32_e32 v6, v6
	v_mul_f32_e32 v10, v83, v10
	v_mul_f32_e32 v13, v83, v14
	v_lshlrev_b32_e32 v7, 8, v7
	v_perm_b32 v6, v7, v6, s28
	v_mul_f32_e32 v7, v83, v11
	v_rndne_f32_e32 v10, v10
	v_mul_f32_e32 v9, v83, v9
	v_rndne_f32_e32 v13, v13
	v_mul_f32_e32 v12, v83, v12
	v_rndne_f32_e32 v7, v7
	v_cvt_i32_f32_e32 v10, v10
	v_rndne_f32_e32 v9, v9
	v_mul_f32_e32 v8, v83, v8
	v_cvt_i32_f32_sdwa v13, v13 dst_sel:WORD_1 dst_unused:UNUSED_PAD src0_sel:DWORD
	v_rndne_f32_e32 v12, v12
	v_cvt_i32_f32_e32 v7, v7
	v_cvt_i32_f32_sdwa v9, v9 dst_sel:WORD_1 dst_unused:UNUSED_PAD src0_sel:DWORD
	v_rndne_f32_e32 v8, v8
	v_cvt_i32_f32_sdwa v12, v12 dst_sel:BYTE_3 dst_unused:UNUSED_PAD src0_sel:DWORD
	v_cvt_i32_f32_sdwa v8, v8 dst_sel:BYTE_3 dst_unused:UNUSED_PAD src0_sel:DWORD
	v_lshlrev_b32_e32 v10, 8, v10
	v_and_b32_e32 v13, 0xff0000, v13
	v_and_b32_e32 v9, 0xff0000, v9
	v_perm_b32 v7, v10, v7, s28
	v_or3_b32 v6, v6, v12, v13
	v_or3_b32 v7, v7, v8, v9
	global_store_dwordx2 v[4:5], v[6:7], off offset:3584
	s_and_saveexec_b64 s[12:13], s[6:7]
	s_cbranch_execz .LBB0_271
	s_add_u32 s34, s78, s9
	s_addc_u32 s35, s79, s22
	global_store_dwordx2 v40, v[2:3], s[34:35]
	s_branch .LBB0_271
